# stack4 with the accumulator pairs of each 16-MFMA block re-sequenced so consecutive pairs reuse the same src0 fragment registers (4 pairs per src0 fragment pair)
# speedup vs baseline: 1.0093x; 1.0093x over previous
; #define PG8_STAGE(bufoff, gbase, voff) do { _Pragma("unroll") for (int _i = 0; _i < 2; ++_i) \
;         __builtin_amdgcn_global_load_lds((const unsigned*)((const char*)(gbase) + (voff)[_i]), (LAS unsigned*)(lds + (bufoff) + ldsw + _i * 8192), 16, 0, 0); } while (0)
; #define PG8_LDA(dst, b, h) do { _Pragma("unroll") for (int m = 0; m < 4; ++m) _Pragma("unroll") for (int k = 0; k < 2; ++k) dst[m][k] = *(const LAS bf16x8*)(lds + PG8_SA(b, h) + aoff + m * 2048 + k * 1024); } while (0)
; #define PG8_LDB(dst, b, h) do { _Pragma("unroll") for (int n = 0; n < 2; ++n) _Pragma("unroll") for (int k = 0; k < 2; ++k) dst[n][k] = *(const LAS bf16x8*)(lds + PG8_SB(b, h) + boff + n * 2048 + k * 1024); } while (0)
; #define PG8_MMA(ai, bj, At, Bt) do { __builtin_amdgcn_s_setprio(1); _Pragma("unroll") for (int m = 0; m < 4; ++m) _Pragma("unroll") for (int n = 0; n < 2; ++n) _Pragma("unroll") for (int k = 0; k < 2; ++k) \
;         acc[ai][bj][m][n] = __builtin_amdgcn_mfma_f32_16x16x32_bf16(Bt[n][k], At[m][k], acc[ai][bj][m][n], 0, 0, 0); __builtin_amdgcn_s_setprio(0); } while (0)
; #define PG8_WAIT_V(n) asm volatile("s_waitcnt vmcnt(" #n ")" ::: "memory")
; #define PG8_WAIT_L(n) asm volatile("s_waitcnt lgkmcnt(" #n ")" ::: "memory")
; #define PG8_BAR __builtin_amdgcn_s_barrier()
; #define PG8_SCHED __builtin_amdgcn_sched_barrier(0)
; template <class Epi>
; DI void gemm_phase(LAS unsigned char* lds, const Gemm g, const StaticOrder& S, const Epi& E) {
;     ...
;             const bool last = (t == nt - 2);
;             const char* a1 = cA + (size_t)(t + 1) * kstep;
;             const char* a2 = last ? nA : cA + (size_t)(t + 2) * kstep; const char* b2 = last ? nB : cB + (size_t)(t + 2) * kstep;
;             const char* a3 = a2 + kstep; const char* b3 = b2 + kstep;
;             PG8_LDB(B0, 0, 0); PG8_LDB(B1, 0, 1); PG8_SCHED; PG8_LDA(At, 0, 0); PG8_STAGE(PG8_SA(1, 1), a1 + hstepA, voffA);
;             PG8_WAIT_V(8); PG8_WAIT_L(0); PG8_BAR; PG8_MMA(0, 0, At, B0); PG8_MMA(0, 1, At, B1); PG8_BAR; PG8_SCHED;
;             PG8_LDA(At, 0, 1); PG8_STAGE(PG8_SB(0, 0), b2, voffB); PG8_STAGE(PG8_SB(0, 1), b2 + hstepB, voffB); PG8_STAGE(PG8_SA(0, 0), a2, voffA);
;             PG8_WAIT_V(8); PG8_WAIT_L(0); PG8_BAR; PG8_MMA(1, 0, At, B0); PG8_MMA(1, 1, At, B1); PG8_BAR; PG8_SCHED;
.LBB0_161:
	ds_read_b128 v[154:157], v150
	ds_read_b128 v[158:161], v150 offset:1024
	ds_read_b128 v[162:165], v150 offset:2048
	ds_read_b128 v[166:169], v150 offset:3072
	ds_read_b128 v[170:173], v151
	ds_read_b128 v[174:177], v151 offset:1024
	ds_read_b128 v[182:185], v151 offset:2048
	ds_read_b128 v[186:189], v151 offset:3072
	s_add_i32 s64, s34, 2
	s_add_u32 s35, s30, 0xfff00080
	s_addc_u32 s38, s31, -1
	s_cmp_eq_u32 s53, s34
	s_cselect_b32 s34, s29, s62
	s_cselect_b32 s39, s19, s38
	s_cselect_b32 s38, s21, s35
	s_cselect_b32 s35, s27, s63
	v_lshl_add_u64 v[146:147], s[30:31], 0, v[138:139]
	s_add_i32 m0, s41, 0xc000
	ds_read_b128 v[190:193], v152
	ds_read_b128 v[194:197], v152 offset:1024
	ds_read_b128 v[198:201], v152 offset:2048
	ds_read_b128 v[202:205], v152 offset:3072
	ds_read_b128 v[206:209], v152 offset:4096
	ds_read_b128 v[210:213], v152 offset:5120
	ds_read_b128 v[214:217], v152 offset:6144
	ds_read_b128 v[218:221], v152 offset:7168
	global_load_lds_dwordx4 v[146:147], off
	v_lshl_add_u64 v[146:147], s[30:31], 0, v[140:141]
	s_add_i32 m0, s41, 0xe000
	s_nop 0
	global_load_lds_dwordx4 v[146:147], off
	s_waitcnt vmcnt(8)
	s_waitcnt lgkmcnt(0)
	s_setprio 1
	s_barrier
	v_mfma_f32_16x16x32_bf16 v[124:127], v[154:157], v[190:193], v[124:127]
	v_mfma_f32_16x16x32_bf16 v[124:127], v[158:161], v[194:197], v[124:127]
	v_mfma_f32_16x16x32_bf16 v[108:111], v[154:157], v[198:201], v[108:111]
	v_mfma_f32_16x16x32_bf16 v[108:111], v[158:161], v[202:205], v[108:111]
	v_mfma_f32_16x16x32_bf16 v[92:95], v[154:157], v[206:209], v[92:95]
	v_mfma_f32_16x16x32_bf16 v[92:95], v[158:161], v[210:213], v[92:95]
	v_mfma_f32_16x16x32_bf16 v[76:79], v[154:157], v[214:217], v[76:79]
	v_mfma_f32_16x16x32_bf16 v[76:79], v[158:161], v[218:221], v[76:79]
	v_mfma_f32_16x16x32_bf16 v[120:123], v[162:165], v[190:193], v[120:123]
	v_mfma_f32_16x16x32_bf16 v[120:123], v[166:169], v[194:197], v[120:123]
	v_mfma_f32_16x16x32_bf16 v[104:107], v[162:165], v[198:201], v[104:107]
	v_mfma_f32_16x16x32_bf16 v[104:107], v[166:169], v[202:205], v[104:107]
	v_mfma_f32_16x16x32_bf16 v[88:91], v[162:165], v[206:209], v[88:91]
	v_mfma_f32_16x16x32_bf16 v[88:91], v[166:169], v[210:213], v[88:91]
	v_mfma_f32_16x16x32_bf16 v[72:75], v[162:165], v[214:217], v[72:75]
	v_mfma_f32_16x16x32_bf16 v[72:75], v[166:169], v[218:221], v[72:75]
	s_setprio 0
	s_setprio 1
	v_mfma_f32_16x16x32_bf16 v[116:119], v[170:173], v[190:193], v[116:119]
	v_mfma_f32_16x16x32_bf16 v[116:119], v[174:177], v[194:197], v[116:119]
	v_mfma_f32_16x16x32_bf16 v[100:103], v[170:173], v[198:201], v[100:103]
	v_mfma_f32_16x16x32_bf16 v[100:103], v[174:177], v[202:205], v[100:103]
	v_mfma_f32_16x16x32_bf16 v[84:87], v[170:173], v[206:209], v[84:87]
	v_mfma_f32_16x16x32_bf16 v[84:87], v[174:177], v[210:213], v[84:87]
	v_mfma_f32_16x16x32_bf16 v[68:71], v[170:173], v[214:217], v[68:71]
	v_mfma_f32_16x16x32_bf16 v[68:71], v[174:177], v[218:221], v[68:71]
	v_mfma_f32_16x16x32_bf16 v[112:115], v[182:185], v[190:193], v[112:115]
	v_mfma_f32_16x16x32_bf16 v[112:115], v[186:189], v[194:197], v[112:115]
	v_mfma_f32_16x16x32_bf16 v[96:99], v[182:185], v[198:201], v[96:99]
	v_mfma_f32_16x16x32_bf16 v[96:99], v[186:189], v[202:205], v[96:99]
	v_mfma_f32_16x16x32_bf16 v[80:83], v[182:185], v[206:209], v[80:83]
	v_mfma_f32_16x16x32_bf16 v[80:83], v[186:189], v[210:213], v[80:83]
	v_mfma_f32_16x16x32_bf16 v[64:67], v[182:185], v[214:217], v[64:67]
	v_mfma_f32_16x16x32_bf16 v[64:67], v[186:189], v[218:221], v[64:67]
	s_setprio 0
	s_barrier
	s_add_i32 s65, s58, s40
	v_lshl_add_u64 v[146:147], s[34:35], 0, v[130:131]
	s_mov_b32 m0, s65
	ds_read_b128 v[190:193], v152 offset:16384
	ds_read_b128 v[194:197], v152 offset:17408
	ds_read_b128 v[198:201], v152 offset:18432
	ds_read_b128 v[202:205], v152 offset:19456
	ds_read_b128 v[206:209], v152 offset:20480
	ds_read_b128 v[210:213], v152 offset:21504
	ds_read_b128 v[214:217], v152 offset:22528
	ds_read_b128 v[218:221], v152 offset:23552
	global_load_lds_dwordx4 v[146:147], off
	s_add_i32 m0, s65, 0x2000
	s_add_u32 s66, s34, 0x100000
	v_lshl_add_u64 v[178:179], s[34:35], 0, v[134:135]
	s_addc_u32 s67, s35, 0
	s_add_i32 s65, s59, s40
	global_load_lds_dwordx4 v[178:179], off
	v_lshl_add_u64 v[222:223], s[66:67], 0, v[130:131]
	s_mov_b32 m0, s65
	v_lshl_add_u64 v[224:225], s[38:39], 0, v[132:133]
	global_load_lds_dwordx4 v[222:223], off
	v_lshl_add_u64 v[222:223], s[66:67], 0, v[134:135]
	s_add_i32 m0, s65, 0x2000
	s_nop 0
	global_load_lds_dwordx4 v[222:223], off
	v_lshl_add_u64 v[222:223], s[38:39], 0, v[128:129]
	s_mov_b32 m0, s41
	s_nop 0
	global_load_lds_dwordx4 v[222:223], off
	s_mov_b32 m0, s42
	s_nop 0
	global_load_lds_dwordx4 v[224:225], off
	s_waitcnt vmcnt(8)
	s_waitcnt lgkmcnt(0)
	s_setprio 1
	s_barrier
; #define PG8_STAGE(bufoff, gbase, voff) do { _Pragma("unroll") for (int _i = 0; _i < 2; ++_i) \
;         __builtin_amdgcn_global_load_lds((const unsigned*)((const char*)(gbase) + (voff)[_i]), (LAS unsigned*)(lds + (bufoff) + ldsw + _i * 8192), 16, 0, 0); } while (0)
; #define PG8_LDA(dst, b, h) do { _Pragma("unroll") for (int m = 0; m < 4; ++m) _Pragma("unroll") for (int k = 0; k < 2; ++k) dst[m][k] = *(const LAS bf16x8*)(lds + PG8_SA(b, h) + aoff + m * 2048 + k * 1024); } while (0)
; #define PG8_LDB(dst, b, h) do { _Pragma("unroll") for (int n = 0; n < 2; ++n) _Pragma("unroll") for (int k = 0; k < 2; ++k) dst[n][k] = *(const LAS bf16x8*)(lds + PG8_SB(b, h) + boff + n * 2048 + k * 1024); } while (0)
; #define PG8_MMA(ai, bj, At, Bt) do { __builtin_amdgcn_s_setprio(1); _Pragma("unroll") for (int m = 0; m < 4; ++m) _Pragma("unroll") for (int n = 0; n < 2; ++n) _Pragma("unroll") for (int k = 0; k < 2; ++k) \
;         acc[ai][bj][m][n] = __builtin_amdgcn_mfma_f32_16x16x32_bf16(Bt[n][k], At[m][k], acc[ai][bj][m][n], 0, 0, 0); __builtin_amdgcn_s_setprio(0); } while (0)
; #define PG8_WAIT_V(n) asm volatile("s_waitcnt vmcnt(" #n ")" ::: "memory")
; #define PG8_WAIT_L(n) asm volatile("s_waitcnt lgkmcnt(" #n ")" ::: "memory")
; #define PG8_BAR __builtin_amdgcn_s_barrier()
; #define PG8_SCHED __builtin_amdgcn_sched_barrier(0)
; template <class Epi>
; DI void gemm_phase(LAS unsigned char* lds, const Gemm g, const StaticOrder& S, const Epi& E) {
;     ...
;             PG8_WAIT_V(8); PG8_WAIT_L(0); PG8_BAR; PG8_MMA(1, 0, At, B0); PG8_MMA(1, 1, At, B1); PG8_BAR; PG8_SCHED;
;             PG8_LDB(B0, 1, 0); PG8_LDB(B1, 1, 1); PG8_SCHED; PG8_LDA(At, 1, 0); PG8_STAGE(PG8_SA(0, 1), a2 + hstepA, voffA);
;             PG8_WAIT_V(8); PG8_WAIT_L(0); PG8_BAR; PG8_MMA(0, 0, At, B0); PG8_MMA(0, 1, At, B1); PG8_BAR; PG8_SCHED;
	v_mfma_f32_16x16x32_bf16 v[60:63], v[154:157], v[190:193], v[60:63]
	v_mfma_f32_16x16x32_bf16 v[60:63], v[158:161], v[194:197], v[60:63]
	v_mfma_f32_16x16x32_bf16 v[44:47], v[154:157], v[198:201], v[44:47]
	v_mfma_f32_16x16x32_bf16 v[44:47], v[158:161], v[202:205], v[44:47]
	v_mfma_f32_16x16x32_bf16 v[28:31], v[154:157], v[206:209], v[28:31]
	v_mfma_f32_16x16x32_bf16 v[28:31], v[158:161], v[210:213], v[28:31]
	v_mfma_f32_16x16x32_bf16 v[12:15], v[154:157], v[214:217], v[12:15]
	v_mfma_f32_16x16x32_bf16 v[12:15], v[158:161], v[218:221], v[12:15]
	v_mfma_f32_16x16x32_bf16 v[56:59], v[162:165], v[190:193], v[56:59]
	v_mfma_f32_16x16x32_bf16 v[56:59], v[166:169], v[194:197], v[56:59]
	v_mfma_f32_16x16x32_bf16 v[40:43], v[162:165], v[198:201], v[40:43]
	v_mfma_f32_16x16x32_bf16 v[40:43], v[166:169], v[202:205], v[40:43]
	v_mfma_f32_16x16x32_bf16 v[24:27], v[162:165], v[206:209], v[24:27]
	v_mfma_f32_16x16x32_bf16 v[24:27], v[166:169], v[210:213], v[24:27]
	v_mfma_f32_16x16x32_bf16 v[8:11], v[162:165], v[214:217], v[8:11]
	v_mfma_f32_16x16x32_bf16 v[8:11], v[166:169], v[218:221], v[8:11]
	s_setprio 0
	s_setprio 1
	v_mfma_f32_16x16x32_bf16 v[52:55], v[170:173], v[190:193], v[52:55]
	v_mfma_f32_16x16x32_bf16 v[52:55], v[174:177], v[194:197], v[52:55]
	v_mfma_f32_16x16x32_bf16 v[36:39], v[170:173], v[198:201], v[36:39]
	v_mfma_f32_16x16x32_bf16 v[36:39], v[174:177], v[202:205], v[36:39]
	v_mfma_f32_16x16x32_bf16 v[20:23], v[170:173], v[206:209], v[20:23]
	v_mfma_f32_16x16x32_bf16 v[20:23], v[174:177], v[210:213], v[20:23]
	v_mfma_f32_16x16x32_bf16 v[4:7], v[170:173], v[214:217], v[4:7]
	v_mfma_f32_16x16x32_bf16 v[4:7], v[174:177], v[218:221], v[4:7]
	v_mfma_f32_16x16x32_bf16 v[48:51], v[182:185], v[190:193], v[48:51]
	v_mfma_f32_16x16x32_bf16 v[48:51], v[186:189], v[194:197], v[48:51]
	v_mfma_f32_16x16x32_bf16 v[32:35], v[182:185], v[198:201], v[32:35]
	v_mfma_f32_16x16x32_bf16 v[32:35], v[186:189], v[202:205], v[32:35]
	v_mfma_f32_16x16x32_bf16 v[16:19], v[182:185], v[206:209], v[16:19]
	v_mfma_f32_16x16x32_bf16 v[16:19], v[186:189], v[210:213], v[16:19]
	v_mfma_f32_16x16x32_bf16 v[0:3], v[182:185], v[214:217], v[0:3]
	v_mfma_f32_16x16x32_bf16 v[0:3], v[186:189], v[218:221], v[0:3]
	s_setprio 0
	s_barrier
	s_add_i32 s65, 0, 0x18000
	s_add_i32 s66, 0, 0x1c000
	v_add_u32_e32 v166, s65, v149
	v_add_u32_e32 v181, s66, v149
	ds_read_b128 v[154:157], v166
	ds_read_b128 v[158:161], v166 offset:1024
	ds_read_b128 v[162:165], v166 offset:2048
	ds_read_b128 v[166:169], v166 offset:3072
	ds_read_b128 v[170:173], v181
	ds_read_b128 v[174:177], v181 offset:1024
	ds_read_b128 v[182:185], v181 offset:2048
	ds_read_b128 v[186:189], v181 offset:3072
	s_add_u32 s38, s38, 0x100000
	s_addc_u32 s39, s39, 0
	s_mov_b32 m0, s43
	v_lshl_add_u64 v[226:227], s[38:39], 0, v[128:129]
	ds_read_b128 v[190:193], v152 offset:32768
	ds_read_b128 v[194:197], v152 offset:33792
	ds_read_b128 v[198:201], v152 offset:34816
	ds_read_b128 v[202:205], v152 offset:35840
	ds_read_b128 v[206:209], v152 offset:36864
	ds_read_b128 v[210:213], v152 offset:37888
	ds_read_b128 v[214:217], v152 offset:38912
	ds_read_b128 v[218:221], v152 offset:39936
	global_load_lds_dwordx4 v[226:227], off
	v_lshl_add_u64 v[226:227], s[38:39], 0, v[132:133]
	s_mov_b32 m0, s46
	s_nop 0
	global_load_lds_dwordx4 v[226:227], off
	s_waitcnt vmcnt(8)
	s_waitcnt lgkmcnt(0)
	s_setprio 1
	s_barrier
	v_mfma_f32_16x16x32_bf16 v[124:127], v[154:157], v[190:193], v[124:127]
	v_mfma_f32_16x16x32_bf16 v[124:127], v[158:161], v[194:197], v[124:127]
	v_mfma_f32_16x16x32_bf16 v[108:111], v[154:157], v[198:201], v[108:111]
	v_mfma_f32_16x16x32_bf16 v[108:111], v[158:161], v[202:205], v[108:111]
	v_mfma_f32_16x16x32_bf16 v[92:95], v[154:157], v[206:209], v[92:95]
	v_mfma_f32_16x16x32_bf16 v[92:95], v[158:161], v[210:213], v[92:95]
	v_mfma_f32_16x16x32_bf16 v[76:79], v[154:157], v[214:217], v[76:79]
	v_mfma_f32_16x16x32_bf16 v[76:79], v[158:161], v[218:221], v[76:79]
	v_mfma_f32_16x16x32_bf16 v[120:123], v[162:165], v[190:193], v[120:123]
	v_mfma_f32_16x16x32_bf16 v[120:123], v[166:169], v[194:197], v[120:123]
	v_mfma_f32_16x16x32_bf16 v[104:107], v[162:165], v[198:201], v[104:107]
	v_mfma_f32_16x16x32_bf16 v[104:107], v[166:169], v[202:205], v[104:107]
	v_mfma_f32_16x16x32_bf16 v[88:91], v[162:165], v[206:209], v[88:91]
	v_mfma_f32_16x16x32_bf16 v[88:91], v[166:169], v[210:213], v[88:91]
	v_mfma_f32_16x16x32_bf16 v[72:75], v[162:165], v[214:217], v[72:75]
	v_mfma_f32_16x16x32_bf16 v[72:75], v[166:169], v[218:221], v[72:75]
	s_setprio 0
	s_setprio 1
	v_mfma_f32_16x16x32_bf16 v[116:119], v[170:173], v[190:193], v[116:119]
	v_mfma_f32_16x16x32_bf16 v[116:119], v[174:177], v[194:197], v[116:119]
	v_mfma_f32_16x16x32_bf16 v[100:103], v[170:173], v[198:201], v[100:103]
	v_mfma_f32_16x16x32_bf16 v[100:103], v[174:177], v[202:205], v[100:103]
	v_mfma_f32_16x16x32_bf16 v[84:87], v[170:173], v[206:209], v[84:87]
	v_mfma_f32_16x16x32_bf16 v[84:87], v[174:177], v[210:213], v[84:87]
	v_mfma_f32_16x16x32_bf16 v[68:71], v[170:173], v[214:217], v[68:71]
	v_mfma_f32_16x16x32_bf16 v[68:71], v[174:177], v[218:221], v[68:71]
	v_mfma_f32_16x16x32_bf16 v[112:115], v[182:185], v[190:193], v[112:115]
	v_mfma_f32_16x16x32_bf16 v[112:115], v[186:189], v[194:197], v[112:115]
	v_mfma_f32_16x16x32_bf16 v[96:99], v[182:185], v[198:201], v[96:99]
	v_mfma_f32_16x16x32_bf16 v[96:99], v[186:189], v[202:205], v[96:99]
	v_mfma_f32_16x16x32_bf16 v[80:83], v[182:185], v[206:209], v[80:83]
	v_mfma_f32_16x16x32_bf16 v[80:83], v[186:189], v[210:213], v[80:83]
	v_mfma_f32_16x16x32_bf16 v[64:67], v[182:185], v[214:217], v[64:67]
	v_mfma_f32_16x16x32_bf16 v[64:67], v[186:189], v[218:221], v[64:67]
	s_setprio 0
	s_barrier
; #define PG8_STAGE(bufoff, gbase, voff) do { _Pragma("unroll") for (int _i = 0; _i < 2; ++_i) \
;         __builtin_amdgcn_global_load_lds((const unsigned*)((const char*)(gbase) + (voff)[_i]), (LAS unsigned*)(lds + (bufoff) + ldsw + _i * 8192), 16, 0, 0); } while (0)
; #define PG8_LDA(dst, b, h) do { _Pragma("unroll") for (int m = 0; m < 4; ++m) _Pragma("unroll") for (int k = 0; k < 2; ++k) dst[m][k] = *(const LAS bf16x8*)(lds + PG8_SA(b, h) + aoff + m * 2048 + k * 1024); } while (0)
; #define PG8_MMA(ai, bj, At, Bt) do { __builtin_amdgcn_s_setprio(1); _Pragma("unroll") for (int m = 0; m < 4; ++m) _Pragma("unroll") for (int n = 0; n < 2; ++n) _Pragma("unroll") for (int k = 0; k < 2; ++k) \
;         acc[ai][bj][m][n] = __builtin_amdgcn_mfma_f32_16x16x32_bf16(Bt[n][k], At[m][k], acc[ai][bj][m][n], 0, 0, 0); __builtin_amdgcn_s_setprio(0); } while (0)
; #define PG8_WAIT_V(n) asm volatile("s_waitcnt vmcnt(" #n ")" ::: "memory")
; #define PG8_WAIT_L(n) asm volatile("s_waitcnt lgkmcnt(" #n ")" ::: "memory")
; #define PG8_BAR __builtin_amdgcn_s_barrier()
; #define PG8_SCHED __builtin_amdgcn_sched_barrier(0)
; template <class Epi>
; DI void gemm_phase(LAS unsigned char* lds, const Gemm g, const StaticOrder& S, const Epi& E) {
;     ...
;             PG8_LDA(At, 1, 1); PG8_STAGE(PG8_SB(1, 0), b3, voffB); PG8_STAGE(PG8_SB(1, 1), b3 + hstepB, voffB); PG8_STAGE(PG8_SA(1, 0), a3, voffA);
;             PG8_WAIT_V(8); PG8_WAIT_L(0); PG8_BAR; PG8_MMA(1, 0, At, B0); PG8_MMA(1, 1, At, B1); PG8_BAR; PG8_SCHED;
;         }
	s_add_i32 s38, s65, s40
	v_lshl_add_u64 v[146:147], v[146:147], 0, s[14:15]
	s_mov_b32 m0, s38
	ds_read_b128 v[190:193], v152 offset:49152
	ds_read_b128 v[194:197], v152 offset:50176
	ds_read_b128 v[198:201], v152 offset:51200
	ds_read_b128 v[202:205], v152 offset:52224
	ds_read_b128 v[206:209], v152 offset:53248
	ds_read_b128 v[210:213], v152 offset:54272
	ds_read_b128 v[214:217], v152 offset:55296
	ds_read_b128 v[218:221], v152 offset:56320
	global_load_lds_dwordx4 v[146:147], off
	s_add_i32 m0, s38, 0x2000
	s_add_u32 s34, s34, 0x100080
	v_lshl_add_u64 v[146:147], v[178:179], 0, s[14:15]
	s_addc_u32 s35, s35, 0
	s_add_i32 s38, s66, s40
	global_load_lds_dwordx4 v[146:147], off
	v_lshl_add_u64 v[146:147], s[34:35], 0, v[130:131]
	s_mov_b32 m0, s38
	s_nop 0
	global_load_lds_dwordx4 v[146:147], off
	v_lshl_add_u64 v[146:147], s[34:35], 0, v[134:135]
	s_add_i32 m0, s38, 0x2000
	s_nop 0
	global_load_lds_dwordx4 v[146:147], off
	v_lshl_add_u64 v[146:147], v[222:223], 0, s[14:15]
	s_mov_b32 m0, s51
	s_nop 0
	global_load_lds_dwordx4 v[146:147], off
	v_lshl_add_u64 v[146:147], v[224:225], 0, s[14:15]
	s_mov_b32 m0, s52
	s_nop 0
	global_load_lds_dwordx4 v[146:147], off
	s_waitcnt vmcnt(8)
	s_waitcnt lgkmcnt(0)
	s_setprio 1
	s_barrier
	v_mfma_f32_16x16x32_bf16 v[60:63], v[154:157], v[190:193], v[60:63]
	v_mfma_f32_16x16x32_bf16 v[60:63], v[158:161], v[194:197], v[60:63]
	v_mfma_f32_16x16x32_bf16 v[44:47], v[154:157], v[198:201], v[44:47]
	v_mfma_f32_16x16x32_bf16 v[44:47], v[158:161], v[202:205], v[44:47]
	v_mfma_f32_16x16x32_bf16 v[28:31], v[154:157], v[206:209], v[28:31]
	v_mfma_f32_16x16x32_bf16 v[28:31], v[158:161], v[210:213], v[28:31]
	v_mfma_f32_16x16x32_bf16 v[12:15], v[154:157], v[214:217], v[12:15]
	v_mfma_f32_16x16x32_bf16 v[12:15], v[158:161], v[218:221], v[12:15]
	v_mfma_f32_16x16x32_bf16 v[56:59], v[162:165], v[190:193], v[56:59]
	v_mfma_f32_16x16x32_bf16 v[56:59], v[166:169], v[194:197], v[56:59]
	v_mfma_f32_16x16x32_bf16 v[40:43], v[162:165], v[198:201], v[40:43]
	v_mfma_f32_16x16x32_bf16 v[40:43], v[166:169], v[202:205], v[40:43]
	v_mfma_f32_16x16x32_bf16 v[24:27], v[162:165], v[206:209], v[24:27]
	v_mfma_f32_16x16x32_bf16 v[24:27], v[166:169], v[210:213], v[24:27]
	v_mfma_f32_16x16x32_bf16 v[8:11], v[162:165], v[214:217], v[8:11]
	v_mfma_f32_16x16x32_bf16 v[8:11], v[166:169], v[218:221], v[8:11]
	s_setprio 0
	s_setprio 1
	v_mfma_f32_16x16x32_bf16 v[52:55], v[170:173], v[190:193], v[52:55]
	v_mfma_f32_16x16x32_bf16 v[52:55], v[174:177], v[194:197], v[52:55]
	v_mfma_f32_16x16x32_bf16 v[36:39], v[170:173], v[198:201], v[36:39]
	v_mfma_f32_16x16x32_bf16 v[36:39], v[174:177], v[202:205], v[36:39]
	v_mfma_f32_16x16x32_bf16 v[20:23], v[170:173], v[206:209], v[20:23]
	v_mfma_f32_16x16x32_bf16 v[20:23], v[174:177], v[210:213], v[20:23]
	v_mfma_f32_16x16x32_bf16 v[4:7], v[170:173], v[214:217], v[4:7]
	v_mfma_f32_16x16x32_bf16 v[4:7], v[174:177], v[218:221], v[4:7]
	v_mfma_f32_16x16x32_bf16 v[48:51], v[182:185], v[190:193], v[48:51]
	v_mfma_f32_16x16x32_bf16 v[48:51], v[186:189], v[194:197], v[48:51]
	v_mfma_f32_16x16x32_bf16 v[32:35], v[182:185], v[198:201], v[32:35]
	v_mfma_f32_16x16x32_bf16 v[32:35], v[186:189], v[202:205], v[32:35]
	v_mfma_f32_16x16x32_bf16 v[16:19], v[182:185], v[206:209], v[16:19]
	v_mfma_f32_16x16x32_bf16 v[16:19], v[186:189], v[210:213], v[16:19]
	v_mfma_f32_16x16x32_bf16 v[0:3], v[182:185], v[214:217], v[0:3]
	v_mfma_f32_16x16x32_bf16 v[0:3], v[186:189], v[218:221], v[0:3]
	s_setprio 0
	s_barrier
	s_add_u32 s30, s30, 0x100
	s_addc_u32 s31, s31, 0
	s_add_u32 s62, s62, 0x100
	s_addc_u32 s63, s63, 0
	s_cmp_ge_i32 s64, s50
	s_mov_b32 s34, s64
	s_cbranch_scc0 .LBB0_161

; #define PG8_STAGE(bufoff, gbase, voff) do { _Pragma("unroll") for (int _i = 0; _i < 2; ++_i) \
;         __builtin_amdgcn_global_load_lds((const unsigned*)((const char*)(gbase) + (voff)[_i]), (LAS unsigned*)(lds + (bufoff) + ldsw + _i * 8192), 16, 0, 0); } while (0)
; #define PG8_LDA(dst, b, h) do { _Pragma("unroll") for (int m = 0; m < 4; ++m) _Pragma("unroll") for (int k = 0; k < 2; ++k) dst[m][k] = *(const LAS bf16x8*)(lds + PG8_SA(b, h) + aoff + m * 2048 + k * 1024); } while (0)
; #define PG8_LDB(dst, b, h) do { _Pragma("unroll") for (int n = 0; n < 2; ++n) _Pragma("unroll") for (int k = 0; k < 2; ++k) dst[n][k] = *(const LAS bf16x8*)(lds + PG8_SB(b, h) + boff + n * 2048 + k * 1024); } while (0)
; #define PG8_MMA(ai, bj, At, Bt) do { __builtin_amdgcn_s_setprio(1); _Pragma("unroll") for (int m = 0; m < 4; ++m) _Pragma("unroll") for (int n = 0; n < 2; ++n) _Pragma("unroll") for (int k = 0; k < 2; ++k) \
;         acc[ai][bj][m][n] = __builtin_amdgcn_mfma_f32_16x16x32_bf16(Bt[n][k], At[m][k], acc[ai][bj][m][n], 0, 0, 0); __builtin_amdgcn_s_setprio(0); } while (0)
; #define PG8_WAIT_V(n) asm volatile("s_waitcnt vmcnt(" #n ")" ::: "memory")
; #define PG8_WAIT_L(n) asm volatile("s_waitcnt lgkmcnt(" #n ")" ::: "memory")
; #define PG8_BAR __builtin_amdgcn_s_barrier()
; #define PG8_SCHED __builtin_amdgcn_sched_barrier(0)
; template <class Epi>
; DI void gemm_phase(LAS unsigned char* lds, const Gemm g, const StaticOrder& S, const Epi& E) {
;     ...
;             const bool last = (t == nt - 2);
;             const char* a1 = cA + (size_t)(t + 1) * kstep;
;             const char* a2 = last ? nA : cA + (size_t)(t + 2) * kstep; const char* b2 = last ? nB : cB + (size_t)(t + 2) * kstep;
;             const char* a3 = a2 + kstep; const char* b3 = b2 + kstep;
;             PG8_LDB(B0, 0, 0); PG8_LDB(B1, 0, 1); PG8_SCHED; PG8_LDA(At, 0, 0); PG8_STAGE(PG8_SA(1, 1), a1 + hstepA, voffA);
;             PG8_WAIT_V(8); PG8_WAIT_L(0); PG8_BAR; PG8_MMA(0, 0, At, B0); PG8_MMA(0, 1, At, B1); PG8_BAR; PG8_SCHED;
;             PG8_LDA(At, 0, 1); PG8_STAGE(PG8_SB(0, 0), b2, voffB); PG8_STAGE(PG8_SB(0, 1), b2 + hstepB, voffB); PG8_STAGE(PG8_SA(0, 0), a2, voffA);
;             PG8_WAIT_V(8); PG8_WAIT_L(0); PG8_BAR; PG8_MMA(1, 0, At, B0); PG8_MMA(1, 1, At, B1); PG8_BAR; PG8_SCHED;
.LBB0_201:
	ds_read_b128 v[148:151], v145
	ds_read_b128 v[152:155], v145 offset:1024
	ds_read_b128 v[156:159], v145 offset:2048
	ds_read_b128 v[160:163], v145 offset:3072
	ds_read_b128 v[164:167], v146
	ds_read_b128 v[168:171], v146 offset:1024
	ds_read_b128 v[172:175], v146 offset:2048
	ds_read_b128 v[176:179], v146 offset:3072
	s_add_i32 s65, s28, 2
	s_add_u32 s29, s26, 0xfff00080
	s_addc_u32 s30, s27, -1
	s_cmp_eq_u32 s50, s28
	s_cselect_b32 s28, s62, s63
	s_cselect_b32 s31, s19, s30
	s_cselect_b32 s30, s21, s29
	s_cselect_b32 s29, s61, s64
	v_lshl_add_u64 v[214:215], s[26:27], 0, v[138:139]
	s_add_i32 m0, s38, 0xc000
	ds_read_b128 v[182:185], v147
	ds_read_b128 v[186:189], v147 offset:1024
	ds_read_b128 v[190:193], v147 offset:2048
	ds_read_b128 v[194:197], v147 offset:3072
	ds_read_b128 v[198:201], v147 offset:4096
	ds_read_b128 v[202:205], v147 offset:5120
	ds_read_b128 v[206:209], v147 offset:6144
	ds_read_b128 v[210:213], v147 offset:7168
	global_load_lds_dwordx4 v[214:215], off
	v_lshl_add_u64 v[214:215], s[26:27], 0, v[140:141]
	s_add_i32 m0, s38, 0xe000
	s_nop 0
	global_load_lds_dwordx4 v[214:215], off
	s_waitcnt vmcnt(8)
	s_waitcnt lgkmcnt(0)
	s_setprio 1
	s_barrier
	v_mfma_f32_16x16x32_bf16 v[120:123], v[148:151], v[182:185], v[120:123]
	v_mfma_f32_16x16x32_bf16 v[120:123], v[152:155], v[186:189], v[120:123]
	v_mfma_f32_16x16x32_bf16 v[108:111], v[148:151], v[190:193], v[108:111]
	v_mfma_f32_16x16x32_bf16 v[108:111], v[152:155], v[194:197], v[108:111]
	v_mfma_f32_16x16x32_bf16 v[92:95], v[148:151], v[198:201], v[92:95]
	v_mfma_f32_16x16x32_bf16 v[92:95], v[152:155], v[202:205], v[92:95]
	v_mfma_f32_16x16x32_bf16 v[76:79], v[148:151], v[206:209], v[76:79]
	v_mfma_f32_16x16x32_bf16 v[76:79], v[152:155], v[210:213], v[76:79]
	v_mfma_f32_16x16x32_bf16 v[124:127], v[156:159], v[182:185], v[124:127]
	v_mfma_f32_16x16x32_bf16 v[124:127], v[160:163], v[186:189], v[124:127]
	v_mfma_f32_16x16x32_bf16 v[104:107], v[156:159], v[190:193], v[104:107]
	v_mfma_f32_16x16x32_bf16 v[104:107], v[160:163], v[194:197], v[104:107]
	v_mfma_f32_16x16x32_bf16 v[88:91], v[156:159], v[198:201], v[88:91]
	v_mfma_f32_16x16x32_bf16 v[88:91], v[160:163], v[202:205], v[88:91]
	v_mfma_f32_16x16x32_bf16 v[72:75], v[156:159], v[206:209], v[72:75]
	v_mfma_f32_16x16x32_bf16 v[72:75], v[160:163], v[210:213], v[72:75]
	s_setprio 0
	s_setprio 1
	v_mfma_f32_16x16x32_bf16 v[116:119], v[164:167], v[182:185], v[116:119]
	v_mfma_f32_16x16x32_bf16 v[116:119], v[168:171], v[186:189], v[116:119]
	v_mfma_f32_16x16x32_bf16 v[100:103], v[164:167], v[190:193], v[100:103]
	v_mfma_f32_16x16x32_bf16 v[100:103], v[168:171], v[194:197], v[100:103]
	v_mfma_f32_16x16x32_bf16 v[84:87], v[164:167], v[198:201], v[84:87]
	v_mfma_f32_16x16x32_bf16 v[84:87], v[168:171], v[202:205], v[84:87]
	v_mfma_f32_16x16x32_bf16 v[68:71], v[164:167], v[206:209], v[68:71]
	v_mfma_f32_16x16x32_bf16 v[68:71], v[168:171], v[210:213], v[68:71]
	v_mfma_f32_16x16x32_bf16 v[112:115], v[172:175], v[182:185], v[112:115]
	v_mfma_f32_16x16x32_bf16 v[112:115], v[176:179], v[186:189], v[112:115]
	v_mfma_f32_16x16x32_bf16 v[96:99], v[172:175], v[190:193], v[96:99]
	v_mfma_f32_16x16x32_bf16 v[96:99], v[176:179], v[194:197], v[96:99]
	v_mfma_f32_16x16x32_bf16 v[80:83], v[172:175], v[198:201], v[80:83]
	v_mfma_f32_16x16x32_bf16 v[80:83], v[176:179], v[202:205], v[80:83]
	v_mfma_f32_16x16x32_bf16 v[64:67], v[172:175], v[206:209], v[64:67]
	v_mfma_f32_16x16x32_bf16 v[64:67], v[176:179], v[210:213], v[64:67]
	s_setprio 0
	s_barrier
	s_add_i32 s66, s52, s35
	v_lshl_add_u64 v[214:215], s[28:29], 0, v[132:133]
	s_mov_b32 m0, s66
	ds_read_b128 v[182:185], v147 offset:16384
	ds_read_b128 v[186:189], v147 offset:17408
	ds_read_b128 v[190:193], v147 offset:18432
	ds_read_b128 v[194:197], v147 offset:19456
	ds_read_b128 v[198:201], v147 offset:20480
	ds_read_b128 v[202:205], v147 offset:21504
	ds_read_b128 v[206:209], v147 offset:22528
	ds_read_b128 v[210:213], v147 offset:23552
	global_load_lds_dwordx4 v[214:215], off
	s_add_i32 m0, s66, 0x2000
	s_add_u32 s66, s28, 0x100000
	v_lshl_add_u64 v[216:217], s[28:29], 0, v[128:129]
	s_addc_u32 s67, s29, 0
	s_add_i32 s68, s53, s35
	global_load_lds_dwordx4 v[216:217], off
	v_lshl_add_u64 v[218:219], s[66:67], 0, v[132:133]
	s_mov_b32 m0, s68
	v_lshl_add_u64 v[220:221], s[30:31], 0, v[130:131]
	global_load_lds_dwordx4 v[218:219], off
	v_lshl_add_u64 v[218:219], s[66:67], 0, v[128:129]
	s_add_i32 m0, s68, 0x2000
	s_nop 0
	global_load_lds_dwordx4 v[218:219], off
	v_lshl_add_u64 v[218:219], s[30:31], 0, v[134:135]
	s_mov_b32 m0, s38
	s_nop 0
	global_load_lds_dwordx4 v[218:219], off
	s_mov_b32 m0, s39
	s_nop 0
	global_load_lds_dwordx4 v[220:221], off
	s_waitcnt vmcnt(8)
	s_waitcnt lgkmcnt(0)
	s_setprio 1
	s_barrier
; #define PG8_STAGE(bufoff, gbase, voff) do { _Pragma("unroll") for (int _i = 0; _i < 2; ++_i) \
;         __builtin_amdgcn_global_load_lds((const unsigned*)((const char*)(gbase) + (voff)[_i]), (LAS unsigned*)(lds + (bufoff) + ldsw + _i * 8192), 16, 0, 0); } while (0)
; #define PG8_LDA(dst, b, h) do { _Pragma("unroll") for (int m = 0; m < 4; ++m) _Pragma("unroll") for (int k = 0; k < 2; ++k) dst[m][k] = *(const LAS bf16x8*)(lds + PG8_SA(b, h) + aoff + m * 2048 + k * 1024); } while (0)
; #define PG8_LDB(dst, b, h) do { _Pragma("unroll") for (int n = 0; n < 2; ++n) _Pragma("unroll") for (int k = 0; k < 2; ++k) dst[n][k] = *(const LAS bf16x8*)(lds + PG8_SB(b, h) + boff + n * 2048 + k * 1024); } while (0)
; #define PG8_MMA(ai, bj, At, Bt) do { __builtin_amdgcn_s_setprio(1); _Pragma("unroll") for (int m = 0; m < 4; ++m) _Pragma("unroll") for (int n = 0; n < 2; ++n) _Pragma("unroll") for (int k = 0; k < 2; ++k) \
;         acc[ai][bj][m][n] = __builtin_amdgcn_mfma_f32_16x16x32_bf16(Bt[n][k], At[m][k], acc[ai][bj][m][n], 0, 0, 0); __builtin_amdgcn_s_setprio(0); } while (0)
; #define PG8_WAIT_V(n) asm volatile("s_waitcnt vmcnt(" #n ")" ::: "memory")
; #define PG8_WAIT_L(n) asm volatile("s_waitcnt lgkmcnt(" #n ")" ::: "memory")
; #define PG8_BAR __builtin_amdgcn_s_barrier()
; #define PG8_SCHED __builtin_amdgcn_sched_barrier(0)
; template <class Epi>
; DI void gemm_phase(LAS unsigned char* lds, const Gemm g, const StaticOrder& S, const Epi& E) {
;     ...
;             PG8_WAIT_V(8); PG8_WAIT_L(0); PG8_BAR; PG8_MMA(1, 0, At, B0); PG8_MMA(1, 1, At, B1); PG8_BAR; PG8_SCHED;
;             PG8_LDB(B0, 1, 0); PG8_LDB(B1, 1, 1); PG8_SCHED; PG8_LDA(At, 1, 0); PG8_STAGE(PG8_SA(0, 1), a2 + hstepA, voffA);
;             PG8_WAIT_V(8); PG8_WAIT_L(0); PG8_BAR; PG8_MMA(0, 0, At, B0); PG8_MMA(0, 1, At, B1); PG8_BAR; PG8_SCHED;
	v_mfma_f32_16x16x32_bf16 v[60:63], v[148:151], v[182:185], v[60:63]
	v_mfma_f32_16x16x32_bf16 v[60:63], v[152:155], v[186:189], v[60:63]
	v_mfma_f32_16x16x32_bf16 v[44:47], v[148:151], v[190:193], v[44:47]
	v_mfma_f32_16x16x32_bf16 v[44:47], v[152:155], v[194:197], v[44:47]
	v_mfma_f32_16x16x32_bf16 v[28:31], v[148:151], v[198:201], v[28:31]
	v_mfma_f32_16x16x32_bf16 v[28:31], v[152:155], v[202:205], v[28:31]
	v_mfma_f32_16x16x32_bf16 v[12:15], v[148:151], v[206:209], v[12:15]
	v_mfma_f32_16x16x32_bf16 v[12:15], v[152:155], v[210:213], v[12:15]
	v_mfma_f32_16x16x32_bf16 v[56:59], v[156:159], v[182:185], v[56:59]
	v_mfma_f32_16x16x32_bf16 v[56:59], v[160:163], v[186:189], v[56:59]
	v_mfma_f32_16x16x32_bf16 v[40:43], v[156:159], v[190:193], v[40:43]
	v_mfma_f32_16x16x32_bf16 v[40:43], v[160:163], v[194:197], v[40:43]
	v_mfma_f32_16x16x32_bf16 v[24:27], v[156:159], v[198:201], v[24:27]
	v_mfma_f32_16x16x32_bf16 v[24:27], v[160:163], v[202:205], v[24:27]
	v_mfma_f32_16x16x32_bf16 v[8:11], v[156:159], v[206:209], v[8:11]
	v_mfma_f32_16x16x32_bf16 v[8:11], v[160:163], v[210:213], v[8:11]
	s_setprio 0
	s_setprio 1
	v_mfma_f32_16x16x32_bf16 v[52:55], v[164:167], v[182:185], v[52:55]
	v_mfma_f32_16x16x32_bf16 v[52:55], v[168:171], v[186:189], v[52:55]
	v_mfma_f32_16x16x32_bf16 v[36:39], v[164:167], v[190:193], v[36:39]
	v_mfma_f32_16x16x32_bf16 v[36:39], v[168:171], v[194:197], v[36:39]
	v_mfma_f32_16x16x32_bf16 v[20:23], v[164:167], v[198:201], v[20:23]
	v_mfma_f32_16x16x32_bf16 v[20:23], v[168:171], v[202:205], v[20:23]
	v_mfma_f32_16x16x32_bf16 v[4:7], v[164:167], v[206:209], v[4:7]
	v_mfma_f32_16x16x32_bf16 v[4:7], v[168:171], v[210:213], v[4:7]
	v_mfma_f32_16x16x32_bf16 v[48:51], v[172:175], v[182:185], v[48:51]
	v_mfma_f32_16x16x32_bf16 v[48:51], v[176:179], v[186:189], v[48:51]
	v_mfma_f32_16x16x32_bf16 v[32:35], v[172:175], v[190:193], v[32:35]
	v_mfma_f32_16x16x32_bf16 v[32:35], v[176:179], v[194:197], v[32:35]
	v_mfma_f32_16x16x32_bf16 v[16:19], v[172:175], v[198:201], v[16:19]
	v_mfma_f32_16x16x32_bf16 v[16:19], v[176:179], v[202:205], v[16:19]
	v_mfma_f32_16x16x32_bf16 v[0:3], v[172:175], v[206:209], v[0:3]
	v_mfma_f32_16x16x32_bf16 v[0:3], v[176:179], v[210:213], v[0:3]
	s_setprio 0
	s_barrier
	s_add_i32 s66, 0, 0x18000
	v_add_u32_e32 v136, s66, v143
	s_add_i32 s67, 0, 0x1c000
	ds_read_b128 v[148:151], v136
	ds_read_b128 v[152:155], v136 offset:1024
	ds_read_b128 v[156:159], v136 offset:2048
	ds_read_b128 v[160:163], v136 offset:3072
	v_add_u32_e32 v136, s67, v143
	ds_read_b128 v[164:167], v136
	ds_read_b128 v[168:171], v136 offset:1024
	ds_read_b128 v[172:175], v136 offset:2048
	ds_read_b128 v[176:179], v136 offset:3072
	s_add_u32 s30, s30, 0x100000
	s_addc_u32 s31, s31, 0
	s_mov_b32 m0, s40
	v_lshl_add_u64 v[222:223], s[30:31], 0, v[134:135]
	ds_read_b128 v[182:185], v147 offset:32768
	ds_read_b128 v[186:189], v147 offset:33792
	ds_read_b128 v[190:193], v147 offset:34816
	ds_read_b128 v[194:197], v147 offset:35840
	ds_read_b128 v[198:201], v147 offset:36864
	ds_read_b128 v[202:205], v147 offset:37888
	ds_read_b128 v[206:209], v147 offset:38912
	ds_read_b128 v[210:213], v147 offset:39936
	global_load_lds_dwordx4 v[222:223], off
	v_lshl_add_u64 v[222:223], s[30:31], 0, v[130:131]
	s_mov_b32 m0, s41
	s_nop 0
	global_load_lds_dwordx4 v[222:223], off
	s_waitcnt vmcnt(8)
	s_waitcnt lgkmcnt(0)
	s_setprio 1
	s_barrier
	v_mfma_f32_16x16x32_bf16 v[120:123], v[148:151], v[182:185], v[120:123]
	v_mfma_f32_16x16x32_bf16 v[120:123], v[152:155], v[186:189], v[120:123]
	v_mfma_f32_16x16x32_bf16 v[108:111], v[148:151], v[190:193], v[108:111]
	v_mfma_f32_16x16x32_bf16 v[108:111], v[152:155], v[194:197], v[108:111]
	v_mfma_f32_16x16x32_bf16 v[92:95], v[148:151], v[198:201], v[92:95]
	v_mfma_f32_16x16x32_bf16 v[92:95], v[152:155], v[202:205], v[92:95]
	v_mfma_f32_16x16x32_bf16 v[76:79], v[148:151], v[206:209], v[76:79]
	v_mfma_f32_16x16x32_bf16 v[76:79], v[152:155], v[210:213], v[76:79]
	v_mfma_f32_16x16x32_bf16 v[124:127], v[156:159], v[182:185], v[124:127]
	v_mfma_f32_16x16x32_bf16 v[124:127], v[160:163], v[186:189], v[124:127]
	v_mfma_f32_16x16x32_bf16 v[104:107], v[156:159], v[190:193], v[104:107]
	v_mfma_f32_16x16x32_bf16 v[104:107], v[160:163], v[194:197], v[104:107]
	v_mfma_f32_16x16x32_bf16 v[88:91], v[156:159], v[198:201], v[88:91]
	v_mfma_f32_16x16x32_bf16 v[88:91], v[160:163], v[202:205], v[88:91]
	v_mfma_f32_16x16x32_bf16 v[72:75], v[156:159], v[206:209], v[72:75]
	v_mfma_f32_16x16x32_bf16 v[72:75], v[160:163], v[210:213], v[72:75]
	s_setprio 0
	s_setprio 1
	v_mfma_f32_16x16x32_bf16 v[116:119], v[164:167], v[182:185], v[116:119]
	v_mfma_f32_16x16x32_bf16 v[116:119], v[168:171], v[186:189], v[116:119]
	v_mfma_f32_16x16x32_bf16 v[100:103], v[164:167], v[190:193], v[100:103]
	v_mfma_f32_16x16x32_bf16 v[100:103], v[168:171], v[194:197], v[100:103]
	v_mfma_f32_16x16x32_bf16 v[84:87], v[164:167], v[198:201], v[84:87]
	v_mfma_f32_16x16x32_bf16 v[84:87], v[168:171], v[202:205], v[84:87]
	v_mfma_f32_16x16x32_bf16 v[68:71], v[164:167], v[206:209], v[68:71]
	v_mfma_f32_16x16x32_bf16 v[68:71], v[168:171], v[210:213], v[68:71]
	v_mfma_f32_16x16x32_bf16 v[112:115], v[172:175], v[182:185], v[112:115]
	v_mfma_f32_16x16x32_bf16 v[112:115], v[176:179], v[186:189], v[112:115]
	v_mfma_f32_16x16x32_bf16 v[96:99], v[172:175], v[190:193], v[96:99]
	v_mfma_f32_16x16x32_bf16 v[96:99], v[176:179], v[194:197], v[96:99]
	v_mfma_f32_16x16x32_bf16 v[80:83], v[172:175], v[198:201], v[80:83]
	v_mfma_f32_16x16x32_bf16 v[80:83], v[176:179], v[202:205], v[80:83]
	v_mfma_f32_16x16x32_bf16 v[64:67], v[172:175], v[206:209], v[64:67]
	v_mfma_f32_16x16x32_bf16 v[64:67], v[176:179], v[210:213], v[64:67]
	s_setprio 0
	s_barrier
; #define PG8_STAGE(bufoff, gbase, voff) do { _Pragma("unroll") for (int _i = 0; _i < 2; ++_i) \
;         __builtin_amdgcn_global_load_lds((const unsigned*)((const char*)(gbase) + (voff)[_i]), (LAS unsigned*)(lds + (bufoff) + ldsw + _i * 8192), 16, 0, 0); } while (0)
; #define PG8_LDA(dst, b, h) do { _Pragma("unroll") for (int m = 0; m < 4; ++m) _Pragma("unroll") for (int k = 0; k < 2; ++k) dst[m][k] = *(const LAS bf16x8*)(lds + PG8_SA(b, h) + aoff + m * 2048 + k * 1024); } while (0)
; #define PG8_MMA(ai, bj, At, Bt) do { __builtin_amdgcn_s_setprio(1); _Pragma("unroll") for (int m = 0; m < 4; ++m) _Pragma("unroll") for (int n = 0; n < 2; ++n) _Pragma("unroll") for (int k = 0; k < 2; ++k) \
;         acc[ai][bj][m][n] = __builtin_amdgcn_mfma_f32_16x16x32_bf16(Bt[n][k], At[m][k], acc[ai][bj][m][n], 0, 0, 0); __builtin_amdgcn_s_setprio(0); } while (0)
; #define PG8_WAIT_V(n) asm volatile("s_waitcnt vmcnt(" #n ")" ::: "memory")
; #define PG8_WAIT_L(n) asm volatile("s_waitcnt lgkmcnt(" #n ")" ::: "memory")
; #define PG8_BAR __builtin_amdgcn_s_barrier()
; #define PG8_SCHED __builtin_amdgcn_sched_barrier(0)
; template <class Epi>
; DI void gemm_phase(LAS unsigned char* lds, const Gemm g, const StaticOrder& S, const Epi& E) {
;     ...
;             PG8_LDA(At, 1, 1); PG8_STAGE(PG8_SB(1, 0), b3, voffB); PG8_STAGE(PG8_SB(1, 1), b3 + hstepB, voffB); PG8_STAGE(PG8_SA(1, 0), a3, voffA);
;             PG8_WAIT_V(8); PG8_WAIT_L(0); PG8_BAR; PG8_MMA(1, 0, At, B0); PG8_MMA(1, 1, At, B1); PG8_BAR; PG8_SCHED;
;         }
	s_add_i32 s30, s66, s35
	v_lshl_add_u64 v[214:215], v[214:215], 0, s[10:11]
	s_mov_b32 m0, s30
	ds_read_b128 v[182:185], v147 offset:49152
	ds_read_b128 v[186:189], v147 offset:50176
	ds_read_b128 v[190:193], v147 offset:51200
	ds_read_b128 v[194:197], v147 offset:52224
	ds_read_b128 v[198:201], v147 offset:53248
	ds_read_b128 v[202:205], v147 offset:54272
	ds_read_b128 v[206:209], v147 offset:55296
	ds_read_b128 v[210:213], v147 offset:56320
	global_load_lds_dwordx4 v[214:215], off
	s_add_i32 m0, s30, 0x2000
	s_add_u32 s28, s28, 0x100080
	v_lshl_add_u64 v[214:215], v[216:217], 0, s[10:11]
	s_addc_u32 s29, s29, 0
	s_add_i32 s30, s67, s35
	global_load_lds_dwordx4 v[214:215], off
	v_lshl_add_u64 v[214:215], s[28:29], 0, v[132:133]
	s_mov_b32 m0, s30
	s_nop 0
	global_load_lds_dwordx4 v[214:215], off
	v_lshl_add_u64 v[214:215], s[28:29], 0, v[128:129]
	s_add_i32 m0, s30, 0x2000
	s_nop 0
	global_load_lds_dwordx4 v[214:215], off
	v_lshl_add_u64 v[214:215], v[218:219], 0, s[10:11]
	s_mov_b32 m0, s46
	s_nop 0
	global_load_lds_dwordx4 v[214:215], off
	v_lshl_add_u64 v[214:215], v[220:221], 0, s[10:11]
	s_mov_b32 m0, s47
	s_nop 0
	global_load_lds_dwordx4 v[214:215], off
	s_waitcnt vmcnt(8)
	s_waitcnt lgkmcnt(0)
	s_setprio 1
	s_barrier
	v_mfma_f32_16x16x32_bf16 v[60:63], v[148:151], v[182:185], v[60:63]
	v_mfma_f32_16x16x32_bf16 v[60:63], v[152:155], v[186:189], v[60:63]
	v_mfma_f32_16x16x32_bf16 v[44:47], v[148:151], v[190:193], v[44:47]
	v_mfma_f32_16x16x32_bf16 v[44:47], v[152:155], v[194:197], v[44:47]
	v_mfma_f32_16x16x32_bf16 v[28:31], v[148:151], v[198:201], v[28:31]
	v_mfma_f32_16x16x32_bf16 v[28:31], v[152:155], v[202:205], v[28:31]
	v_mfma_f32_16x16x32_bf16 v[12:15], v[148:151], v[206:209], v[12:15]
	v_mfma_f32_16x16x32_bf16 v[12:15], v[152:155], v[210:213], v[12:15]
	v_mfma_f32_16x16x32_bf16 v[56:59], v[156:159], v[182:185], v[56:59]
	v_mfma_f32_16x16x32_bf16 v[56:59], v[160:163], v[186:189], v[56:59]
	v_mfma_f32_16x16x32_bf16 v[40:43], v[156:159], v[190:193], v[40:43]
	v_mfma_f32_16x16x32_bf16 v[40:43], v[160:163], v[194:197], v[40:43]
	v_mfma_f32_16x16x32_bf16 v[24:27], v[156:159], v[198:201], v[24:27]
	v_mfma_f32_16x16x32_bf16 v[24:27], v[160:163], v[202:205], v[24:27]
	v_mfma_f32_16x16x32_bf16 v[8:11], v[156:159], v[206:209], v[8:11]
	v_mfma_f32_16x16x32_bf16 v[8:11], v[160:163], v[210:213], v[8:11]
	s_setprio 0
	s_setprio 1
	v_mfma_f32_16x16x32_bf16 v[52:55], v[164:167], v[182:185], v[52:55]
	v_mfma_f32_16x16x32_bf16 v[52:55], v[168:171], v[186:189], v[52:55]
	v_mfma_f32_16x16x32_bf16 v[36:39], v[164:167], v[190:193], v[36:39]
	v_mfma_f32_16x16x32_bf16 v[36:39], v[168:171], v[194:197], v[36:39]
	v_mfma_f32_16x16x32_bf16 v[20:23], v[164:167], v[198:201], v[20:23]
	v_mfma_f32_16x16x32_bf16 v[20:23], v[168:171], v[202:205], v[20:23]
	v_mfma_f32_16x16x32_bf16 v[4:7], v[164:167], v[206:209], v[4:7]
	v_mfma_f32_16x16x32_bf16 v[4:7], v[168:171], v[210:213], v[4:7]
	v_mfma_f32_16x16x32_bf16 v[48:51], v[172:175], v[182:185], v[48:51]
	v_mfma_f32_16x16x32_bf16 v[48:51], v[176:179], v[186:189], v[48:51]
	v_mfma_f32_16x16x32_bf16 v[32:35], v[172:175], v[190:193], v[32:35]
	v_mfma_f32_16x16x32_bf16 v[32:35], v[176:179], v[194:197], v[32:35]
	v_mfma_f32_16x16x32_bf16 v[16:19], v[172:175], v[198:201], v[16:19]
	v_mfma_f32_16x16x32_bf16 v[16:19], v[176:179], v[202:205], v[16:19]
	v_mfma_f32_16x16x32_bf16 v[0:3], v[172:175], v[206:209], v[0:3]
	v_mfma_f32_16x16x32_bf16 v[0:3], v[176:179], v[210:213], v[0:3]
	s_setprio 0
	s_barrier
	s_add_u32 s26, s26, 0x100
	s_addc_u32 s27, s27, 0
	s_add_u32 s63, s63, 0x100
	s_addc_u32 s64, s64, 0
	s_cmp_ge_i32 s65, s43
	s_mov_b32 s28, s65
	s_cbranch_scc0 .LBB0_201

; #define PG8_STAGE(bufoff, gbase, voff) do { _Pragma("unroll") for (int _i = 0; _i < 2; ++_i) \
;         __builtin_amdgcn_global_load_lds((const unsigned*)((const char*)(gbase) + (voff)[_i]), (LAS unsigned*)(lds + (bufoff) + ldsw + _i * 8192), 16, 0, 0); } while (0)
; #define PG8_LDA(dst, b, h) do { _Pragma("unroll") for (int m = 0; m < 4; ++m) _Pragma("unroll") for (int k = 0; k < 2; ++k) dst[m][k] = *(const LAS bf16x8*)(lds + PG8_SA(b, h) + aoff + m * 2048 + k * 1024); } while (0)
; #define PG8_LDB(dst, b, h) do { _Pragma("unroll") for (int n = 0; n < 2; ++n) _Pragma("unroll") for (int k = 0; k < 2; ++k) dst[n][k] = *(const LAS bf16x8*)(lds + PG8_SB(b, h) + boff + n * 2048 + k * 1024); } while (0)
; #define PG8_MMA(ai, bj, At, Bt) do { __builtin_amdgcn_s_setprio(1); _Pragma("unroll") for (int m = 0; m < 4; ++m) _Pragma("unroll") for (int n = 0; n < 2; ++n) _Pragma("unroll") for (int k = 0; k < 2; ++k) \
;         acc[ai][bj][m][n] = __builtin_amdgcn_mfma_f32_16x16x32_bf16(Bt[n][k], At[m][k], acc[ai][bj][m][n], 0, 0, 0); __builtin_amdgcn_s_setprio(0); } while (0)
; #define PG8_WAIT_V(n) asm volatile("s_waitcnt vmcnt(" #n ")" ::: "memory")
; #define PG8_WAIT_L(n) asm volatile("s_waitcnt lgkmcnt(" #n ")" ::: "memory")
; #define PG8_BAR __builtin_amdgcn_s_barrier()
; #define PG8_SCHED __builtin_amdgcn_sched_barrier(0)
; template <class Epi>
; DI void gemm_phase(LAS unsigned char* lds, const Gemm g, const StaticOrder& S, const Epi& E) {
;     ...
;             const bool last = (t == nt - 2);
;             const char* a1 = cA + (size_t)(t + 1) * kstep;
;             const char* a2 = last ? nA : cA + (size_t)(t + 2) * kstep; const char* b2 = last ? nB : cB + (size_t)(t + 2) * kstep;
;             const char* a3 = a2 + kstep; const char* b3 = b2 + kstep;
;             PG8_LDB(B0, 0, 0); PG8_LDB(B1, 0, 1); PG8_SCHED; PG8_LDA(At, 0, 0); PG8_STAGE(PG8_SA(1, 1), a1 + hstepA, voffA);
;             PG8_WAIT_V(8); PG8_WAIT_L(0); PG8_BAR; PG8_MMA(0, 0, At, B0); PG8_MMA(0, 1, At, B1); PG8_BAR; PG8_SCHED;
;             PG8_LDA(At, 0, 1); PG8_STAGE(PG8_SB(0, 0), b2, voffB); PG8_STAGE(PG8_SB(0, 1), b2 + hstepB, voffB); PG8_STAGE(PG8_SA(0, 0), a2, voffA);
;             PG8_WAIT_V(8); PG8_WAIT_L(0); PG8_BAR; PG8_MMA(1, 0, At, B0); PG8_MMA(1, 1, At, B1); PG8_BAR; PG8_SCHED;
.LBB0_302:
	ds_read_b128 v[128:131], v174
	ds_read_b128 v[132:135], v174 offset:1024
	ds_read_b128 v[156:159], v174 offset:2048
	ds_read_b128 v[160:163], v174 offset:3072
	ds_read_b128 v[164:167], v175
	ds_read_b128 v[168:171], v175 offset:1024
	ds_read_b128 v[182:185], v175 offset:2048
	ds_read_b128 v[186:189], v175 offset:3072
	s_add_i32 s30, s10, 2
	s_add_u32 s6, s8, 0x100
	s_addc_u32 s7, s9, 0
	s_cmp_eq_u32 s68, s10
	s_cselect_b32 s10, s17, s18
	s_cselect_b32 s13, s43, s7
	s_cselect_b32 s12, s42, s6
	s_cselect_b32 s11, s16, s19
	v_lshl_add_u64 v[178:179], s[8:9], 0, v[148:149]
	s_add_i32 m0, s61, 0xc000
	ds_read_b128 v[190:193], v176
	ds_read_b128 v[194:197], v176 offset:1024
	ds_read_b128 v[198:201], v176 offset:2048
	ds_read_b128 v[202:205], v176 offset:3072
	ds_read_b128 v[206:209], v176 offset:4096
	ds_read_b128 v[210:213], v176 offset:5120
	ds_read_b128 v[214:217], v176 offset:6144
	ds_read_b128 v[218:221], v176 offset:7168
	global_load_lds_dwordx4 v[178:179], off
	v_lshl_add_u64 v[178:179], s[8:9], 0, v[150:151]
	s_add_i32 m0, s61, 0xe000
	s_nop 0
	global_load_lds_dwordx4 v[178:179], off
	s_waitcnt vmcnt(8)
	s_waitcnt lgkmcnt(0)
	s_setprio 1
	s_barrier
	v_mfma_f32_16x16x32_bf16 v[120:123], v[128:131], v[190:193], v[120:123]
	v_mfma_f32_16x16x32_bf16 v[120:123], v[132:135], v[194:197], v[120:123]
	v_mfma_f32_16x16x32_bf16 v[108:111], v[128:131], v[198:201], v[108:111]
	v_mfma_f32_16x16x32_bf16 v[108:111], v[132:135], v[202:205], v[108:111]
	v_mfma_f32_16x16x32_bf16 v[92:95], v[128:131], v[206:209], v[92:95]
	v_mfma_f32_16x16x32_bf16 v[92:95], v[132:135], v[210:213], v[92:95]
	v_mfma_f32_16x16x32_bf16 v[76:79], v[128:131], v[214:217], v[76:79]
	v_mfma_f32_16x16x32_bf16 v[76:79], v[132:135], v[218:221], v[76:79]
	v_mfma_f32_16x16x32_bf16 v[124:127], v[156:159], v[190:193], v[124:127]
	v_mfma_f32_16x16x32_bf16 v[124:127], v[160:163], v[194:197], v[124:127]
	v_mfma_f32_16x16x32_bf16 v[104:107], v[156:159], v[198:201], v[104:107]
	v_mfma_f32_16x16x32_bf16 v[104:107], v[160:163], v[202:205], v[104:107]
	v_mfma_f32_16x16x32_bf16 v[88:91], v[156:159], v[206:209], v[88:91]
	v_mfma_f32_16x16x32_bf16 v[88:91], v[160:163], v[210:213], v[88:91]
	v_mfma_f32_16x16x32_bf16 v[72:75], v[156:159], v[214:217], v[72:75]
	v_mfma_f32_16x16x32_bf16 v[72:75], v[160:163], v[218:221], v[72:75]
	s_setprio 0
	s_setprio 1
	v_mfma_f32_16x16x32_bf16 v[116:119], v[164:167], v[190:193], v[116:119]
	v_mfma_f32_16x16x32_bf16 v[116:119], v[168:171], v[194:197], v[116:119]
	v_mfma_f32_16x16x32_bf16 v[100:103], v[164:167], v[198:201], v[100:103]
	v_mfma_f32_16x16x32_bf16 v[100:103], v[168:171], v[202:205], v[100:103]
	v_mfma_f32_16x16x32_bf16 v[84:87], v[164:167], v[206:209], v[84:87]
	v_mfma_f32_16x16x32_bf16 v[84:87], v[168:171], v[210:213], v[84:87]
	v_mfma_f32_16x16x32_bf16 v[68:71], v[164:167], v[214:217], v[68:71]
	v_mfma_f32_16x16x32_bf16 v[68:71], v[168:171], v[218:221], v[68:71]
	v_mfma_f32_16x16x32_bf16 v[112:115], v[182:185], v[190:193], v[112:115]
	v_mfma_f32_16x16x32_bf16 v[112:115], v[186:189], v[194:197], v[112:115]
	v_mfma_f32_16x16x32_bf16 v[96:99], v[182:185], v[198:201], v[96:99]
	v_mfma_f32_16x16x32_bf16 v[96:99], v[186:189], v[202:205], v[96:99]
	v_mfma_f32_16x16x32_bf16 v[80:83], v[182:185], v[206:209], v[80:83]
	v_mfma_f32_16x16x32_bf16 v[80:83], v[186:189], v[210:213], v[80:83]
	v_mfma_f32_16x16x32_bf16 v[64:67], v[182:185], v[214:217], v[64:67]
	v_mfma_f32_16x16x32_bf16 v[64:67], v[186:189], v[218:221], v[64:67]
	s_setprio 0
	s_barrier
	s_add_i32 s8, s69, s59
	v_lshl_add_u64 v[178:179], s[10:11], 0, v[140:141]
	s_mov_b32 m0, s8
	ds_read_b128 v[190:193], v176 offset:16384
	ds_read_b128 v[194:197], v176 offset:17408
	ds_read_b128 v[198:201], v176 offset:18432
	ds_read_b128 v[202:205], v176 offset:19456
	ds_read_b128 v[206:209], v176 offset:20480
	ds_read_b128 v[210:213], v176 offset:21504
	ds_read_b128 v[214:217], v176 offset:22528
	ds_read_b128 v[218:221], v176 offset:23552
	global_load_lds_dwordx4 v[178:179], off
	s_add_i32 m0, s8, 0x2000
	s_add_u32 s8, s10, 0x40000
	v_lshl_add_u64 v[222:223], s[10:11], 0, v[136:137]
	s_addc_u32 s9, s11, 0
	s_add_i32 s41, s70, s59
	global_load_lds_dwordx4 v[222:223], off
	v_lshl_add_u64 v[224:225], s[8:9], 0, v[140:141]
	s_mov_b32 m0, s41
	v_lshl_add_u64 v[226:227], s[12:13], 0, v[138:139]
	global_load_lds_dwordx4 v[224:225], off
	v_lshl_add_u64 v[224:225], s[8:9], 0, v[136:137]
	s_add_i32 m0, s41, 0x2000
	s_nop 0
	global_load_lds_dwordx4 v[224:225], off
	v_lshl_add_u64 v[224:225], s[12:13], 0, v[142:143]
	s_mov_b32 m0, s61
	s_nop 0
	global_load_lds_dwordx4 v[224:225], off
	s_mov_b32 m0, s62
	s_nop 0
	global_load_lds_dwordx4 v[226:227], off
	s_waitcnt vmcnt(8)
	s_waitcnt lgkmcnt(0)
	s_setprio 1
	s_barrier
; #define PG8_STAGE(bufoff, gbase, voff) do { _Pragma("unroll") for (int _i = 0; _i < 2; ++_i) \
;         __builtin_amdgcn_global_load_lds((const unsigned*)((const char*)(gbase) + (voff)[_i]), (LAS unsigned*)(lds + (bufoff) + ldsw + _i * 8192), 16, 0, 0); } while (0)
; #define PG8_LDA(dst, b, h) do { _Pragma("unroll") for (int m = 0; m < 4; ++m) _Pragma("unroll") for (int k = 0; k < 2; ++k) dst[m][k] = *(const LAS bf16x8*)(lds + PG8_SA(b, h) + aoff + m * 2048 + k * 1024); } while (0)
; #define PG8_LDB(dst, b, h) do { _Pragma("unroll") for (int n = 0; n < 2; ++n) _Pragma("unroll") for (int k = 0; k < 2; ++k) dst[n][k] = *(const LAS bf16x8*)(lds + PG8_SB(b, h) + boff + n * 2048 + k * 1024); } while (0)
; #define PG8_MMA(ai, bj, At, Bt) do { __builtin_amdgcn_s_setprio(1); _Pragma("unroll") for (int m = 0; m < 4; ++m) _Pragma("unroll") for (int n = 0; n < 2; ++n) _Pragma("unroll") for (int k = 0; k < 2; ++k) \
;         acc[ai][bj][m][n] = __builtin_amdgcn_mfma_f32_16x16x32_bf16(Bt[n][k], At[m][k], acc[ai][bj][m][n], 0, 0, 0); __builtin_amdgcn_s_setprio(0); } while (0)
; #define PG8_WAIT_V(n) asm volatile("s_waitcnt vmcnt(" #n ")" ::: "memory")
; #define PG8_WAIT_L(n) asm volatile("s_waitcnt lgkmcnt(" #n ")" ::: "memory")
; #define PG8_BAR __builtin_amdgcn_s_barrier()
; #define PG8_SCHED __builtin_amdgcn_sched_barrier(0)
; template <class Epi>
; DI void gemm_phase(LAS unsigned char* lds, const Gemm g, const StaticOrder& S, const Epi& E) {
;     ...
;             PG8_WAIT_V(8); PG8_WAIT_L(0); PG8_BAR; PG8_MMA(1, 0, At, B0); PG8_MMA(1, 1, At, B1); PG8_BAR; PG8_SCHED;
;             PG8_LDB(B0, 1, 0); PG8_LDB(B1, 1, 1); PG8_SCHED; PG8_LDA(At, 1, 0); PG8_STAGE(PG8_SA(0, 1), a2 + hstepA, voffA);
;             PG8_WAIT_V(8); PG8_WAIT_L(0); PG8_BAR; PG8_MMA(0, 0, At, B0); PG8_MMA(0, 1, At, B1); PG8_BAR; PG8_SCHED;
	v_mfma_f32_16x16x32_bf16 v[60:63], v[128:131], v[190:193], v[60:63]
	v_mfma_f32_16x16x32_bf16 v[60:63], v[132:135], v[194:197], v[60:63]
	v_mfma_f32_16x16x32_bf16 v[44:47], v[128:131], v[198:201], v[44:47]
	v_mfma_f32_16x16x32_bf16 v[44:47], v[132:135], v[202:205], v[44:47]
	v_mfma_f32_16x16x32_bf16 v[28:31], v[128:131], v[206:209], v[28:31]
	v_mfma_f32_16x16x32_bf16 v[28:31], v[132:135], v[210:213], v[28:31]
	v_mfma_f32_16x16x32_bf16 v[12:15], v[128:131], v[214:217], v[12:15]
	v_mfma_f32_16x16x32_bf16 v[12:15], v[132:135], v[218:221], v[12:15]
	v_mfma_f32_16x16x32_bf16 v[56:59], v[156:159], v[190:193], v[56:59]
	v_mfma_f32_16x16x32_bf16 v[56:59], v[160:163], v[194:197], v[56:59]
	v_mfma_f32_16x16x32_bf16 v[40:43], v[156:159], v[198:201], v[40:43]
	v_mfma_f32_16x16x32_bf16 v[40:43], v[160:163], v[202:205], v[40:43]
	v_mfma_f32_16x16x32_bf16 v[24:27], v[156:159], v[206:209], v[24:27]
	v_mfma_f32_16x16x32_bf16 v[24:27], v[160:163], v[210:213], v[24:27]
	v_mfma_f32_16x16x32_bf16 v[8:11], v[156:159], v[214:217], v[8:11]
	v_mfma_f32_16x16x32_bf16 v[8:11], v[160:163], v[218:221], v[8:11]
	s_setprio 0
	s_setprio 1
	v_mfma_f32_16x16x32_bf16 v[52:55], v[164:167], v[190:193], v[52:55]
	v_mfma_f32_16x16x32_bf16 v[52:55], v[168:171], v[194:197], v[52:55]
	v_mfma_f32_16x16x32_bf16 v[36:39], v[164:167], v[198:201], v[36:39]
	v_mfma_f32_16x16x32_bf16 v[36:39], v[168:171], v[202:205], v[36:39]
	v_mfma_f32_16x16x32_bf16 v[20:23], v[164:167], v[206:209], v[20:23]
	v_mfma_f32_16x16x32_bf16 v[20:23], v[168:171], v[210:213], v[20:23]
	v_mfma_f32_16x16x32_bf16 v[4:7], v[164:167], v[214:217], v[4:7]
	v_mfma_f32_16x16x32_bf16 v[4:7], v[168:171], v[218:221], v[4:7]
	v_mfma_f32_16x16x32_bf16 v[48:51], v[182:185], v[190:193], v[48:51]
	v_mfma_f32_16x16x32_bf16 v[48:51], v[186:189], v[194:197], v[48:51]
	v_mfma_f32_16x16x32_bf16 v[32:35], v[182:185], v[198:201], v[32:35]
	v_mfma_f32_16x16x32_bf16 v[32:35], v[186:189], v[202:205], v[32:35]
	v_mfma_f32_16x16x32_bf16 v[16:19], v[182:185], v[206:209], v[16:19]
	v_mfma_f32_16x16x32_bf16 v[16:19], v[186:189], v[210:213], v[16:19]
	v_mfma_f32_16x16x32_bf16 v[0:3], v[182:185], v[214:217], v[0:3]
	v_mfma_f32_16x16x32_bf16 v[0:3], v[186:189], v[218:221], v[0:3]
	s_setprio 0
	s_barrier
	s_add_i32 s41, 0, 0x18000
	s_add_i32 s50, 0, 0x1c000
	v_add_u32_e32 v160, s41, v173
	v_add_u32_e32 v181, s50, v173
	ds_read_b128 v[128:131], v160
	ds_read_b128 v[132:135], v160 offset:1024
	ds_read_b128 v[156:159], v160 offset:2048
	ds_read_b128 v[160:163], v160 offset:3072
	ds_read_b128 v[164:167], v181
	ds_read_b128 v[168:171], v181 offset:1024
	ds_read_b128 v[182:185], v181 offset:2048
	ds_read_b128 v[186:189], v181 offset:3072
	s_add_u32 s8, s12, 0x110000
	s_addc_u32 s9, s13, 0
	s_mov_b32 m0, s63
	v_lshl_add_u64 v[228:229], s[8:9], 0, v[142:143]
	ds_read_b128 v[190:193], v176 offset:32768
	ds_read_b128 v[194:197], v176 offset:33792
	ds_read_b128 v[198:201], v176 offset:34816
	ds_read_b128 v[202:205], v176 offset:35840
	ds_read_b128 v[206:209], v176 offset:36864
	ds_read_b128 v[210:213], v176 offset:37888
	ds_read_b128 v[214:217], v176 offset:38912
	ds_read_b128 v[218:221], v176 offset:39936
	global_load_lds_dwordx4 v[228:229], off
	v_lshl_add_u64 v[228:229], s[8:9], 0, v[138:139]
	s_mov_b32 m0, s64
	s_nop 0
	global_load_lds_dwordx4 v[228:229], off
	s_waitcnt vmcnt(8)
	s_waitcnt lgkmcnt(0)
	s_setprio 1
	s_barrier
	v_mfma_f32_16x16x32_bf16 v[120:123], v[128:131], v[190:193], v[120:123]
	v_mfma_f32_16x16x32_bf16 v[120:123], v[132:135], v[194:197], v[120:123]
	v_mfma_f32_16x16x32_bf16 v[108:111], v[128:131], v[198:201], v[108:111]
	v_mfma_f32_16x16x32_bf16 v[108:111], v[132:135], v[202:205], v[108:111]
	v_mfma_f32_16x16x32_bf16 v[92:95], v[128:131], v[206:209], v[92:95]
	v_mfma_f32_16x16x32_bf16 v[92:95], v[132:135], v[210:213], v[92:95]
	v_mfma_f32_16x16x32_bf16 v[76:79], v[128:131], v[214:217], v[76:79]
	v_mfma_f32_16x16x32_bf16 v[76:79], v[132:135], v[218:221], v[76:79]
	v_mfma_f32_16x16x32_bf16 v[124:127], v[156:159], v[190:193], v[124:127]
	v_mfma_f32_16x16x32_bf16 v[124:127], v[160:163], v[194:197], v[124:127]
	v_mfma_f32_16x16x32_bf16 v[104:107], v[156:159], v[198:201], v[104:107]
	v_mfma_f32_16x16x32_bf16 v[104:107], v[160:163], v[202:205], v[104:107]
	v_mfma_f32_16x16x32_bf16 v[88:91], v[156:159], v[206:209], v[88:91]
	v_mfma_f32_16x16x32_bf16 v[88:91], v[160:163], v[210:213], v[88:91]
	v_mfma_f32_16x16x32_bf16 v[72:75], v[156:159], v[214:217], v[72:75]
	v_mfma_f32_16x16x32_bf16 v[72:75], v[160:163], v[218:221], v[72:75]
	s_setprio 0
	s_setprio 1
	v_mfma_f32_16x16x32_bf16 v[116:119], v[164:167], v[190:193], v[116:119]
	v_mfma_f32_16x16x32_bf16 v[116:119], v[168:171], v[194:197], v[116:119]
	v_mfma_f32_16x16x32_bf16 v[100:103], v[164:167], v[198:201], v[100:103]
	v_mfma_f32_16x16x32_bf16 v[100:103], v[168:171], v[202:205], v[100:103]
	v_mfma_f32_16x16x32_bf16 v[84:87], v[164:167], v[206:209], v[84:87]
	v_mfma_f32_16x16x32_bf16 v[84:87], v[168:171], v[210:213], v[84:87]
	v_mfma_f32_16x16x32_bf16 v[68:71], v[164:167], v[214:217], v[68:71]
	v_mfma_f32_16x16x32_bf16 v[68:71], v[168:171], v[218:221], v[68:71]
	v_mfma_f32_16x16x32_bf16 v[112:115], v[182:185], v[190:193], v[112:115]
	v_mfma_f32_16x16x32_bf16 v[112:115], v[186:189], v[194:197], v[112:115]
	v_mfma_f32_16x16x32_bf16 v[96:99], v[182:185], v[198:201], v[96:99]
	v_mfma_f32_16x16x32_bf16 v[96:99], v[186:189], v[202:205], v[96:99]
	v_mfma_f32_16x16x32_bf16 v[80:83], v[182:185], v[206:209], v[80:83]
	v_mfma_f32_16x16x32_bf16 v[80:83], v[186:189], v[210:213], v[80:83]
	v_mfma_f32_16x16x32_bf16 v[64:67], v[182:185], v[214:217], v[64:67]
	v_mfma_f32_16x16x32_bf16 v[64:67], v[186:189], v[218:221], v[64:67]
	s_setprio 0
	s_barrier
; #define PG8_STAGE(bufoff, gbase, voff) do { _Pragma("unroll") for (int _i = 0; _i < 2; ++_i) \
;         __builtin_amdgcn_global_load_lds((const unsigned*)((const char*)(gbase) + (voff)[_i]), (LAS unsigned*)(lds + (bufoff) + ldsw + _i * 8192), 16, 0, 0); } while (0)
; #define PG8_LDA(dst, b, h) do { _Pragma("unroll") for (int m = 0; m < 4; ++m) _Pragma("unroll") for (int k = 0; k < 2; ++k) dst[m][k] = *(const LAS bf16x8*)(lds + PG8_SA(b, h) + aoff + m * 2048 + k * 1024); } while (0)
; #define PG8_MMA(ai, bj, At, Bt) do { __builtin_amdgcn_s_setprio(1); _Pragma("unroll") for (int m = 0; m < 4; ++m) _Pragma("unroll") for (int n = 0; n < 2; ++n) _Pragma("unroll") for (int k = 0; k < 2; ++k) \
;         acc[ai][bj][m][n] = __builtin_amdgcn_mfma_f32_16x16x32_bf16(Bt[n][k], At[m][k], acc[ai][bj][m][n], 0, 0, 0); __builtin_amdgcn_s_setprio(0); } while (0)
; #define PG8_WAIT_V(n) asm volatile("s_waitcnt vmcnt(" #n ")" ::: "memory")
; #define PG8_WAIT_L(n) asm volatile("s_waitcnt lgkmcnt(" #n ")" ::: "memory")
; #define PG8_BAR __builtin_amdgcn_s_barrier()
; #define PG8_SCHED __builtin_amdgcn_sched_barrier(0)
; template <class Epi>
; DI void gemm_phase(LAS unsigned char* lds, const Gemm g, const StaticOrder& S, const Epi& E) {
;     ...
;             PG8_LDA(At, 1, 1); PG8_STAGE(PG8_SB(1, 0), b3, voffB); PG8_STAGE(PG8_SB(1, 1), b3 + hstepB, voffB); PG8_STAGE(PG8_SA(1, 0), a3, voffA);
;             PG8_WAIT_V(8); PG8_WAIT_L(0); PG8_BAR; PG8_MMA(1, 0, At, B0); PG8_MMA(1, 1, At, B1); PG8_BAR; PG8_SCHED;
;         }
	s_add_i32 s8, s41, s59
	v_lshl_add_u64 v[178:179], v[178:179], 0, s[28:29]
	s_mov_b32 m0, s8
	ds_read_b128 v[190:193], v176 offset:49152
	ds_read_b128 v[194:197], v176 offset:50176
	ds_read_b128 v[198:201], v176 offset:51200
	ds_read_b128 v[202:205], v176 offset:52224
	ds_read_b128 v[206:209], v176 offset:53248
	ds_read_b128 v[210:213], v176 offset:54272
	ds_read_b128 v[214:217], v176 offset:55296
	ds_read_b128 v[218:221], v176 offset:56320
	global_load_lds_dwordx4 v[178:179], off
	s_add_i32 m0, s8, 0x2000
	s_add_u32 s8, s10, 0x40080
	v_lshl_add_u64 v[178:179], v[222:223], 0, s[28:29]
	s_addc_u32 s9, s11, 0
	s_add_i32 s10, s50, s59
	global_load_lds_dwordx4 v[178:179], off
	v_lshl_add_u64 v[178:179], s[8:9], 0, v[140:141]
	s_mov_b32 m0, s10
	s_nop 0
	global_load_lds_dwordx4 v[178:179], off
	v_lshl_add_u64 v[178:179], s[8:9], 0, v[136:137]
	s_add_i32 m0, s10, 0x2000
	s_nop 0
	global_load_lds_dwordx4 v[178:179], off
	v_lshl_add_u64 v[178:179], v[224:225], 0, s[28:29]
	s_mov_b32 m0, s66
	s_nop 0
	global_load_lds_dwordx4 v[178:179], off
	v_lshl_add_u64 v[178:179], v[226:227], 0, s[28:29]
	s_mov_b32 m0, s67
	s_nop 0
	global_load_lds_dwordx4 v[178:179], off
	s_waitcnt vmcnt(8)
	s_waitcnt lgkmcnt(0)
	s_setprio 1
	s_barrier
	v_mfma_f32_16x16x32_bf16 v[60:63], v[128:131], v[190:193], v[60:63]
	v_mfma_f32_16x16x32_bf16 v[60:63], v[132:135], v[194:197], v[60:63]
	v_mfma_f32_16x16x32_bf16 v[44:47], v[128:131], v[198:201], v[44:47]
	v_mfma_f32_16x16x32_bf16 v[44:47], v[132:135], v[202:205], v[44:47]
	v_mfma_f32_16x16x32_bf16 v[28:31], v[128:131], v[206:209], v[28:31]
	v_mfma_f32_16x16x32_bf16 v[28:31], v[132:135], v[210:213], v[28:31]
	v_mfma_f32_16x16x32_bf16 v[12:15], v[128:131], v[214:217], v[12:15]
	v_mfma_f32_16x16x32_bf16 v[12:15], v[132:135], v[218:221], v[12:15]
	v_mfma_f32_16x16x32_bf16 v[56:59], v[156:159], v[190:193], v[56:59]
	v_mfma_f32_16x16x32_bf16 v[56:59], v[160:163], v[194:197], v[56:59]
	v_mfma_f32_16x16x32_bf16 v[40:43], v[156:159], v[198:201], v[40:43]
	v_mfma_f32_16x16x32_bf16 v[40:43], v[160:163], v[202:205], v[40:43]
	v_mfma_f32_16x16x32_bf16 v[24:27], v[156:159], v[206:209], v[24:27]
	v_mfma_f32_16x16x32_bf16 v[24:27], v[160:163], v[210:213], v[24:27]
	v_mfma_f32_16x16x32_bf16 v[8:11], v[156:159], v[214:217], v[8:11]
	v_mfma_f32_16x16x32_bf16 v[8:11], v[160:163], v[218:221], v[8:11]
	s_setprio 0
	s_setprio 1
	v_mfma_f32_16x16x32_bf16 v[52:55], v[164:167], v[190:193], v[52:55]
	v_mfma_f32_16x16x32_bf16 v[52:55], v[168:171], v[194:197], v[52:55]
	v_mfma_f32_16x16x32_bf16 v[36:39], v[164:167], v[198:201], v[36:39]
	v_mfma_f32_16x16x32_bf16 v[36:39], v[168:171], v[202:205], v[36:39]
	v_mfma_f32_16x16x32_bf16 v[20:23], v[164:167], v[206:209], v[20:23]
	v_mfma_f32_16x16x32_bf16 v[20:23], v[168:171], v[210:213], v[20:23]
	v_mfma_f32_16x16x32_bf16 v[4:7], v[164:167], v[214:217], v[4:7]
	v_mfma_f32_16x16x32_bf16 v[4:7], v[168:171], v[218:221], v[4:7]
	v_mfma_f32_16x16x32_bf16 v[48:51], v[182:185], v[190:193], v[48:51]
	v_mfma_f32_16x16x32_bf16 v[48:51], v[186:189], v[194:197], v[48:51]
	v_mfma_f32_16x16x32_bf16 v[32:35], v[182:185], v[198:201], v[32:35]
	v_mfma_f32_16x16x32_bf16 v[32:35], v[186:189], v[202:205], v[32:35]
	v_mfma_f32_16x16x32_bf16 v[16:19], v[182:185], v[206:209], v[16:19]
	v_mfma_f32_16x16x32_bf16 v[16:19], v[186:189], v[210:213], v[16:19]
	v_mfma_f32_16x16x32_bf16 v[0:3], v[182:185], v[214:217], v[0:3]
	v_mfma_f32_16x16x32_bf16 v[0:3], v[186:189], v[218:221], v[0:3]
	s_setprio 0
	s_barrier
	s_add_u32 s18, s18, 0x100
	s_addc_u32 s19, s19, 0
	s_cmp_ge_i32 s30, s65
	s_mov_b64 s[8:9], s[6:7]
	s_mov_b32 s10, s30
	s_cbranch_scc0 .LBB0_302

; #define PG8_STAGE(bufoff, gbase, voff) do { _Pragma("unroll") for (int _i = 0; _i < 2; ++_i) \
;         __builtin_amdgcn_global_load_lds((const unsigned*)((const char*)(gbase) + (voff)[_i]), (LAS unsigned*)(lds + (bufoff) + ldsw + _i * 8192), 16, 0, 0); } while (0)
; #define PG8_LDA(dst, b, h) do { _Pragma("unroll") for (int m = 0; m < 4; ++m) _Pragma("unroll") for (int k = 0; k < 2; ++k) dst[m][k] = *(const LAS bf16x8*)(lds + PG8_SA(b, h) + aoff + m * 2048 + k * 1024); } while (0)
; #define PG8_LDB(dst, b, h) do { _Pragma("unroll") for (int n = 0; n < 2; ++n) _Pragma("unroll") for (int k = 0; k < 2; ++k) dst[n][k] = *(const LAS bf16x8*)(lds + PG8_SB(b, h) + boff + n * 2048 + k * 1024); } while (0)
; #define PG8_MMA(ai, bj, At, Bt) do { __builtin_amdgcn_s_setprio(1); _Pragma("unroll") for (int m = 0; m < 4; ++m) _Pragma("unroll") for (int n = 0; n < 2; ++n) _Pragma("unroll") for (int k = 0; k < 2; ++k) \
;         acc[ai][bj][m][n] = __builtin_amdgcn_mfma_f32_16x16x32_bf16(Bt[n][k], At[m][k], acc[ai][bj][m][n], 0, 0, 0); __builtin_amdgcn_s_setprio(0); } while (0)
; #define PG8_WAIT_V(n) asm volatile("s_waitcnt vmcnt(" #n ")" ::: "memory")
; #define PG8_WAIT_L(n) asm volatile("s_waitcnt lgkmcnt(" #n ")" ::: "memory")
; #define PG8_BAR __builtin_amdgcn_s_barrier()
; #define PG8_SCHED __builtin_amdgcn_sched_barrier(0)
; template <class Epi>
; DI void gemm_phase(LAS unsigned char* lds, const Gemm g, const StaticOrder& S, const Epi& E) {
;     ...
;             const bool last = (t == nt - 2);
;             const char* a1 = cA + (size_t)(t + 1) * kstep;
;             const char* a2 = last ? nA : cA + (size_t)(t + 2) * kstep; const char* b2 = last ? nB : cB + (size_t)(t + 2) * kstep;
;             const char* a3 = a2 + kstep; const char* b3 = b2 + kstep;
;             PG8_LDB(B0, 0, 0); PG8_LDB(B1, 0, 1); PG8_SCHED; PG8_LDA(At, 0, 0); PG8_STAGE(PG8_SA(1, 1), a1 + hstepA, voffA);
;             PG8_WAIT_V(8); PG8_WAIT_L(0); PG8_BAR; PG8_MMA(0, 0, At, B0); PG8_MMA(0, 1, At, B1); PG8_BAR; PG8_SCHED;
;             PG8_LDA(At, 0, 1); PG8_STAGE(PG8_SB(0, 0), b2, voffB); PG8_STAGE(PG8_SB(0, 1), b2 + hstepB, voffB); PG8_STAGE(PG8_SA(0, 0), a2, voffA);
;             PG8_WAIT_V(8); PG8_WAIT_L(0); PG8_BAR; PG8_MMA(1, 0, At, B0); PG8_MMA(1, 1, At, B1); PG8_BAR; PG8_SCHED;
.LBB0_329:
	ds_read_b128 v[154:157], v150
	ds_read_b128 v[158:161], v150 offset:1024
	ds_read_b128 v[162:165], v150 offset:2048
	ds_read_b128 v[166:169], v150 offset:3072
	ds_read_b128 v[170:173], v151
	ds_read_b128 v[174:177], v151 offset:1024
	ds_read_b128 v[182:185], v151 offset:2048
	ds_read_b128 v[186:189], v151 offset:3072
	s_add_i32 s73, s30, 2
	s_add_u32 s6, s8, 0x100
	s_addc_u32 s7, s9, 0
	s_cmp_eq_u32 s62, s30
	s_cselect_b32 s30, s70, s71
	s_cselect_b32 s39, s27, s7
	s_cselect_b32 s38, s26, s6
	s_cselect_b32 s31, s25, s72
	v_lshl_add_u64 v[146:147], s[8:9], 0, v[138:139]
	s_add_i32 m0, s47, 0xc000
	ds_read_b128 v[190:193], v152
	ds_read_b128 v[194:197], v152 offset:1024
	ds_read_b128 v[198:201], v152 offset:2048
	ds_read_b128 v[202:205], v152 offset:3072
	ds_read_b128 v[206:209], v152 offset:4096
	ds_read_b128 v[210:213], v152 offset:5120
	ds_read_b128 v[214:217], v152 offset:6144
	ds_read_b128 v[218:221], v152 offset:7168
	global_load_lds_dwordx4 v[146:147], off
	v_lshl_add_u64 v[146:147], s[8:9], 0, v[140:141]
	s_add_i32 m0, s47, 0xe000
	s_nop 0
	global_load_lds_dwordx4 v[146:147], off
	s_waitcnt vmcnt(8)
	s_waitcnt lgkmcnt(0)
	s_setprio 1
	s_barrier
	v_mfma_f32_16x16x32_bf16 v[120:123], v[154:157], v[190:193], v[120:123]
	v_mfma_f32_16x16x32_bf16 v[120:123], v[158:161], v[194:197], v[120:123]
	v_mfma_f32_16x16x32_bf16 v[108:111], v[154:157], v[198:201], v[108:111]
	v_mfma_f32_16x16x32_bf16 v[108:111], v[158:161], v[202:205], v[108:111]
	v_mfma_f32_16x16x32_bf16 v[92:95], v[154:157], v[206:209], v[92:95]
	v_mfma_f32_16x16x32_bf16 v[92:95], v[158:161], v[210:213], v[92:95]
	v_mfma_f32_16x16x32_bf16 v[76:79], v[154:157], v[214:217], v[76:79]
	v_mfma_f32_16x16x32_bf16 v[76:79], v[158:161], v[218:221], v[76:79]
	v_mfma_f32_16x16x32_bf16 v[124:127], v[162:165], v[190:193], v[124:127]
	v_mfma_f32_16x16x32_bf16 v[124:127], v[166:169], v[194:197], v[124:127]
	v_mfma_f32_16x16x32_bf16 v[104:107], v[162:165], v[198:201], v[104:107]
	v_mfma_f32_16x16x32_bf16 v[104:107], v[166:169], v[202:205], v[104:107]
	v_mfma_f32_16x16x32_bf16 v[88:91], v[162:165], v[206:209], v[88:91]
	v_mfma_f32_16x16x32_bf16 v[88:91], v[166:169], v[210:213], v[88:91]
	v_mfma_f32_16x16x32_bf16 v[72:75], v[162:165], v[214:217], v[72:75]
	v_mfma_f32_16x16x32_bf16 v[72:75], v[166:169], v[218:221], v[72:75]
	s_setprio 0
	s_setprio 1
	v_mfma_f32_16x16x32_bf16 v[116:119], v[170:173], v[190:193], v[116:119]
	v_mfma_f32_16x16x32_bf16 v[116:119], v[174:177], v[194:197], v[116:119]
	v_mfma_f32_16x16x32_bf16 v[100:103], v[170:173], v[198:201], v[100:103]
	v_mfma_f32_16x16x32_bf16 v[100:103], v[174:177], v[202:205], v[100:103]
	v_mfma_f32_16x16x32_bf16 v[84:87], v[170:173], v[206:209], v[84:87]
	v_mfma_f32_16x16x32_bf16 v[84:87], v[174:177], v[210:213], v[84:87]
	v_mfma_f32_16x16x32_bf16 v[68:71], v[170:173], v[214:217], v[68:71]
	v_mfma_f32_16x16x32_bf16 v[68:71], v[174:177], v[218:221], v[68:71]
	v_mfma_f32_16x16x32_bf16 v[112:115], v[182:185], v[190:193], v[112:115]
	v_mfma_f32_16x16x32_bf16 v[112:115], v[186:189], v[194:197], v[112:115]
	v_mfma_f32_16x16x32_bf16 v[96:99], v[182:185], v[198:201], v[96:99]
	v_mfma_f32_16x16x32_bf16 v[96:99], v[186:189], v[202:205], v[96:99]
	v_mfma_f32_16x16x32_bf16 v[80:83], v[182:185], v[206:209], v[80:83]
	v_mfma_f32_16x16x32_bf16 v[80:83], v[186:189], v[210:213], v[80:83]
	v_mfma_f32_16x16x32_bf16 v[64:67], v[182:185], v[214:217], v[64:67]
	v_mfma_f32_16x16x32_bf16 v[64:67], v[186:189], v[218:221], v[64:67]
	s_setprio 0
	s_barrier
	s_add_i32 s8, s63, s41
	v_lshl_add_u64 v[146:147], s[30:31], 0, v[132:133]
	s_mov_b32 m0, s8
	ds_read_b128 v[190:193], v152 offset:16384
	ds_read_b128 v[194:197], v152 offset:17408
	ds_read_b128 v[198:201], v152 offset:18432
	ds_read_b128 v[202:205], v152 offset:19456
	ds_read_b128 v[206:209], v152 offset:20480
	ds_read_b128 v[210:213], v152 offset:21504
	ds_read_b128 v[214:217], v152 offset:22528
	ds_read_b128 v[218:221], v152 offset:23552
	global_load_lds_dwordx4 v[146:147], off
	s_add_i32 m0, s8, 0x2000
	s_add_u32 s8, s30, 0x20000
	v_lshl_add_u64 v[178:179], s[30:31], 0, v[128:129]
	s_addc_u32 s9, s31, 0
	s_add_i32 s74, s64, s41
	global_load_lds_dwordx4 v[178:179], off
	v_lshl_add_u64 v[222:223], s[8:9], 0, v[132:133]
	s_mov_b32 m0, s74
	v_lshl_add_u64 v[224:225], s[38:39], 0, v[130:131]
	global_load_lds_dwordx4 v[222:223], off
	v_lshl_add_u64 v[222:223], s[8:9], 0, v[128:129]
	s_add_i32 m0, s74, 0x2000
	s_nop 0
	global_load_lds_dwordx4 v[222:223], off
	v_lshl_add_u64 v[222:223], s[38:39], 0, v[134:135]
	s_mov_b32 m0, s47
	s_nop 0
	global_load_lds_dwordx4 v[222:223], off
	s_mov_b32 m0, s50
	s_nop 0
	global_load_lds_dwordx4 v[224:225], off
	s_waitcnt vmcnt(8)
	s_waitcnt lgkmcnt(0)
	s_setprio 1
	s_barrier
; #define PG8_STAGE(bufoff, gbase, voff) do { _Pragma("unroll") for (int _i = 0; _i < 2; ++_i) \
;         __builtin_amdgcn_global_load_lds((const unsigned*)((const char*)(gbase) + (voff)[_i]), (LAS unsigned*)(lds + (bufoff) + ldsw + _i * 8192), 16, 0, 0); } while (0)
; #define PG8_LDA(dst, b, h) do { _Pragma("unroll") for (int m = 0; m < 4; ++m) _Pragma("unroll") for (int k = 0; k < 2; ++k) dst[m][k] = *(const LAS bf16x8*)(lds + PG8_SA(b, h) + aoff + m * 2048 + k * 1024); } while (0)
; #define PG8_LDB(dst, b, h) do { _Pragma("unroll") for (int n = 0; n < 2; ++n) _Pragma("unroll") for (int k = 0; k < 2; ++k) dst[n][k] = *(const LAS bf16x8*)(lds + PG8_SB(b, h) + boff + n * 2048 + k * 1024); } while (0)
; #define PG8_MMA(ai, bj, At, Bt) do { __builtin_amdgcn_s_setprio(1); _Pragma("unroll") for (int m = 0; m < 4; ++m) _Pragma("unroll") for (int n = 0; n < 2; ++n) _Pragma("unroll") for (int k = 0; k < 2; ++k) \
;         acc[ai][bj][m][n] = __builtin_amdgcn_mfma_f32_16x16x32_bf16(Bt[n][k], At[m][k], acc[ai][bj][m][n], 0, 0, 0); __builtin_amdgcn_s_setprio(0); } while (0)
; #define PG8_WAIT_V(n) asm volatile("s_waitcnt vmcnt(" #n ")" ::: "memory")
; #define PG8_WAIT_L(n) asm volatile("s_waitcnt lgkmcnt(" #n ")" ::: "memory")
; #define PG8_BAR __builtin_amdgcn_s_barrier()
; #define PG8_SCHED __builtin_amdgcn_sched_barrier(0)
; template <class Epi>
; DI void gemm_phase(LAS unsigned char* lds, const Gemm g, const StaticOrder& S, const Epi& E) {
;     ...
;             PG8_WAIT_V(8); PG8_WAIT_L(0); PG8_BAR; PG8_MMA(1, 0, At, B0); PG8_MMA(1, 1, At, B1); PG8_BAR; PG8_SCHED;
;             PG8_LDB(B0, 1, 0); PG8_LDB(B1, 1, 1); PG8_SCHED; PG8_LDA(At, 1, 0); PG8_STAGE(PG8_SA(0, 1), a2 + hstepA, voffA);
;             PG8_WAIT_V(8); PG8_WAIT_L(0); PG8_BAR; PG8_MMA(0, 0, At, B0); PG8_MMA(0, 1, At, B1); PG8_BAR; PG8_SCHED;
	v_mfma_f32_16x16x32_bf16 v[60:63], v[154:157], v[190:193], v[60:63]
	v_mfma_f32_16x16x32_bf16 v[60:63], v[158:161], v[194:197], v[60:63]
	v_mfma_f32_16x16x32_bf16 v[44:47], v[154:157], v[198:201], v[44:47]
	v_mfma_f32_16x16x32_bf16 v[44:47], v[158:161], v[202:205], v[44:47]
	v_mfma_f32_16x16x32_bf16 v[28:31], v[154:157], v[206:209], v[28:31]
	v_mfma_f32_16x16x32_bf16 v[28:31], v[158:161], v[210:213], v[28:31]
	v_mfma_f32_16x16x32_bf16 v[12:15], v[154:157], v[214:217], v[12:15]
	v_mfma_f32_16x16x32_bf16 v[12:15], v[158:161], v[218:221], v[12:15]
	v_mfma_f32_16x16x32_bf16 v[56:59], v[162:165], v[190:193], v[56:59]
	v_mfma_f32_16x16x32_bf16 v[56:59], v[166:169], v[194:197], v[56:59]
	v_mfma_f32_16x16x32_bf16 v[40:43], v[162:165], v[198:201], v[40:43]
	v_mfma_f32_16x16x32_bf16 v[40:43], v[166:169], v[202:205], v[40:43]
	v_mfma_f32_16x16x32_bf16 v[24:27], v[162:165], v[206:209], v[24:27]
	v_mfma_f32_16x16x32_bf16 v[24:27], v[166:169], v[210:213], v[24:27]
	v_mfma_f32_16x16x32_bf16 v[8:11], v[162:165], v[214:217], v[8:11]
	v_mfma_f32_16x16x32_bf16 v[8:11], v[166:169], v[218:221], v[8:11]
	s_setprio 0
	s_setprio 1
	v_mfma_f32_16x16x32_bf16 v[52:55], v[170:173], v[190:193], v[52:55]
	v_mfma_f32_16x16x32_bf16 v[52:55], v[174:177], v[194:197], v[52:55]
	v_mfma_f32_16x16x32_bf16 v[36:39], v[170:173], v[198:201], v[36:39]
	v_mfma_f32_16x16x32_bf16 v[36:39], v[174:177], v[202:205], v[36:39]
	v_mfma_f32_16x16x32_bf16 v[20:23], v[170:173], v[206:209], v[20:23]
	v_mfma_f32_16x16x32_bf16 v[20:23], v[174:177], v[210:213], v[20:23]
	v_mfma_f32_16x16x32_bf16 v[4:7], v[170:173], v[214:217], v[4:7]
	v_mfma_f32_16x16x32_bf16 v[4:7], v[174:177], v[218:221], v[4:7]
	v_mfma_f32_16x16x32_bf16 v[48:51], v[182:185], v[190:193], v[48:51]
	v_mfma_f32_16x16x32_bf16 v[48:51], v[186:189], v[194:197], v[48:51]
	v_mfma_f32_16x16x32_bf16 v[32:35], v[182:185], v[198:201], v[32:35]
	v_mfma_f32_16x16x32_bf16 v[32:35], v[186:189], v[202:205], v[32:35]
	v_mfma_f32_16x16x32_bf16 v[16:19], v[182:185], v[206:209], v[16:19]
	v_mfma_f32_16x16x32_bf16 v[16:19], v[186:189], v[210:213], v[16:19]
	v_mfma_f32_16x16x32_bf16 v[0:3], v[182:185], v[214:217], v[0:3]
	v_mfma_f32_16x16x32_bf16 v[0:3], v[186:189], v[218:221], v[0:3]
	s_setprio 0
	s_barrier
	s_add_i32 s74, 0, 0x18000
	s_add_i32 s75, 0, 0x1c000
	v_add_u32_e32 v166, s74, v149
	v_add_u32_e32 v181, s75, v149
	ds_read_b128 v[154:157], v166
	ds_read_b128 v[158:161], v166 offset:1024
	ds_read_b128 v[162:165], v166 offset:2048
	ds_read_b128 v[166:169], v166 offset:3072
	ds_read_b128 v[170:173], v181
	ds_read_b128 v[174:177], v181 offset:1024
	ds_read_b128 v[182:185], v181 offset:2048
	ds_read_b128 v[186:189], v181 offset:3072
	s_add_u32 s8, s38, 0x110000
	s_addc_u32 s9, s39, 0
	s_mov_b32 m0, s51
	v_lshl_add_u64 v[226:227], s[8:9], 0, v[134:135]
	ds_read_b128 v[190:193], v152 offset:32768
	ds_read_b128 v[194:197], v152 offset:33792
	ds_read_b128 v[198:201], v152 offset:34816
	ds_read_b128 v[202:205], v152 offset:35840
	ds_read_b128 v[206:209], v152 offset:36864
	ds_read_b128 v[210:213], v152 offset:37888
	ds_read_b128 v[214:217], v152 offset:38912
	ds_read_b128 v[218:221], v152 offset:39936
	global_load_lds_dwordx4 v[226:227], off
	v_lshl_add_u64 v[226:227], s[8:9], 0, v[130:131]
	s_mov_b32 m0, s56
	s_nop 0
	global_load_lds_dwordx4 v[226:227], off
	s_waitcnt vmcnt(8)
	s_waitcnt lgkmcnt(0)
	s_setprio 1
	s_barrier
	v_mfma_f32_16x16x32_bf16 v[120:123], v[154:157], v[190:193], v[120:123]
	v_mfma_f32_16x16x32_bf16 v[120:123], v[158:161], v[194:197], v[120:123]
	v_mfma_f32_16x16x32_bf16 v[108:111], v[154:157], v[198:201], v[108:111]
	v_mfma_f32_16x16x32_bf16 v[108:111], v[158:161], v[202:205], v[108:111]
	v_mfma_f32_16x16x32_bf16 v[92:95], v[154:157], v[206:209], v[92:95]
	v_mfma_f32_16x16x32_bf16 v[92:95], v[158:161], v[210:213], v[92:95]
	v_mfma_f32_16x16x32_bf16 v[76:79], v[154:157], v[214:217], v[76:79]
	v_mfma_f32_16x16x32_bf16 v[76:79], v[158:161], v[218:221], v[76:79]
	v_mfma_f32_16x16x32_bf16 v[124:127], v[162:165], v[190:193], v[124:127]
	v_mfma_f32_16x16x32_bf16 v[124:127], v[166:169], v[194:197], v[124:127]
	v_mfma_f32_16x16x32_bf16 v[104:107], v[162:165], v[198:201], v[104:107]
	v_mfma_f32_16x16x32_bf16 v[104:107], v[166:169], v[202:205], v[104:107]
	v_mfma_f32_16x16x32_bf16 v[88:91], v[162:165], v[206:209], v[88:91]
	v_mfma_f32_16x16x32_bf16 v[88:91], v[166:169], v[210:213], v[88:91]
	v_mfma_f32_16x16x32_bf16 v[72:75], v[162:165], v[214:217], v[72:75]
	v_mfma_f32_16x16x32_bf16 v[72:75], v[166:169], v[218:221], v[72:75]
	s_setprio 0
	s_setprio 1
	v_mfma_f32_16x16x32_bf16 v[116:119], v[170:173], v[190:193], v[116:119]
	v_mfma_f32_16x16x32_bf16 v[116:119], v[174:177], v[194:197], v[116:119]
	v_mfma_f32_16x16x32_bf16 v[100:103], v[170:173], v[198:201], v[100:103]
	v_mfma_f32_16x16x32_bf16 v[100:103], v[174:177], v[202:205], v[100:103]
	v_mfma_f32_16x16x32_bf16 v[84:87], v[170:173], v[206:209], v[84:87]
	v_mfma_f32_16x16x32_bf16 v[84:87], v[174:177], v[210:213], v[84:87]
	v_mfma_f32_16x16x32_bf16 v[68:71], v[170:173], v[214:217], v[68:71]
	v_mfma_f32_16x16x32_bf16 v[68:71], v[174:177], v[218:221], v[68:71]
	v_mfma_f32_16x16x32_bf16 v[112:115], v[182:185], v[190:193], v[112:115]
	v_mfma_f32_16x16x32_bf16 v[112:115], v[186:189], v[194:197], v[112:115]
	v_mfma_f32_16x16x32_bf16 v[96:99], v[182:185], v[198:201], v[96:99]
	v_mfma_f32_16x16x32_bf16 v[96:99], v[186:189], v[202:205], v[96:99]
	v_mfma_f32_16x16x32_bf16 v[80:83], v[182:185], v[206:209], v[80:83]
	v_mfma_f32_16x16x32_bf16 v[80:83], v[186:189], v[210:213], v[80:83]
	v_mfma_f32_16x16x32_bf16 v[64:67], v[182:185], v[214:217], v[64:67]
	v_mfma_f32_16x16x32_bf16 v[64:67], v[186:189], v[218:221], v[64:67]
	s_setprio 0
	s_barrier
; #define PG8_STAGE(bufoff, gbase, voff) do { _Pragma("unroll") for (int _i = 0; _i < 2; ++_i) \
;         __builtin_amdgcn_global_load_lds((const unsigned*)((const char*)(gbase) + (voff)[_i]), (LAS unsigned*)(lds + (bufoff) + ldsw + _i * 8192), 16, 0, 0); } while (0)
; #define PG8_LDA(dst, b, h) do { _Pragma("unroll") for (int m = 0; m < 4; ++m) _Pragma("unroll") for (int k = 0; k < 2; ++k) dst[m][k] = *(const LAS bf16x8*)(lds + PG8_SA(b, h) + aoff + m * 2048 + k * 1024); } while (0)
; #define PG8_MMA(ai, bj, At, Bt) do { __builtin_amdgcn_s_setprio(1); _Pragma("unroll") for (int m = 0; m < 4; ++m) _Pragma("unroll") for (int n = 0; n < 2; ++n) _Pragma("unroll") for (int k = 0; k < 2; ++k) \
;         acc[ai][bj][m][n] = __builtin_amdgcn_mfma_f32_16x16x32_bf16(Bt[n][k], At[m][k], acc[ai][bj][m][n], 0, 0, 0); __builtin_amdgcn_s_setprio(0); } while (0)
; #define PG8_WAIT_V(n) asm volatile("s_waitcnt vmcnt(" #n ")" ::: "memory")
; #define PG8_WAIT_L(n) asm volatile("s_waitcnt lgkmcnt(" #n ")" ::: "memory")
; #define PG8_BAR __builtin_amdgcn_s_barrier()
; #define PG8_SCHED __builtin_amdgcn_sched_barrier(0)
; template <class Epi>
; DI void gemm_phase(LAS unsigned char* lds, const Gemm g, const StaticOrder& S, const Epi& E) {
;     ...
;             PG8_LDA(At, 1, 1); PG8_STAGE(PG8_SB(1, 0), b3, voffB); PG8_STAGE(PG8_SB(1, 1), b3 + hstepB, voffB); PG8_STAGE(PG8_SA(1, 0), a3, voffA);
;             PG8_WAIT_V(8); PG8_WAIT_L(0); PG8_BAR; PG8_MMA(1, 0, At, B0); PG8_MMA(1, 1, At, B1); PG8_BAR; PG8_SCHED;
;         }
	s_add_i32 s8, s74, s41
	v_lshl_add_u64 v[146:147], v[146:147], 0, s[16:17]
	s_mov_b32 m0, s8
	ds_read_b128 v[190:193], v152 offset:49152
	ds_read_b128 v[194:197], v152 offset:50176
	ds_read_b128 v[198:201], v152 offset:51200
	ds_read_b128 v[202:205], v152 offset:52224
	ds_read_b128 v[206:209], v152 offset:53248
	ds_read_b128 v[210:213], v152 offset:54272
	ds_read_b128 v[214:217], v152 offset:55296
	ds_read_b128 v[218:221], v152 offset:56320
	global_load_lds_dwordx4 v[146:147], off
	s_add_i32 m0, s8, 0x2000
	s_add_u32 s8, s30, 0x20080
	v_lshl_add_u64 v[146:147], v[178:179], 0, s[16:17]
	s_addc_u32 s9, s31, 0
	s_add_i32 s30, s75, s41
	global_load_lds_dwordx4 v[146:147], off
	v_lshl_add_u64 v[146:147], s[8:9], 0, v[132:133]
	s_mov_b32 m0, s30
	s_nop 0
	global_load_lds_dwordx4 v[146:147], off
	v_lshl_add_u64 v[146:147], s[8:9], 0, v[128:129]
	s_add_i32 m0, s30, 0x2000
	s_nop 0
	global_load_lds_dwordx4 v[146:147], off
	v_lshl_add_u64 v[146:147], v[222:223], 0, s[16:17]
	s_mov_b32 m0, s60
	s_nop 0
	global_load_lds_dwordx4 v[146:147], off
	v_lshl_add_u64 v[146:147], v[224:225], 0, s[16:17]
	s_mov_b32 m0, s61
	s_nop 0
	global_load_lds_dwordx4 v[146:147], off
	s_waitcnt vmcnt(8)
	s_waitcnt lgkmcnt(0)
	s_setprio 1
	s_barrier
	v_mfma_f32_16x16x32_bf16 v[60:63], v[154:157], v[190:193], v[60:63]
	v_mfma_f32_16x16x32_bf16 v[60:63], v[158:161], v[194:197], v[60:63]
	v_mfma_f32_16x16x32_bf16 v[44:47], v[154:157], v[198:201], v[44:47]
	v_mfma_f32_16x16x32_bf16 v[44:47], v[158:161], v[202:205], v[44:47]
	v_mfma_f32_16x16x32_bf16 v[28:31], v[154:157], v[206:209], v[28:31]
	v_mfma_f32_16x16x32_bf16 v[28:31], v[158:161], v[210:213], v[28:31]
	v_mfma_f32_16x16x32_bf16 v[12:15], v[154:157], v[214:217], v[12:15]
	v_mfma_f32_16x16x32_bf16 v[12:15], v[158:161], v[218:221], v[12:15]
	v_mfma_f32_16x16x32_bf16 v[56:59], v[162:165], v[190:193], v[56:59]
	v_mfma_f32_16x16x32_bf16 v[56:59], v[166:169], v[194:197], v[56:59]
	v_mfma_f32_16x16x32_bf16 v[40:43], v[162:165], v[198:201], v[40:43]
	v_mfma_f32_16x16x32_bf16 v[40:43], v[166:169], v[202:205], v[40:43]
	v_mfma_f32_16x16x32_bf16 v[24:27], v[162:165], v[206:209], v[24:27]
	v_mfma_f32_16x16x32_bf16 v[24:27], v[166:169], v[210:213], v[24:27]
	v_mfma_f32_16x16x32_bf16 v[8:11], v[162:165], v[214:217], v[8:11]
	v_mfma_f32_16x16x32_bf16 v[8:11], v[166:169], v[218:221], v[8:11]
	s_setprio 0
	s_setprio 1
	v_mfma_f32_16x16x32_bf16 v[52:55], v[170:173], v[190:193], v[52:55]
	v_mfma_f32_16x16x32_bf16 v[52:55], v[174:177], v[194:197], v[52:55]
	v_mfma_f32_16x16x32_bf16 v[36:39], v[170:173], v[198:201], v[36:39]
	v_mfma_f32_16x16x32_bf16 v[36:39], v[174:177], v[202:205], v[36:39]
	v_mfma_f32_16x16x32_bf16 v[20:23], v[170:173], v[206:209], v[20:23]
	v_mfma_f32_16x16x32_bf16 v[20:23], v[174:177], v[210:213], v[20:23]
	v_mfma_f32_16x16x32_bf16 v[4:7], v[170:173], v[214:217], v[4:7]
	v_mfma_f32_16x16x32_bf16 v[4:7], v[174:177], v[218:221], v[4:7]
	v_mfma_f32_16x16x32_bf16 v[48:51], v[182:185], v[190:193], v[48:51]
	v_mfma_f32_16x16x32_bf16 v[48:51], v[186:189], v[194:197], v[48:51]
	v_mfma_f32_16x16x32_bf16 v[32:35], v[182:185], v[198:201], v[32:35]
	v_mfma_f32_16x16x32_bf16 v[32:35], v[186:189], v[202:205], v[32:35]
	v_mfma_f32_16x16x32_bf16 v[16:19], v[182:185], v[206:209], v[16:19]
	v_mfma_f32_16x16x32_bf16 v[16:19], v[186:189], v[210:213], v[16:19]
	v_mfma_f32_16x16x32_bf16 v[0:3], v[182:185], v[214:217], v[0:3]
	v_mfma_f32_16x16x32_bf16 v[0:3], v[186:189], v[218:221], v[0:3]
	s_setprio 0
	s_barrier
	s_add_u32 s71, s71, 0x100
	s_addc_u32 s72, s72, 0
	s_cmp_ge_i32 s73, s59
	s_mov_b64 s[8:9], s[6:7]
	s_mov_b32 s30, s73
	s_cbranch_scc0 .LBB0_329

; #define PG8_STAGE(bufoff, gbase, voff) do { _Pragma("unroll") for (int _i = 0; _i < 2; ++_i) \
;         __builtin_amdgcn_global_load_lds((const unsigned*)((const char*)(gbase) + (voff)[_i]), (LAS unsigned*)(lds + (bufoff) + ldsw + _i * 8192), 16, 0, 0); } while (0)
; #define PG8_LDA(dst, b, h) do { _Pragma("unroll") for (int m = 0; m < 4; ++m) _Pragma("unroll") for (int k = 0; k < 2; ++k) dst[m][k] = *(const LAS bf16x8*)(lds + PG8_SA(b, h) + aoff + m * 2048 + k * 1024); } while (0)
; #define PG8_LDB(dst, b, h) do { _Pragma("unroll") for (int n = 0; n < 2; ++n) _Pragma("unroll") for (int k = 0; k < 2; ++k) dst[n][k] = *(const LAS bf16x8*)(lds + PG8_SB(b, h) + boff + n * 2048 + k * 1024); } while (0)
; #define PG8_MMA(ai, bj, At, Bt) do { __builtin_amdgcn_s_setprio(1); _Pragma("unroll") for (int m = 0; m < 4; ++m) _Pragma("unroll") for (int n = 0; n < 2; ++n) _Pragma("unroll") for (int k = 0; k < 2; ++k) \
;         acc[ai][bj][m][n] = __builtin_amdgcn_mfma_f32_16x16x32_bf16(Bt[n][k], At[m][k], acc[ai][bj][m][n], 0, 0, 0); __builtin_amdgcn_s_setprio(0); } while (0)
; #define PG8_WAIT_V(n) asm volatile("s_waitcnt vmcnt(" #n ")" ::: "memory")
; #define PG8_WAIT_L(n) asm volatile("s_waitcnt lgkmcnt(" #n ")" ::: "memory")
; #define PG8_BAR __builtin_amdgcn_s_barrier()
; #define PG8_SCHED __builtin_amdgcn_sched_barrier(0)
; template <class Epi>
; DI void gemm_phase(LAS unsigned char* lds, const Gemm g, const StaticOrder& S, const Epi& E) {
;     ...
;             const bool last = (t == nt - 2);
;             const char* a1 = cA + (size_t)(t + 1) * kstep;
;             const char* a2 = last ? nA : cA + (size_t)(t + 2) * kstep; const char* b2 = last ? nB : cB + (size_t)(t + 2) * kstep;
;             const char* a3 = a2 + kstep; const char* b3 = b2 + kstep;
;             PG8_LDB(B0, 0, 0); PG8_LDB(B1, 0, 1); PG8_SCHED; PG8_LDA(At, 0, 0); PG8_STAGE(PG8_SA(1, 1), a1 + hstepA, voffA);
;             PG8_WAIT_V(8); PG8_WAIT_L(0); PG8_BAR; PG8_MMA(0, 0, At, B0); PG8_MMA(0, 1, At, B1); PG8_BAR; PG8_SCHED;
;             PG8_LDA(At, 0, 1); PG8_STAGE(PG8_SB(0, 0), b2, voffB); PG8_STAGE(PG8_SB(0, 1), b2 + hstepB, voffB); PG8_STAGE(PG8_SA(0, 0), a2, voffA);
;             PG8_WAIT_V(8); PG8_WAIT_L(0); PG8_BAR; PG8_MMA(1, 0, At, B0); PG8_MMA(1, 1, At, B1); PG8_BAR; PG8_SCHED;
.LBB0_352:
	ds_read_b128 v[146:149], v167
	ds_read_b128 v[150:153], v167 offset:1024
	ds_read_b128 v[154:157], v167 offset:2048
	ds_read_b128 v[158:161], v167 offset:3072
	ds_read_b128 v[172:175], v168
	ds_read_b128 v[176:179], v168 offset:1024
	ds_read_b128 v[182:185], v168 offset:2048
	ds_read_b128 v[186:189], v168 offset:3072
	s_add_i32 s16, s8, 2
	s_add_u32 s9, s6, 0xfffe0080
	s_addc_u32 s10, s7, -1
	s_cmp_eq_u32 s76, s8
	s_cselect_b32 s8, s60, s14
	s_cselect_b32 s11, s12, s10
	s_cselect_b32 s10, s13, s9
	s_cselect_b32 s9, s61, s15
	v_lshl_add_u64 v[162:163], s[6:7], 0, v[138:139]
	s_add_i32 m0, s65, 0xc000
	ds_read_b128 v[190:193], v169
	ds_read_b128 v[194:197], v169 offset:1024
	ds_read_b128 v[198:201], v169 offset:2048
	ds_read_b128 v[202:205], v169 offset:3072
	ds_read_b128 v[206:209], v169 offset:4096
	ds_read_b128 v[210:213], v169 offset:5120
	ds_read_b128 v[214:217], v169 offset:6144
	ds_read_b128 v[218:221], v169 offset:7168
	global_load_lds_dwordx4 v[162:163], off
	v_lshl_add_u64 v[162:163], s[6:7], 0, v[140:141]
	s_add_i32 m0, s65, 0xe000
	s_nop 0
	global_load_lds_dwordx4 v[162:163], off
	s_waitcnt vmcnt(8)
	s_waitcnt lgkmcnt(0)
	s_setprio 1
	s_barrier
	v_mfma_f32_16x16x32_bf16 v[124:127], v[146:149], v[190:193], v[124:127]
	v_mfma_f32_16x16x32_bf16 v[124:127], v[150:153], v[194:197], v[124:127]
	v_mfma_f32_16x16x32_bf16 v[108:111], v[146:149], v[198:201], v[108:111]
	v_mfma_f32_16x16x32_bf16 v[108:111], v[150:153], v[202:205], v[108:111]
	v_mfma_f32_16x16x32_bf16 v[92:95], v[146:149], v[206:209], v[92:95]
	v_mfma_f32_16x16x32_bf16 v[92:95], v[150:153], v[210:213], v[92:95]
	v_mfma_f32_16x16x32_bf16 v[76:79], v[146:149], v[214:217], v[76:79]
	v_mfma_f32_16x16x32_bf16 v[76:79], v[150:153], v[218:221], v[76:79]
	v_mfma_f32_16x16x32_bf16 v[120:123], v[154:157], v[190:193], v[120:123]
	v_mfma_f32_16x16x32_bf16 v[120:123], v[158:161], v[194:197], v[120:123]
	v_mfma_f32_16x16x32_bf16 v[104:107], v[154:157], v[198:201], v[104:107]
	v_mfma_f32_16x16x32_bf16 v[104:107], v[158:161], v[202:205], v[104:107]
	v_mfma_f32_16x16x32_bf16 v[88:91], v[154:157], v[206:209], v[88:91]
	v_mfma_f32_16x16x32_bf16 v[88:91], v[158:161], v[210:213], v[88:91]
	v_mfma_f32_16x16x32_bf16 v[72:75], v[154:157], v[214:217], v[72:75]
	v_mfma_f32_16x16x32_bf16 v[72:75], v[158:161], v[218:221], v[72:75]
	s_setprio 0
	s_setprio 1
	v_mfma_f32_16x16x32_bf16 v[116:119], v[172:175], v[190:193], v[116:119]
	v_mfma_f32_16x16x32_bf16 v[116:119], v[176:179], v[194:197], v[116:119]
	v_mfma_f32_16x16x32_bf16 v[100:103], v[172:175], v[198:201], v[100:103]
	v_mfma_f32_16x16x32_bf16 v[100:103], v[176:179], v[202:205], v[100:103]
	v_mfma_f32_16x16x32_bf16 v[84:87], v[172:175], v[206:209], v[84:87]
	v_mfma_f32_16x16x32_bf16 v[84:87], v[176:179], v[210:213], v[84:87]
	v_mfma_f32_16x16x32_bf16 v[68:71], v[172:175], v[214:217], v[68:71]
	v_mfma_f32_16x16x32_bf16 v[68:71], v[176:179], v[218:221], v[68:71]
	v_mfma_f32_16x16x32_bf16 v[112:115], v[182:185], v[190:193], v[112:115]
	v_mfma_f32_16x16x32_bf16 v[112:115], v[186:189], v[194:197], v[112:115]
	v_mfma_f32_16x16x32_bf16 v[96:99], v[182:185], v[198:201], v[96:99]
	v_mfma_f32_16x16x32_bf16 v[96:99], v[186:189], v[202:205], v[96:99]
	v_mfma_f32_16x16x32_bf16 v[80:83], v[182:185], v[206:209], v[80:83]
	v_mfma_f32_16x16x32_bf16 v[80:83], v[186:189], v[210:213], v[80:83]
	v_mfma_f32_16x16x32_bf16 v[64:67], v[182:185], v[214:217], v[64:67]
	v_mfma_f32_16x16x32_bf16 v[64:67], v[186:189], v[218:221], v[64:67]
	s_setprio 0
	s_barrier
	s_add_i32 s17, s77, s66
	v_lshl_add_u64 v[162:163], s[8:9], 0, v[132:133]
	s_mov_b32 m0, s17
	ds_read_b128 v[190:193], v169 offset:16384
	ds_read_b128 v[194:197], v169 offset:17408
	ds_read_b128 v[198:201], v169 offset:18432
	ds_read_b128 v[202:205], v169 offset:19456
	ds_read_b128 v[206:209], v169 offset:20480
	ds_read_b128 v[210:213], v169 offset:21504
	ds_read_b128 v[214:217], v169 offset:22528
	ds_read_b128 v[218:221], v169 offset:23552
	global_load_lds_dwordx4 v[162:163], off
	s_add_i32 m0, s17, 0x2000
	s_add_u32 s18, s8, 0x110000
	v_lshl_add_u64 v[222:223], s[8:9], 0, v[128:129]
	s_addc_u32 s19, s9, 0
	s_add_i32 s17, s78, s66
	global_load_lds_dwordx4 v[222:223], off
	v_lshl_add_u64 v[224:225], s[18:19], 0, v[132:133]
	s_mov_b32 m0, s17
	v_lshl_add_u64 v[226:227], s[10:11], 0, v[130:131]
	global_load_lds_dwordx4 v[224:225], off
	v_lshl_add_u64 v[224:225], s[18:19], 0, v[128:129]
	s_add_i32 m0, s17, 0x2000
	s_nop 0
	global_load_lds_dwordx4 v[224:225], off
	v_lshl_add_u64 v[224:225], s[10:11], 0, v[134:135]
	s_mov_b32 m0, s65
	s_nop 0
	global_load_lds_dwordx4 v[224:225], off
	s_mov_b32 m0, s69
	s_nop 0
	global_load_lds_dwordx4 v[226:227], off
	s_waitcnt vmcnt(8)
	s_waitcnt lgkmcnt(0)
	s_setprio 1
	s_barrier
; #define PG8_STAGE(bufoff, gbase, voff) do { _Pragma("unroll") for (int _i = 0; _i < 2; ++_i) \
;         __builtin_amdgcn_global_load_lds((const unsigned*)((const char*)(gbase) + (voff)[_i]), (LAS unsigned*)(lds + (bufoff) + ldsw + _i * 8192), 16, 0, 0); } while (0)
; #define PG8_LDA(dst, b, h) do { _Pragma("unroll") for (int m = 0; m < 4; ++m) _Pragma("unroll") for (int k = 0; k < 2; ++k) dst[m][k] = *(const LAS bf16x8*)(lds + PG8_SA(b, h) + aoff + m * 2048 + k * 1024); } while (0)
; #define PG8_LDB(dst, b, h) do { _Pragma("unroll") for (int n = 0; n < 2; ++n) _Pragma("unroll") for (int k = 0; k < 2; ++k) dst[n][k] = *(const LAS bf16x8*)(lds + PG8_SB(b, h) + boff + n * 2048 + k * 1024); } while (0)
; #define PG8_MMA(ai, bj, At, Bt) do { __builtin_amdgcn_s_setprio(1); _Pragma("unroll") for (int m = 0; m < 4; ++m) _Pragma("unroll") for (int n = 0; n < 2; ++n) _Pragma("unroll") for (int k = 0; k < 2; ++k) \
;         acc[ai][bj][m][n] = __builtin_amdgcn_mfma_f32_16x16x32_bf16(Bt[n][k], At[m][k], acc[ai][bj][m][n], 0, 0, 0); __builtin_amdgcn_s_setprio(0); } while (0)
; #define PG8_WAIT_V(n) asm volatile("s_waitcnt vmcnt(" #n ")" ::: "memory")
; #define PG8_WAIT_L(n) asm volatile("s_waitcnt lgkmcnt(" #n ")" ::: "memory")
; #define PG8_BAR __builtin_amdgcn_s_barrier()
; #define PG8_SCHED __builtin_amdgcn_sched_barrier(0)
; template <class Epi>
; DI void gemm_phase(LAS unsigned char* lds, const Gemm g, const StaticOrder& S, const Epi& E) {
;     ...
;             PG8_WAIT_V(8); PG8_WAIT_L(0); PG8_BAR; PG8_MMA(1, 0, At, B0); PG8_MMA(1, 1, At, B1); PG8_BAR; PG8_SCHED;
;             PG8_LDB(B0, 1, 0); PG8_LDB(B1, 1, 1); PG8_SCHED; PG8_LDA(At, 1, 0); PG8_STAGE(PG8_SA(0, 1), a2 + hstepA, voffA);
;             PG8_WAIT_V(8); PG8_WAIT_L(0); PG8_BAR; PG8_MMA(0, 0, At, B0); PG8_MMA(0, 1, At, B1); PG8_BAR; PG8_SCHED;
	v_mfma_f32_16x16x32_bf16 v[60:63], v[146:149], v[190:193], v[60:63]
	v_mfma_f32_16x16x32_bf16 v[60:63], v[150:153], v[194:197], v[60:63]
	v_mfma_f32_16x16x32_bf16 v[44:47], v[146:149], v[198:201], v[44:47]
	v_mfma_f32_16x16x32_bf16 v[44:47], v[150:153], v[202:205], v[44:47]
	v_mfma_f32_16x16x32_bf16 v[28:31], v[146:149], v[206:209], v[28:31]
	v_mfma_f32_16x16x32_bf16 v[28:31], v[150:153], v[210:213], v[28:31]
	v_mfma_f32_16x16x32_bf16 v[12:15], v[146:149], v[214:217], v[12:15]
	v_mfma_f32_16x16x32_bf16 v[12:15], v[150:153], v[218:221], v[12:15]
	v_mfma_f32_16x16x32_bf16 v[56:59], v[154:157], v[190:193], v[56:59]
	v_mfma_f32_16x16x32_bf16 v[56:59], v[158:161], v[194:197], v[56:59]
	v_mfma_f32_16x16x32_bf16 v[40:43], v[154:157], v[198:201], v[40:43]
	v_mfma_f32_16x16x32_bf16 v[40:43], v[158:161], v[202:205], v[40:43]
	v_mfma_f32_16x16x32_bf16 v[24:27], v[154:157], v[206:209], v[24:27]
	v_mfma_f32_16x16x32_bf16 v[24:27], v[158:161], v[210:213], v[24:27]
	v_mfma_f32_16x16x32_bf16 v[8:11], v[154:157], v[214:217], v[8:11]
	v_mfma_f32_16x16x32_bf16 v[8:11], v[158:161], v[218:221], v[8:11]
	s_setprio 0
	s_setprio 1
	v_mfma_f32_16x16x32_bf16 v[52:55], v[172:175], v[190:193], v[52:55]
	v_mfma_f32_16x16x32_bf16 v[52:55], v[176:179], v[194:197], v[52:55]
	v_mfma_f32_16x16x32_bf16 v[36:39], v[172:175], v[198:201], v[36:39]
	v_mfma_f32_16x16x32_bf16 v[36:39], v[176:179], v[202:205], v[36:39]
	v_mfma_f32_16x16x32_bf16 v[20:23], v[172:175], v[206:209], v[20:23]
	v_mfma_f32_16x16x32_bf16 v[20:23], v[176:179], v[210:213], v[20:23]
	v_mfma_f32_16x16x32_bf16 v[4:7], v[172:175], v[214:217], v[4:7]
	v_mfma_f32_16x16x32_bf16 v[4:7], v[176:179], v[218:221], v[4:7]
	v_mfma_f32_16x16x32_bf16 v[48:51], v[182:185], v[190:193], v[48:51]
	v_mfma_f32_16x16x32_bf16 v[48:51], v[186:189], v[194:197], v[48:51]
	v_mfma_f32_16x16x32_bf16 v[32:35], v[182:185], v[198:201], v[32:35]
	v_mfma_f32_16x16x32_bf16 v[32:35], v[186:189], v[202:205], v[32:35]
	v_mfma_f32_16x16x32_bf16 v[16:19], v[182:185], v[206:209], v[16:19]
	v_mfma_f32_16x16x32_bf16 v[16:19], v[186:189], v[210:213], v[16:19]
	v_mfma_f32_16x16x32_bf16 v[0:3], v[182:185], v[214:217], v[0:3]
	v_mfma_f32_16x16x32_bf16 v[0:3], v[186:189], v[218:221], v[0:3]
	s_setprio 0
	s_barrier
	s_add_i32 s17, 0, 0x18000
	v_add_u32_e32 v136, s17, v165
	s_add_i32 s18, 0, 0x1c000
	ds_read_b128 v[146:149], v136
	ds_read_b128 v[150:153], v136 offset:1024
	ds_read_b128 v[154:157], v136 offset:2048
	ds_read_b128 v[158:161], v136 offset:3072
	v_add_u32_e32 v136, s18, v165
	ds_read_b128 v[172:175], v136
	ds_read_b128 v[176:179], v136 offset:1024
	ds_read_b128 v[182:185], v136 offset:2048
	ds_read_b128 v[186:189], v136 offset:3072
	s_add_u32 s10, s10, 0x20000
	s_addc_u32 s11, s11, 0
	s_mov_b32 m0, s70
	v_lshl_add_u64 v[228:229], s[10:11], 0, v[134:135]
	ds_read_b128 v[190:193], v169 offset:32768
	ds_read_b128 v[194:197], v169 offset:33792
	ds_read_b128 v[198:201], v169 offset:34816
	ds_read_b128 v[202:205], v169 offset:35840
	ds_read_b128 v[206:209], v169 offset:36864
	ds_read_b128 v[210:213], v169 offset:37888
	ds_read_b128 v[214:217], v169 offset:38912
	ds_read_b128 v[218:221], v169 offset:39936
	global_load_lds_dwordx4 v[228:229], off
	v_lshl_add_u64 v[228:229], s[10:11], 0, v[130:131]
	s_mov_b32 m0, s71
	s_nop 0
	global_load_lds_dwordx4 v[228:229], off
	s_waitcnt vmcnt(8)
	s_waitcnt lgkmcnt(0)
	s_setprio 1
	s_barrier
	v_mfma_f32_16x16x32_bf16 v[124:127], v[146:149], v[190:193], v[124:127]
	v_mfma_f32_16x16x32_bf16 v[124:127], v[150:153], v[194:197], v[124:127]
	v_mfma_f32_16x16x32_bf16 v[108:111], v[146:149], v[198:201], v[108:111]
	v_mfma_f32_16x16x32_bf16 v[108:111], v[150:153], v[202:205], v[108:111]
	v_mfma_f32_16x16x32_bf16 v[92:95], v[146:149], v[206:209], v[92:95]
	v_mfma_f32_16x16x32_bf16 v[92:95], v[150:153], v[210:213], v[92:95]
	v_mfma_f32_16x16x32_bf16 v[76:79], v[146:149], v[214:217], v[76:79]
	v_mfma_f32_16x16x32_bf16 v[76:79], v[150:153], v[218:221], v[76:79]
	v_mfma_f32_16x16x32_bf16 v[120:123], v[154:157], v[190:193], v[120:123]
	v_mfma_f32_16x16x32_bf16 v[120:123], v[158:161], v[194:197], v[120:123]
	v_mfma_f32_16x16x32_bf16 v[104:107], v[154:157], v[198:201], v[104:107]
	v_mfma_f32_16x16x32_bf16 v[104:107], v[158:161], v[202:205], v[104:107]
	v_mfma_f32_16x16x32_bf16 v[88:91], v[154:157], v[206:209], v[88:91]
	v_mfma_f32_16x16x32_bf16 v[88:91], v[158:161], v[210:213], v[88:91]
	v_mfma_f32_16x16x32_bf16 v[72:75], v[154:157], v[214:217], v[72:75]
	v_mfma_f32_16x16x32_bf16 v[72:75], v[158:161], v[218:221], v[72:75]
	s_setprio 0
	s_setprio 1
	v_mfma_f32_16x16x32_bf16 v[116:119], v[172:175], v[190:193], v[116:119]
	v_mfma_f32_16x16x32_bf16 v[116:119], v[176:179], v[194:197], v[116:119]
	v_mfma_f32_16x16x32_bf16 v[100:103], v[172:175], v[198:201], v[100:103]
	v_mfma_f32_16x16x32_bf16 v[100:103], v[176:179], v[202:205], v[100:103]
	v_mfma_f32_16x16x32_bf16 v[84:87], v[172:175], v[206:209], v[84:87]
	v_mfma_f32_16x16x32_bf16 v[84:87], v[176:179], v[210:213], v[84:87]
	v_mfma_f32_16x16x32_bf16 v[68:71], v[172:175], v[214:217], v[68:71]
	v_mfma_f32_16x16x32_bf16 v[68:71], v[176:179], v[218:221], v[68:71]
	v_mfma_f32_16x16x32_bf16 v[112:115], v[182:185], v[190:193], v[112:115]
	v_mfma_f32_16x16x32_bf16 v[112:115], v[186:189], v[194:197], v[112:115]
	v_mfma_f32_16x16x32_bf16 v[96:99], v[182:185], v[198:201], v[96:99]
	v_mfma_f32_16x16x32_bf16 v[96:99], v[186:189], v[202:205], v[96:99]
	v_mfma_f32_16x16x32_bf16 v[80:83], v[182:185], v[206:209], v[80:83]
	v_mfma_f32_16x16x32_bf16 v[80:83], v[186:189], v[210:213], v[80:83]
	v_mfma_f32_16x16x32_bf16 v[64:67], v[182:185], v[214:217], v[64:67]
	v_mfma_f32_16x16x32_bf16 v[64:67], v[186:189], v[218:221], v[64:67]
	s_setprio 0
	s_barrier
; #define PG8_STAGE(bufoff, gbase, voff) do { _Pragma("unroll") for (int _i = 0; _i < 2; ++_i) \
;         __builtin_amdgcn_global_load_lds((const unsigned*)((const char*)(gbase) + (voff)[_i]), (LAS unsigned*)(lds + (bufoff) + ldsw + _i * 8192), 16, 0, 0); } while (0)
; #define PG8_LDA(dst, b, h) do { _Pragma("unroll") for (int m = 0; m < 4; ++m) _Pragma("unroll") for (int k = 0; k < 2; ++k) dst[m][k] = *(const LAS bf16x8*)(lds + PG8_SA(b, h) + aoff + m * 2048 + k * 1024); } while (0)
; #define PG8_MMA(ai, bj, At, Bt) do { __builtin_amdgcn_s_setprio(1); _Pragma("unroll") for (int m = 0; m < 4; ++m) _Pragma("unroll") for (int n = 0; n < 2; ++n) _Pragma("unroll") for (int k = 0; k < 2; ++k) \
;         acc[ai][bj][m][n] = __builtin_amdgcn_mfma_f32_16x16x32_bf16(Bt[n][k], At[m][k], acc[ai][bj][m][n], 0, 0, 0); __builtin_amdgcn_s_setprio(0); } while (0)
; #define PG8_WAIT_V(n) asm volatile("s_waitcnt vmcnt(" #n ")" ::: "memory")
; #define PG8_WAIT_L(n) asm volatile("s_waitcnt lgkmcnt(" #n ")" ::: "memory")
; #define PG8_BAR __builtin_amdgcn_s_barrier()
; #define PG8_SCHED __builtin_amdgcn_sched_barrier(0)
; template <class Epi>
; DI void gemm_phase(LAS unsigned char* lds, const Gemm g, const StaticOrder& S, const Epi& E) {
;     ...
;             PG8_LDA(At, 1, 1); PG8_STAGE(PG8_SB(1, 0), b3, voffB); PG8_STAGE(PG8_SB(1, 1), b3 + hstepB, voffB); PG8_STAGE(PG8_SA(1, 0), a3, voffA);
;             PG8_WAIT_V(8); PG8_WAIT_L(0); PG8_BAR; PG8_MMA(1, 0, At, B0); PG8_MMA(1, 1, At, B1); PG8_BAR; PG8_SCHED;
;         }
	s_add_i32 s10, s17, s66
	v_lshl_add_u64 v[162:163], v[162:163], 0, s[42:43]
	s_mov_b32 m0, s10
	ds_read_b128 v[190:193], v169 offset:49152
	ds_read_b128 v[194:197], v169 offset:50176
	ds_read_b128 v[198:201], v169 offset:51200
	ds_read_b128 v[202:205], v169 offset:52224
	ds_read_b128 v[206:209], v169 offset:53248
	ds_read_b128 v[210:213], v169 offset:54272
	ds_read_b128 v[214:217], v169 offset:55296
	ds_read_b128 v[218:221], v169 offset:56320
	global_load_lds_dwordx4 v[162:163], off
	s_add_i32 m0, s10, 0x2000
	s_add_u32 s8, s8, 0x110080
	v_lshl_add_u64 v[162:163], v[222:223], 0, s[42:43]
	s_addc_u32 s9, s9, 0
	s_add_i32 s10, s18, s66
	global_load_lds_dwordx4 v[162:163], off
	v_lshl_add_u64 v[162:163], s[8:9], 0, v[132:133]
	s_mov_b32 m0, s10
	s_nop 0
	global_load_lds_dwordx4 v[162:163], off
	v_lshl_add_u64 v[162:163], s[8:9], 0, v[128:129]
	s_add_i32 m0, s10, 0x2000
	s_nop 0
	global_load_lds_dwordx4 v[162:163], off
	v_lshl_add_u64 v[162:163], v[224:225], 0, s[42:43]
	s_mov_b32 m0, s74
	s_nop 0
	global_load_lds_dwordx4 v[162:163], off
	v_lshl_add_u64 v[162:163], v[226:227], 0, s[42:43]
	s_mov_b32 m0, s75
	s_nop 0
	global_load_lds_dwordx4 v[162:163], off
	s_waitcnt vmcnt(8)
	s_waitcnt lgkmcnt(0)
	s_setprio 1
	s_barrier
	v_mfma_f32_16x16x32_bf16 v[60:63], v[146:149], v[190:193], v[60:63]
	v_mfma_f32_16x16x32_bf16 v[60:63], v[150:153], v[194:197], v[60:63]
	v_mfma_f32_16x16x32_bf16 v[44:47], v[146:149], v[198:201], v[44:47]
	v_mfma_f32_16x16x32_bf16 v[44:47], v[150:153], v[202:205], v[44:47]
	v_mfma_f32_16x16x32_bf16 v[28:31], v[146:149], v[206:209], v[28:31]
	v_mfma_f32_16x16x32_bf16 v[28:31], v[150:153], v[210:213], v[28:31]
	v_mfma_f32_16x16x32_bf16 v[12:15], v[146:149], v[214:217], v[12:15]
	v_mfma_f32_16x16x32_bf16 v[12:15], v[150:153], v[218:221], v[12:15]
	v_mfma_f32_16x16x32_bf16 v[56:59], v[154:157], v[190:193], v[56:59]
	v_mfma_f32_16x16x32_bf16 v[56:59], v[158:161], v[194:197], v[56:59]
	v_mfma_f32_16x16x32_bf16 v[40:43], v[154:157], v[198:201], v[40:43]
	v_mfma_f32_16x16x32_bf16 v[40:43], v[158:161], v[202:205], v[40:43]
	v_mfma_f32_16x16x32_bf16 v[24:27], v[154:157], v[206:209], v[24:27]
	v_mfma_f32_16x16x32_bf16 v[24:27], v[158:161], v[210:213], v[24:27]
	v_mfma_f32_16x16x32_bf16 v[8:11], v[154:157], v[214:217], v[8:11]
	v_mfma_f32_16x16x32_bf16 v[8:11], v[158:161], v[218:221], v[8:11]
	s_setprio 0
	s_setprio 1
	v_mfma_f32_16x16x32_bf16 v[52:55], v[172:175], v[190:193], v[52:55]
	v_mfma_f32_16x16x32_bf16 v[52:55], v[176:179], v[194:197], v[52:55]
	v_mfma_f32_16x16x32_bf16 v[36:39], v[172:175], v[198:201], v[36:39]
	v_mfma_f32_16x16x32_bf16 v[36:39], v[176:179], v[202:205], v[36:39]
	v_mfma_f32_16x16x32_bf16 v[20:23], v[172:175], v[206:209], v[20:23]
	v_mfma_f32_16x16x32_bf16 v[20:23], v[176:179], v[210:213], v[20:23]
	v_mfma_f32_16x16x32_bf16 v[4:7], v[172:175], v[214:217], v[4:7]
	v_mfma_f32_16x16x32_bf16 v[4:7], v[176:179], v[218:221], v[4:7]
	v_mfma_f32_16x16x32_bf16 v[48:51], v[182:185], v[190:193], v[48:51]
	v_mfma_f32_16x16x32_bf16 v[48:51], v[186:189], v[194:197], v[48:51]
	v_mfma_f32_16x16x32_bf16 v[32:35], v[182:185], v[198:201], v[32:35]
	v_mfma_f32_16x16x32_bf16 v[32:35], v[186:189], v[202:205], v[32:35]
	v_mfma_f32_16x16x32_bf16 v[16:19], v[182:185], v[206:209], v[16:19]
	v_mfma_f32_16x16x32_bf16 v[16:19], v[186:189], v[210:213], v[16:19]
	v_mfma_f32_16x16x32_bf16 v[0:3], v[182:185], v[214:217], v[0:3]
	v_mfma_f32_16x16x32_bf16 v[0:3], v[186:189], v[218:221], v[0:3]
	s_setprio 0
	s_barrier
	s_add_u32 s6, s6, 0x100
	s_addc_u32 s7, s7, 0
	s_add_u32 s14, s14, 0x100
	s_addc_u32 s15, s15, 0
	s_cmp_ge_i32 s16, s73
	s_mov_b32 s8, s16
	s_cbranch_scc0 .LBB0_352

; #define PG8_STAGE(bufoff, gbase, voff) do { _Pragma("unroll") for (int _i = 0; _i < 2; ++_i) \
;         __builtin_amdgcn_global_load_lds((const unsigned*)((const char*)(gbase) + (voff)[_i]), (LAS unsigned*)(lds + (bufoff) + ldsw + _i * 8192), 16, 0, 0); } while (0)
; #define PG8_LDA(dst, b, h) do { _Pragma("unroll") for (int m = 0; m < 4; ++m) _Pragma("unroll") for (int k = 0; k < 2; ++k) dst[m][k] = *(const LAS bf16x8*)(lds + PG8_SA(b, h) + aoff + m * 2048 + k * 1024); } while (0)
; #define PG8_LDB(dst, b, h) do { _Pragma("unroll") for (int n = 0; n < 2; ++n) _Pragma("unroll") for (int k = 0; k < 2; ++k) dst[n][k] = *(const LAS bf16x8*)(lds + PG8_SB(b, h) + boff + n * 2048 + k * 1024); } while (0)
; #define PG8_MMA(ai, bj, At, Bt) do { __builtin_amdgcn_s_setprio(1); _Pragma("unroll") for (int m = 0; m < 4; ++m) _Pragma("unroll") for (int n = 0; n < 2; ++n) _Pragma("unroll") for (int k = 0; k < 2; ++k) \
;         acc[ai][bj][m][n] = __builtin_amdgcn_mfma_f32_16x16x32_bf16(Bt[n][k], At[m][k], acc[ai][bj][m][n], 0, 0, 0); __builtin_amdgcn_s_setprio(0); } while (0)
; #define PG8_WAIT_V(n) asm volatile("s_waitcnt vmcnt(" #n ")" ::: "memory")
; #define PG8_WAIT_L(n) asm volatile("s_waitcnt lgkmcnt(" #n ")" ::: "memory")
; #define PG8_BAR __builtin_amdgcn_s_barrier()
; #define PG8_SCHED __builtin_amdgcn_sched_barrier(0)
; template <class Epi>
; DI void gemm_phase(LAS unsigned char* lds, const Gemm g, const StaticOrder& S, const Epi& E) {
;     ...
;             const bool last = (t == nt - 2);
;             const char* a1 = cA + (size_t)(t + 1) * kstep;
;             const char* a2 = last ? nA : cA + (size_t)(t + 2) * kstep; const char* b2 = last ? nB : cB + (size_t)(t + 2) * kstep;
;             const char* a3 = a2 + kstep; const char* b3 = b2 + kstep;
;             PG8_LDB(B0, 0, 0); PG8_LDB(B1, 0, 1); PG8_SCHED; PG8_LDA(At, 0, 0); PG8_STAGE(PG8_SA(1, 1), a1 + hstepA, voffA);
;             PG8_WAIT_V(8); PG8_WAIT_L(0); PG8_BAR; PG8_MMA(0, 0, At, B0); PG8_MMA(0, 1, At, B1); PG8_BAR; PG8_SCHED;
;             PG8_LDA(At, 0, 1); PG8_STAGE(PG8_SB(0, 0), b2, voffB); PG8_STAGE(PG8_SB(0, 1), b2 + hstepB, voffB); PG8_STAGE(PG8_SA(0, 0), a2, voffA);
;             PG8_WAIT_V(8); PG8_WAIT_L(0); PG8_BAR; PG8_MMA(1, 0, At, B0); PG8_MMA(1, 1, At, B1); PG8_BAR; PG8_SCHED;
.LBB0_548:
	v_add_u32_e32 v1, s65, v160
	ds_read_b128 v[148:151], v1
	ds_read_b128 v[152:155], v1 offset:1024
	ds_read_b128 v[166:169], v1 offset:2048
	ds_read_b128 v[170:173], v1 offset:3072
	v_add_u32_e32 v1, s66, v160
	ds_read_b128 v[174:177], v1
	ds_read_b128 v[182:185], v1 offset:1024
	ds_read_b128 v[186:189], v1 offset:2048
	ds_read_b128 v[190:193], v1 offset:3072
	s_add_i32 s39, s46, 2
	s_add_u32 s47, s8, 0xfff00080
	s_addc_u32 s50, s9, -1
	s_cmp_eq_u32 s64, s46
	s_cselect_b32 s46, s42, s13
	s_cselect_b32 s51, s41, s50
	s_cselect_b32 s50, s40, s47
	s_cselect_b32 s47, s43, s35
	s_waitcnt lgkmcnt(0)
	v_lshl_add_u64 v[2:3], s[8:9], 0, v[140:141]
	s_add_i32 m0, s56, 0xc000
	ds_read_b128 v[194:197], v162
	ds_read_b128 v[198:201], v162 offset:1024
	ds_read_b128 v[202:205], v162 offset:2048
	ds_read_b128 v[206:209], v162 offset:3072
	ds_read_b128 v[210:213], v162 offset:4096
	ds_read_b128 v[214:217], v162 offset:5120
	ds_read_b128 v[218:221], v162 offset:6144
	ds_read_b128 v[222:225], v162 offset:7168
	global_load_lds_dwordx4 v[2:3], off
	v_lshl_add_u64 v[2:3], s[8:9], 0, v[142:143]
	s_add_i32 m0, s56, 0xe000
	s_nop 0
	global_load_lds_dwordx4 v[2:3], off
	s_waitcnt vmcnt(8)
	s_waitcnt lgkmcnt(0)
	s_setprio 1
	s_barrier
	v_mfma_f32_16x16x32_bf16 v[128:131], v[148:151], v[194:197], v[128:131]
	v_mfma_f32_16x16x32_bf16 v[128:131], v[152:155], v[198:201], v[128:131]
	v_mfma_f32_16x16x32_bf16 v[120:123], v[148:151], v[202:205], v[120:123]
	v_mfma_f32_16x16x32_bf16 v[120:123], v[152:155], v[206:209], v[120:123]
	v_mfma_f32_16x16x32_bf16 v[112:115], v[148:151], v[210:213], v[112:115]
	v_mfma_f32_16x16x32_bf16 v[112:115], v[152:155], v[214:217], v[112:115]
	v_mfma_f32_16x16x32_bf16 v[104:107], v[148:151], v[218:221], v[104:107]
	v_mfma_f32_16x16x32_bf16 v[104:107], v[152:155], v[222:225], v[104:107]
	v_mfma_f32_16x16x32_bf16 v[124:127], v[166:169], v[194:197], v[124:127]
	v_mfma_f32_16x16x32_bf16 v[124:127], v[170:173], v[198:201], v[124:127]
	v_mfma_f32_16x16x32_bf16 v[116:119], v[166:169], v[202:205], v[116:119]
	v_mfma_f32_16x16x32_bf16 v[116:119], v[170:173], v[206:209], v[116:119]
	v_mfma_f32_16x16x32_bf16 v[108:111], v[166:169], v[210:213], v[108:111]
	v_mfma_f32_16x16x32_bf16 v[108:111], v[170:173], v[214:217], v[108:111]
	v_mfma_f32_16x16x32_bf16 v[100:103], v[166:169], v[218:221], v[100:103]
	v_mfma_f32_16x16x32_bf16 v[100:103], v[170:173], v[222:225], v[100:103]
	s_setprio 0
	s_setprio 1
	v_mfma_f32_16x16x32_bf16 v[96:99], v[174:177], v[194:197], v[96:99]
	v_mfma_f32_16x16x32_bf16 v[96:99], v[182:185], v[198:201], v[96:99]
	v_mfma_f32_16x16x32_bf16 v[88:91], v[174:177], v[202:205], v[88:91]
	v_mfma_f32_16x16x32_bf16 v[88:91], v[182:185], v[206:209], v[88:91]
	v_mfma_f32_16x16x32_bf16 v[80:83], v[174:177], v[210:213], v[80:83]
	v_mfma_f32_16x16x32_bf16 v[80:83], v[182:185], v[214:217], v[80:83]
	v_mfma_f32_16x16x32_bf16 v[72:75], v[174:177], v[218:221], v[72:75]
	v_mfma_f32_16x16x32_bf16 v[72:75], v[182:185], v[222:225], v[72:75]
	v_mfma_f32_16x16x32_bf16 v[92:95], v[186:189], v[194:197], v[92:95]
	v_mfma_f32_16x16x32_bf16 v[92:95], v[190:193], v[198:201], v[92:95]
	v_mfma_f32_16x16x32_bf16 v[84:87], v[186:189], v[202:205], v[84:87]
	v_mfma_f32_16x16x32_bf16 v[84:87], v[190:193], v[206:209], v[84:87]
	v_mfma_f32_16x16x32_bf16 v[76:79], v[186:189], v[210:213], v[76:79]
	v_mfma_f32_16x16x32_bf16 v[76:79], v[190:193], v[214:217], v[76:79]
	v_mfma_f32_16x16x32_bf16 v[68:71], v[186:189], v[218:221], v[68:71]
	v_mfma_f32_16x16x32_bf16 v[68:71], v[190:193], v[222:225], v[68:71]
	s_setprio 0
	s_barrier
	s_add_i32 s71, s65, s55
	v_lshl_add_u64 v[156:157], s[46:47], 0, v[134:135]
	s_mov_b32 m0, s71
	ds_read_b128 v[194:197], v162 offset:16384
	ds_read_b128 v[198:201], v162 offset:17408
	ds_read_b128 v[202:205], v162 offset:18432
	ds_read_b128 v[206:209], v162 offset:19456
	ds_read_b128 v[210:213], v162 offset:20480
	ds_read_b128 v[214:217], v162 offset:21504
	ds_read_b128 v[218:221], v162 offset:22528
	ds_read_b128 v[222:225], v162 offset:23552
	global_load_lds_dwordx4 v[156:157], off
	s_add_i32 m0, s71, 0x2000
	s_add_u32 s72, s46, 0x100000
	v_lshl_add_u64 v[178:179], s[46:47], 0, v[138:139]
	s_addc_u32 s73, s47, 0
	s_add_i32 s71, s66, s55
	global_load_lds_dwordx4 v[178:179], off
	v_lshl_add_u64 v[2:3], s[72:73], 0, v[134:135]
	s_mov_b32 m0, s71
	v_lshl_add_u64 v[226:227], s[50:51], 0, v[132:133]
	global_load_lds_dwordx4 v[2:3], off
	v_lshl_add_u64 v[2:3], s[72:73], 0, v[138:139]
	s_add_i32 m0, s71, 0x2000
	v_lshl_add_u64 v[228:229], s[50:51], 0, v[136:137]
	global_load_lds_dwordx4 v[2:3], off
	s_mov_b32 m0, s56
	s_nop 0
	global_load_lds_dwordx4 v[226:227], off
	s_mov_b32 m0, s57
	s_nop 0
	global_load_lds_dwordx4 v[228:229], off
	s_waitcnt vmcnt(8)
	s_waitcnt lgkmcnt(0)
	s_setprio 1
	s_barrier
; #define PG8_STAGE(bufoff, gbase, voff) do { _Pragma("unroll") for (int _i = 0; _i < 2; ++_i) \
;         __builtin_amdgcn_global_load_lds((const unsigned*)((const char*)(gbase) + (voff)[_i]), (LAS unsigned*)(lds + (bufoff) + ldsw + _i * 8192), 16, 0, 0); } while (0)
; #define PG8_LDA(dst, b, h) do { _Pragma("unroll") for (int m = 0; m < 4; ++m) _Pragma("unroll") for (int k = 0; k < 2; ++k) dst[m][k] = *(const LAS bf16x8*)(lds + PG8_SA(b, h) + aoff + m * 2048 + k * 1024); } while (0)
; #define PG8_LDB(dst, b, h) do { _Pragma("unroll") for (int n = 0; n < 2; ++n) _Pragma("unroll") for (int k = 0; k < 2; ++k) dst[n][k] = *(const LAS bf16x8*)(lds + PG8_SB(b, h) + boff + n * 2048 + k * 1024); } while (0)
; #define PG8_MMA(ai, bj, At, Bt) do { __builtin_amdgcn_s_setprio(1); _Pragma("unroll") for (int m = 0; m < 4; ++m) _Pragma("unroll") for (int n = 0; n < 2; ++n) _Pragma("unroll") for (int k = 0; k < 2; ++k) \
;         acc[ai][bj][m][n] = __builtin_amdgcn_mfma_f32_16x16x32_bf16(Bt[n][k], At[m][k], acc[ai][bj][m][n], 0, 0, 0); __builtin_amdgcn_s_setprio(0); } while (0)
; #define PG8_WAIT_V(n) asm volatile("s_waitcnt vmcnt(" #n ")" ::: "memory")
; #define PG8_WAIT_L(n) asm volatile("s_waitcnt lgkmcnt(" #n ")" ::: "memory")
; #define PG8_BAR __builtin_amdgcn_s_barrier()
; #define PG8_SCHED __builtin_amdgcn_sched_barrier(0)
; template <class Epi>
; DI void gemm_phase(LAS unsigned char* lds, const Gemm g, const StaticOrder& S, const Epi& E) {
;     ...
;             PG8_WAIT_V(8); PG8_WAIT_L(0); PG8_BAR; PG8_MMA(1, 0, At, B0); PG8_MMA(1, 1, At, B1); PG8_BAR; PG8_SCHED;
;             PG8_LDB(B0, 1, 0); PG8_LDB(B1, 1, 1); PG8_SCHED; PG8_LDA(At, 1, 0); PG8_STAGE(PG8_SA(0, 1), a2 + hstepA, voffA);
;             PG8_WAIT_V(8); PG8_WAIT_L(0); PG8_BAR; PG8_MMA(0, 0, At, B0); PG8_MMA(0, 1, At, B1); PG8_BAR; PG8_SCHED;
	v_mfma_f32_16x16x32_bf16 v[64:67], v[148:151], v[194:197], v[64:67]
	v_mfma_f32_16x16x32_bf16 v[64:67], v[152:155], v[198:201], v[64:67]
	v_mfma_f32_16x16x32_bf16 v[56:59], v[148:151], v[202:205], v[56:59]
	v_mfma_f32_16x16x32_bf16 v[56:59], v[152:155], v[206:209], v[56:59]
	v_mfma_f32_16x16x32_bf16 v[48:51], v[148:151], v[210:213], v[48:51]
	v_mfma_f32_16x16x32_bf16 v[48:51], v[152:155], v[214:217], v[48:51]
	v_mfma_f32_16x16x32_bf16 v[40:43], v[148:151], v[218:221], v[40:43]
	v_mfma_f32_16x16x32_bf16 v[40:43], v[152:155], v[222:225], v[40:43]
	v_mfma_f32_16x16x32_bf16 v[60:63], v[166:169], v[194:197], v[60:63]
	v_mfma_f32_16x16x32_bf16 v[60:63], v[170:173], v[198:201], v[60:63]
	v_mfma_f32_16x16x32_bf16 v[52:55], v[166:169], v[202:205], v[52:55]
	v_mfma_f32_16x16x32_bf16 v[52:55], v[170:173], v[206:209], v[52:55]
	v_mfma_f32_16x16x32_bf16 v[44:47], v[166:169], v[210:213], v[44:47]
	v_mfma_f32_16x16x32_bf16 v[44:47], v[170:173], v[214:217], v[44:47]
	v_mfma_f32_16x16x32_bf16 v[36:39], v[166:169], v[218:221], v[36:39]
	v_mfma_f32_16x16x32_bf16 v[36:39], v[170:173], v[222:225], v[36:39]
	s_setprio 0
	s_setprio 1
	v_mfma_f32_16x16x32_bf16 v[32:35], v[174:177], v[194:197], v[32:35]
	v_mfma_f32_16x16x32_bf16 v[32:35], v[182:185], v[198:201], v[32:35]
	v_mfma_f32_16x16x32_bf16 v[24:27], v[174:177], v[202:205], v[24:27]
	v_mfma_f32_16x16x32_bf16 v[24:27], v[182:185], v[206:209], v[24:27]
	v_mfma_f32_16x16x32_bf16 v[16:19], v[174:177], v[210:213], v[16:19]
	v_mfma_f32_16x16x32_bf16 v[16:19], v[182:185], v[214:217], v[16:19]
	v_mfma_f32_16x16x32_bf16 v[8:11], v[174:177], v[218:221], v[8:11]
	v_mfma_f32_16x16x32_bf16 v[8:11], v[182:185], v[222:225], v[8:11]
	v_mfma_f32_16x16x32_bf16 v[28:31], v[186:189], v[194:197], v[28:31]
	v_mfma_f32_16x16x32_bf16 v[28:31], v[190:193], v[198:201], v[28:31]
	v_mfma_f32_16x16x32_bf16 v[20:23], v[186:189], v[202:205], v[20:23]
	v_mfma_f32_16x16x32_bf16 v[20:23], v[190:193], v[206:209], v[20:23]
	v_mfma_f32_16x16x32_bf16 v[12:15], v[186:189], v[210:213], v[12:15]
	v_mfma_f32_16x16x32_bf16 v[12:15], v[190:193], v[214:217], v[12:15]
	v_mfma_f32_16x16x32_bf16 v[2:5], v[186:189], v[218:221], v[4:7]
	v_mfma_f32_16x16x32_bf16 v[2:5], v[190:193], v[222:225], v[2:5]
	s_setprio 0
	s_barrier
	s_add_i32 s71, 0, 0x18000
	v_add_u32_e32 v1, s71, v160
	s_add_i32 s72, 0, 0x1c000
	ds_read_b128 v[148:151], v1
	ds_read_b128 v[152:155], v1 offset:1024
	ds_read_b128 v[166:169], v1 offset:2048
	ds_read_b128 v[170:173], v1 offset:3072
	v_add_u32_e32 v1, s72, v160
	ds_read_b128 v[174:177], v1
	ds_read_b128 v[182:185], v1 offset:1024
	ds_read_b128 v[186:189], v1 offset:2048
	ds_read_b128 v[190:193], v1 offset:3072
	s_add_u32 s50, s50, 0x100000
	s_addc_u32 s51, s51, 0
	s_mov_b32 m0, s58
	v_lshl_add_u64 v[6:7], s[50:51], 0, v[132:133]
	ds_read_b128 v[194:197], v162 offset:32768
	ds_read_b128 v[198:201], v162 offset:33792
	ds_read_b128 v[202:205], v162 offset:34816
	ds_read_b128 v[206:209], v162 offset:35840
	ds_read_b128 v[210:213], v162 offset:36864
	ds_read_b128 v[214:217], v162 offset:37888
	ds_read_b128 v[218:221], v162 offset:38912
	ds_read_b128 v[222:225], v162 offset:39936
	global_load_lds_dwordx4 v[6:7], off
	v_lshl_add_u64 v[6:7], s[50:51], 0, v[136:137]
	s_mov_b32 m0, s59
	s_nop 0
	global_load_lds_dwordx4 v[6:7], off
	s_waitcnt vmcnt(8)
	s_waitcnt lgkmcnt(0)
	s_setprio 1
	s_barrier
	v_mfma_f32_16x16x32_bf16 v[128:131], v[148:151], v[194:197], v[128:131]
	v_mfma_f32_16x16x32_bf16 v[128:131], v[152:155], v[198:201], v[128:131]
	v_mfma_f32_16x16x32_bf16 v[120:123], v[148:151], v[202:205], v[120:123]
	v_mfma_f32_16x16x32_bf16 v[120:123], v[152:155], v[206:209], v[120:123]
	v_mfma_f32_16x16x32_bf16 v[112:115], v[148:151], v[210:213], v[112:115]
	v_mfma_f32_16x16x32_bf16 v[112:115], v[152:155], v[214:217], v[112:115]
	v_mfma_f32_16x16x32_bf16 v[104:107], v[148:151], v[218:221], v[104:107]
	v_mfma_f32_16x16x32_bf16 v[104:107], v[152:155], v[222:225], v[104:107]
	v_mfma_f32_16x16x32_bf16 v[124:127], v[166:169], v[194:197], v[124:127]
	v_mfma_f32_16x16x32_bf16 v[124:127], v[170:173], v[198:201], v[124:127]
	v_mfma_f32_16x16x32_bf16 v[116:119], v[166:169], v[202:205], v[116:119]
	v_mfma_f32_16x16x32_bf16 v[116:119], v[170:173], v[206:209], v[116:119]
	v_mfma_f32_16x16x32_bf16 v[108:111], v[166:169], v[210:213], v[108:111]
	v_mfma_f32_16x16x32_bf16 v[108:111], v[170:173], v[214:217], v[108:111]
	v_mfma_f32_16x16x32_bf16 v[100:103], v[166:169], v[218:221], v[100:103]
	v_mfma_f32_16x16x32_bf16 v[100:103], v[170:173], v[222:225], v[100:103]
	s_setprio 0
	s_setprio 1
	v_mfma_f32_16x16x32_bf16 v[96:99], v[174:177], v[194:197], v[96:99]
	v_mfma_f32_16x16x32_bf16 v[96:99], v[182:185], v[198:201], v[96:99]
	v_mfma_f32_16x16x32_bf16 v[88:91], v[174:177], v[202:205], v[88:91]
	v_mfma_f32_16x16x32_bf16 v[88:91], v[182:185], v[206:209], v[88:91]
	v_mfma_f32_16x16x32_bf16 v[80:83], v[174:177], v[210:213], v[80:83]
	v_mfma_f32_16x16x32_bf16 v[80:83], v[182:185], v[214:217], v[80:83]
	v_mfma_f32_16x16x32_bf16 v[72:75], v[174:177], v[218:221], v[72:75]
	v_mfma_f32_16x16x32_bf16 v[72:75], v[182:185], v[222:225], v[72:75]
	v_mfma_f32_16x16x32_bf16 v[92:95], v[186:189], v[194:197], v[92:95]
	v_mfma_f32_16x16x32_bf16 v[92:95], v[190:193], v[198:201], v[92:95]
	v_mfma_f32_16x16x32_bf16 v[84:87], v[186:189], v[202:205], v[84:87]
	v_mfma_f32_16x16x32_bf16 v[84:87], v[190:193], v[206:209], v[84:87]
	v_mfma_f32_16x16x32_bf16 v[76:79], v[186:189], v[210:213], v[76:79]
	v_mfma_f32_16x16x32_bf16 v[76:79], v[190:193], v[214:217], v[76:79]
	v_mfma_f32_16x16x32_bf16 v[68:71], v[186:189], v[218:221], v[68:71]
	v_mfma_f32_16x16x32_bf16 v[68:71], v[190:193], v[222:225], v[68:71]
	s_setprio 0
	s_barrier
; #define PG8_STAGE(bufoff, gbase, voff) do { _Pragma("unroll") for (int _i = 0; _i < 2; ++_i) \
;         __builtin_amdgcn_global_load_lds((const unsigned*)((const char*)(gbase) + (voff)[_i]), (LAS unsigned*)(lds + (bufoff) + ldsw + _i * 8192), 16, 0, 0); } while (0)
; #define PG8_LDA(dst, b, h) do { _Pragma("unroll") for (int m = 0; m < 4; ++m) _Pragma("unroll") for (int k = 0; k < 2; ++k) dst[m][k] = *(const LAS bf16x8*)(lds + PG8_SA(b, h) + aoff + m * 2048 + k * 1024); } while (0)
; #define PG8_MMA(ai, bj, At, Bt) do { __builtin_amdgcn_s_setprio(1); _Pragma("unroll") for (int m = 0; m < 4; ++m) _Pragma("unroll") for (int n = 0; n < 2; ++n) _Pragma("unroll") for (int k = 0; k < 2; ++k) \
;         acc[ai][bj][m][n] = __builtin_amdgcn_mfma_f32_16x16x32_bf16(Bt[n][k], At[m][k], acc[ai][bj][m][n], 0, 0, 0); __builtin_amdgcn_s_setprio(0); } while (0)
; #define PG8_WAIT_V(n) asm volatile("s_waitcnt vmcnt(" #n ")" ::: "memory")
; #define PG8_WAIT_L(n) asm volatile("s_waitcnt lgkmcnt(" #n ")" ::: "memory")
; #define PG8_BAR __builtin_amdgcn_s_barrier()
; #define PG8_SCHED __builtin_amdgcn_sched_barrier(0)
; template <class Epi>
; DI void gemm_phase(LAS unsigned char* lds, const Gemm g, const StaticOrder& S, const Epi& E) {
;     ...
;             PG8_LDA(At, 1, 1); PG8_STAGE(PG8_SB(1, 0), b3, voffB); PG8_STAGE(PG8_SB(1, 1), b3 + hstepB, voffB); PG8_STAGE(PG8_SA(1, 0), a3, voffA);
;             PG8_WAIT_V(8); PG8_WAIT_L(0); PG8_BAR; PG8_MMA(1, 0, At, B0); PG8_MMA(1, 1, At, B1); PG8_BAR; PG8_SCHED;
;         }
	s_add_i32 s50, s71, s55
	v_lshl_add_u64 v[6:7], v[156:157], 0, s[26:27]
	s_mov_b32 m0, s50
	ds_read_b128 v[194:197], v162 offset:49152
	ds_read_b128 v[198:201], v162 offset:50176
	ds_read_b128 v[202:205], v162 offset:51200
	ds_read_b128 v[206:209], v162 offset:52224
	ds_read_b128 v[210:213], v162 offset:53248
	ds_read_b128 v[214:217], v162 offset:54272
	ds_read_b128 v[218:221], v162 offset:55296
	ds_read_b128 v[222:225], v162 offset:56320
	global_load_lds_dwordx4 v[6:7], off
	s_add_i32 m0, s50, 0x2000
	s_add_u32 s46, s46, 0x100080
	v_lshl_add_u64 v[6:7], v[178:179], 0, s[26:27]
	s_addc_u32 s47, s47, 0
	s_add_i32 s50, s72, s55
	global_load_lds_dwordx4 v[6:7], off
	v_lshl_add_u64 v[6:7], s[46:47], 0, v[134:135]
	s_mov_b32 m0, s50
	s_nop 0
	global_load_lds_dwordx4 v[6:7], off
	v_lshl_add_u64 v[6:7], s[46:47], 0, v[138:139]
	s_add_i32 m0, s50, 0x2000
	s_nop 0
	global_load_lds_dwordx4 v[6:7], off
	v_lshl_add_u64 v[6:7], v[226:227], 0, s[26:27]
	s_mov_b32 m0, s62
	s_nop 0
	global_load_lds_dwordx4 v[6:7], off
	v_lshl_add_u64 v[6:7], v[228:229], 0, s[26:27]
	s_mov_b32 m0, s63
	s_nop 0
	global_load_lds_dwordx4 v[6:7], off
	s_waitcnt vmcnt(8)
	s_waitcnt lgkmcnt(0)
	s_setprio 1
	s_barrier
	v_mfma_f32_16x16x32_bf16 v[64:67], v[148:151], v[194:197], v[64:67]
	v_mfma_f32_16x16x32_bf16 v[64:67], v[152:155], v[198:201], v[64:67]
	v_mfma_f32_16x16x32_bf16 v[56:59], v[148:151], v[202:205], v[56:59]
	v_mfma_f32_16x16x32_bf16 v[56:59], v[152:155], v[206:209], v[56:59]
	v_mfma_f32_16x16x32_bf16 v[48:51], v[148:151], v[210:213], v[48:51]
	v_mfma_f32_16x16x32_bf16 v[48:51], v[152:155], v[214:217], v[48:51]
	v_mfma_f32_16x16x32_bf16 v[40:43], v[148:151], v[218:221], v[40:43]
	v_mfma_f32_16x16x32_bf16 v[40:43], v[152:155], v[222:225], v[40:43]
	v_mfma_f32_16x16x32_bf16 v[60:63], v[166:169], v[194:197], v[60:63]
	v_mfma_f32_16x16x32_bf16 v[60:63], v[170:173], v[198:201], v[60:63]
	v_mfma_f32_16x16x32_bf16 v[52:55], v[166:169], v[202:205], v[52:55]
	v_mfma_f32_16x16x32_bf16 v[52:55], v[170:173], v[206:209], v[52:55]
	v_mfma_f32_16x16x32_bf16 v[44:47], v[166:169], v[210:213], v[44:47]
	v_mfma_f32_16x16x32_bf16 v[44:47], v[170:173], v[214:217], v[44:47]
	v_mfma_f32_16x16x32_bf16 v[36:39], v[166:169], v[218:221], v[36:39]
	v_mfma_f32_16x16x32_bf16 v[36:39], v[170:173], v[222:225], v[36:39]
	s_setprio 0
	s_setprio 1
	v_mfma_f32_16x16x32_bf16 v[32:35], v[174:177], v[194:197], v[32:35]
	v_mfma_f32_16x16x32_bf16 v[32:35], v[182:185], v[198:201], v[32:35]
	v_mfma_f32_16x16x32_bf16 v[28:31], v[186:189], v[194:197], v[28:31]
	v_mfma_f32_16x16x32_bf16 v[28:31], v[190:193], v[198:201], v[28:31]
	v_mfma_f32_16x16x32_bf16 v[24:27], v[174:177], v[202:205], v[24:27]
	v_mfma_f32_16x16x32_bf16 v[24:27], v[182:185], v[206:209], v[24:27]
	v_mfma_f32_16x16x32_bf16 v[20:23], v[186:189], v[202:205], v[20:23]
	v_mfma_f32_16x16x32_bf16 v[20:23], v[190:193], v[206:209], v[20:23]
	v_mfma_f32_16x16x32_bf16 v[16:19], v[174:177], v[210:213], v[16:19]
	v_mfma_f32_16x16x32_bf16 v[16:19], v[182:185], v[214:217], v[16:19]
	v_mfma_f32_16x16x32_bf16 v[12:15], v[186:189], v[210:213], v[12:15]
	v_mfma_f32_16x16x32_bf16 v[12:15], v[190:193], v[214:217], v[12:15]
	v_mfma_f32_16x16x32_bf16 v[6:9], v[174:177], v[218:221], v[8:11]
	v_mfma_f32_16x16x32_bf16 v[2:5], v[186:189], v[218:221], v[2:5]
	v_mfma_f32_16x16x32_bf16 v[8:11], v[182:185], v[222:225], v[6:9]
	v_mfma_f32_16x16x32_bf16 v[4:7], v[190:193], v[222:225], v[2:5]
	s_setprio 0
	s_barrier
	s_add_u32 s8, s8, 0x100
	s_addc_u32 s9, s9, 0
	s_add_u32 s13, s13, 0x100
	s_addc_u32 s35, s35, 0
	s_cmp_ge_i32 s39, s61
	s_mov_b32 s46, s39
	s_cbranch_scc0 .LBB0_548

; #define PG8_STAGE(bufoff, gbase, voff) do { _Pragma("unroll") for (int _i = 0; _i < 2; ++_i) \
;         __builtin_amdgcn_global_load_lds((const unsigned*)((const char*)(gbase) + (voff)[_i]), (LAS unsigned*)(lds + (bufoff) + ldsw + _i * 8192), 16, 0, 0); } while (0)
; #define PG8_LDA(dst, b, h) do { _Pragma("unroll") for (int m = 0; m < 4; ++m) _Pragma("unroll") for (int k = 0; k < 2; ++k) dst[m][k] = *(const LAS bf16x8*)(lds + PG8_SA(b, h) + aoff + m * 2048 + k * 1024); } while (0)
; #define PG8_LDB(dst, b, h) do { _Pragma("unroll") for (int n = 0; n < 2; ++n) _Pragma("unroll") for (int k = 0; k < 2; ++k) dst[n][k] = *(const LAS bf16x8*)(lds + PG8_SB(b, h) + boff + n * 2048 + k * 1024); } while (0)
; #define PG8_MMA(ai, bj, At, Bt) do { __builtin_amdgcn_s_setprio(1); _Pragma("unroll") for (int m = 0; m < 4; ++m) _Pragma("unroll") for (int n = 0; n < 2; ++n) _Pragma("unroll") for (int k = 0; k < 2; ++k) \
;         acc[ai][bj][m][n] = __builtin_amdgcn_mfma_f32_16x16x32_bf16(Bt[n][k], At[m][k], acc[ai][bj][m][n], 0, 0, 0); __builtin_amdgcn_s_setprio(0); } while (0)
; #define PG8_WAIT_V(n) asm volatile("s_waitcnt vmcnt(" #n ")" ::: "memory")
; #define PG8_WAIT_L(n) asm volatile("s_waitcnt lgkmcnt(" #n ")" ::: "memory")
; #define PG8_BAR __builtin_amdgcn_s_barrier()
; #define PG8_SCHED __builtin_amdgcn_sched_barrier(0)
; template <class Epi>
; DI void gemm_phase(LAS unsigned char* lds, const Gemm g, const StaticOrder& S, const Epi& E) {
;     ...
;             const bool last = (t == nt - 2);
;             const char* a1 = cA + (size_t)(t + 1) * kstep;
;             const char* a2 = last ? nA : cA + (size_t)(t + 2) * kstep; const char* b2 = last ? nB : cB + (size_t)(t + 2) * kstep;
;             const char* a3 = a2 + kstep; const char* b3 = b2 + kstep;
;             PG8_LDB(B0, 0, 0); PG8_LDB(B1, 0, 1); PG8_SCHED; PG8_LDA(At, 0, 0); PG8_STAGE(PG8_SA(1, 1), a1 + hstepA, voffA);
;             PG8_WAIT_V(8); PG8_WAIT_L(0); PG8_BAR; PG8_MMA(0, 0, At, B0); PG8_MMA(0, 1, At, B1); PG8_BAR; PG8_SCHED;
;             PG8_LDA(At, 0, 1); PG8_STAGE(PG8_SB(0, 0), b2, voffB); PG8_STAGE(PG8_SB(0, 1), b2 + hstepB, voffB); PG8_STAGE(PG8_SA(0, 0), a2, voffA);
;             PG8_WAIT_V(8); PG8_WAIT_L(0); PG8_BAR; PG8_MMA(1, 0, At, B0); PG8_MMA(1, 1, At, B1); PG8_BAR; PG8_SCHED;
.LBB0_705:
	ds_read_b128 v[150:153], v147
	ds_read_b128 v[154:157], v147 offset:1024
	ds_read_b128 v[158:161], v147 offset:2048
	ds_read_b128 v[162:165], v147 offset:3072
	ds_read_b128 v[166:169], v148
	ds_read_b128 v[170:173], v148 offset:1024
	ds_read_b128 v[174:177], v148 offset:2048
	ds_read_b128 v[182:185], v148 offset:3072
	s_add_i32 s63, s28, 2
	s_add_u32 s29, s26, 0xfff00080
	s_addc_u32 s30, s27, -1
	s_cmp_eq_u32 s54, s28
	s_cselect_b32 s28, s60, s61
	s_cselect_b32 s31, s17, s30
	s_cselect_b32 s30, s19, s29
	s_cselect_b32 s29, s59, s62
	v_lshl_add_u64 v[178:179], s[26:27], 0, v[136:137]
	s_add_i32 m0, s25, 0xc000
	ds_read_b128 v[186:189], v149
	ds_read_b128 v[190:193], v149 offset:1024
	ds_read_b128 v[194:197], v149 offset:2048
	ds_read_b128 v[198:201], v149 offset:3072
	ds_read_b128 v[202:205], v149 offset:4096
	ds_read_b128 v[206:209], v149 offset:5120
	ds_read_b128 v[210:213], v149 offset:6144
	ds_read_b128 v[214:217], v149 offset:7168
	global_load_lds_dwordx4 v[178:179], off
	v_lshl_add_u64 v[178:179], s[26:27], 0, v[138:139]
	s_add_i32 m0, s25, 0xe000
	s_nop 0
	global_load_lds_dwordx4 v[178:179], off
	s_waitcnt vmcnt(8)
	s_waitcnt lgkmcnt(0)
	s_setprio 1
	s_barrier
	v_mfma_f32_16x16x32_bf16 v[124:127], v[150:153], v[186:189], v[124:127]
	v_mfma_f32_16x16x32_bf16 v[124:127], v[154:157], v[190:193], v[124:127]
	v_mfma_f32_16x16x32_bf16 v[108:111], v[150:153], v[194:197], v[108:111]
	v_mfma_f32_16x16x32_bf16 v[108:111], v[154:157], v[198:201], v[108:111]
	v_mfma_f32_16x16x32_bf16 v[92:95], v[150:153], v[202:205], v[92:95]
	v_mfma_f32_16x16x32_bf16 v[92:95], v[154:157], v[206:209], v[92:95]
	v_mfma_f32_16x16x32_bf16 v[76:79], v[150:153], v[210:213], v[76:79]
	v_mfma_f32_16x16x32_bf16 v[76:79], v[154:157], v[214:217], v[76:79]
	v_mfma_f32_16x16x32_bf16 v[116:119], v[158:161], v[186:189], v[116:119]
	v_mfma_f32_16x16x32_bf16 v[116:119], v[162:165], v[190:193], v[116:119]
	v_mfma_f32_16x16x32_bf16 v[100:103], v[158:161], v[194:197], v[100:103]
	v_mfma_f32_16x16x32_bf16 v[100:103], v[162:165], v[198:201], v[100:103]
	v_mfma_f32_16x16x32_bf16 v[84:87], v[158:161], v[202:205], v[84:87]
	v_mfma_f32_16x16x32_bf16 v[84:87], v[162:165], v[206:209], v[84:87]
	v_mfma_f32_16x16x32_bf16 v[68:71], v[158:161], v[210:213], v[68:71]
	v_mfma_f32_16x16x32_bf16 v[68:71], v[162:165], v[214:217], v[68:71]
	s_setprio 0
	s_setprio 1
	v_mfma_f32_16x16x32_bf16 v[120:123], v[166:169], v[186:189], v[120:123]
	v_mfma_f32_16x16x32_bf16 v[120:123], v[170:173], v[190:193], v[120:123]
	v_mfma_f32_16x16x32_bf16 v[104:107], v[166:169], v[194:197], v[104:107]
	v_mfma_f32_16x16x32_bf16 v[104:107], v[170:173], v[198:201], v[104:107]
	v_mfma_f32_16x16x32_bf16 v[88:91], v[166:169], v[202:205], v[88:91]
	v_mfma_f32_16x16x32_bf16 v[88:91], v[170:173], v[206:209], v[88:91]
	v_mfma_f32_16x16x32_bf16 v[72:75], v[166:169], v[210:213], v[72:75]
	v_mfma_f32_16x16x32_bf16 v[72:75], v[170:173], v[214:217], v[72:75]
	v_mfma_f32_16x16x32_bf16 v[112:115], v[174:177], v[186:189], v[112:115]
	v_mfma_f32_16x16x32_bf16 v[112:115], v[182:185], v[190:193], v[112:115]
	v_mfma_f32_16x16x32_bf16 v[96:99], v[174:177], v[194:197], v[96:99]
	v_mfma_f32_16x16x32_bf16 v[96:99], v[182:185], v[198:201], v[96:99]
	v_mfma_f32_16x16x32_bf16 v[80:83], v[174:177], v[202:205], v[80:83]
	v_mfma_f32_16x16x32_bf16 v[80:83], v[182:185], v[206:209], v[80:83]
	v_mfma_f32_16x16x32_bf16 v[64:67], v[174:177], v[210:213], v[64:67]
	v_mfma_f32_16x16x32_bf16 v[64:67], v[182:185], v[214:217], v[64:67]
	s_setprio 0
	s_barrier
	s_add_i32 s64, s55, s39
	v_lshl_add_u64 v[178:179], s[28:29], 0, v[132:133]
	s_mov_b32 m0, s64
	ds_read_b128 v[186:189], v149 offset:16384
	ds_read_b128 v[190:193], v149 offset:17408
	ds_read_b128 v[194:197], v149 offset:18432
	ds_read_b128 v[198:201], v149 offset:19456
	ds_read_b128 v[202:205], v149 offset:20480
	ds_read_b128 v[206:209], v149 offset:21504
	ds_read_b128 v[210:213], v149 offset:22528
	ds_read_b128 v[214:217], v149 offset:23552
	global_load_lds_dwordx4 v[178:179], off
	s_add_i32 m0, s64, 0x2000
	s_add_u32 s64, s28, 0x100000
	v_lshl_add_u64 v[218:219], s[28:29], 0, v[128:129]
	s_addc_u32 s65, s29, 0
	s_add_i32 s66, s56, s39
	global_load_lds_dwordx4 v[218:219], off
	v_lshl_add_u64 v[220:221], s[64:65], 0, v[132:133]
	s_mov_b32 m0, s66
	v_lshl_add_u64 v[222:223], s[30:31], 0, v[130:131]
	global_load_lds_dwordx4 v[220:221], off
	v_lshl_add_u64 v[220:221], s[64:65], 0, v[128:129]
	s_add_i32 m0, s66, 0x2000
	s_nop 0
	global_load_lds_dwordx4 v[220:221], off
	v_lshl_add_u64 v[220:221], s[30:31], 0, v[134:135]
	s_mov_b32 m0, s25
	s_nop 0
	global_load_lds_dwordx4 v[220:221], off
	s_mov_b32 m0, s42
	s_nop 0
	global_load_lds_dwordx4 v[222:223], off
	s_waitcnt vmcnt(8)
	s_waitcnt lgkmcnt(0)
	s_setprio 1
	s_barrier
; #define PG8_STAGE(bufoff, gbase, voff) do { _Pragma("unroll") for (int _i = 0; _i < 2; ++_i) \
;         __builtin_amdgcn_global_load_lds((const unsigned*)((const char*)(gbase) + (voff)[_i]), (LAS unsigned*)(lds + (bufoff) + ldsw + _i * 8192), 16, 0, 0); } while (0)
; #define PG8_LDA(dst, b, h) do { _Pragma("unroll") for (int m = 0; m < 4; ++m) _Pragma("unroll") for (int k = 0; k < 2; ++k) dst[m][k] = *(const LAS bf16x8*)(lds + PG8_SA(b, h) + aoff + m * 2048 + k * 1024); } while (0)
; #define PG8_LDB(dst, b, h) do { _Pragma("unroll") for (int n = 0; n < 2; ++n) _Pragma("unroll") for (int k = 0; k < 2; ++k) dst[n][k] = *(const LAS bf16x8*)(lds + PG8_SB(b, h) + boff + n * 2048 + k * 1024); } while (0)
; #define PG8_MMA(ai, bj, At, Bt) do { __builtin_amdgcn_s_setprio(1); _Pragma("unroll") for (int m = 0; m < 4; ++m) _Pragma("unroll") for (int n = 0; n < 2; ++n) _Pragma("unroll") for (int k = 0; k < 2; ++k) \
;         acc[ai][bj][m][n] = __builtin_amdgcn_mfma_f32_16x16x32_bf16(Bt[n][k], At[m][k], acc[ai][bj][m][n], 0, 0, 0); __builtin_amdgcn_s_setprio(0); } while (0)
; #define PG8_WAIT_V(n) asm volatile("s_waitcnt vmcnt(" #n ")" ::: "memory")
; #define PG8_WAIT_L(n) asm volatile("s_waitcnt lgkmcnt(" #n ")" ::: "memory")
; #define PG8_BAR __builtin_amdgcn_s_barrier()
; #define PG8_SCHED __builtin_amdgcn_sched_barrier(0)
; template <class Epi>
; DI void gemm_phase(LAS unsigned char* lds, const Gemm g, const StaticOrder& S, const Epi& E) {
;     ...
;             PG8_WAIT_V(8); PG8_WAIT_L(0); PG8_BAR; PG8_MMA(1, 0, At, B0); PG8_MMA(1, 1, At, B1); PG8_BAR; PG8_SCHED;
;             PG8_LDB(B0, 1, 0); PG8_LDB(B1, 1, 1); PG8_SCHED; PG8_LDA(At, 1, 0); PG8_STAGE(PG8_SA(0, 1), a2 + hstepA, voffA);
;             PG8_WAIT_V(8); PG8_WAIT_L(0); PG8_BAR; PG8_MMA(0, 0, At, B0); PG8_MMA(0, 1, At, B1); PG8_BAR; PG8_SCHED;
	v_mfma_f32_16x16x32_bf16 v[60:63], v[150:153], v[186:189], v[60:63]
	v_mfma_f32_16x16x32_bf16 v[60:63], v[154:157], v[190:193], v[60:63]
	v_mfma_f32_16x16x32_bf16 v[44:47], v[150:153], v[194:197], v[44:47]
	v_mfma_f32_16x16x32_bf16 v[44:47], v[154:157], v[198:201], v[44:47]
	v_mfma_f32_16x16x32_bf16 v[28:31], v[150:153], v[202:205], v[28:31]
	v_mfma_f32_16x16x32_bf16 v[28:31], v[154:157], v[206:209], v[28:31]
	v_mfma_f32_16x16x32_bf16 v[12:15], v[150:153], v[210:213], v[12:15]
	v_mfma_f32_16x16x32_bf16 v[12:15], v[154:157], v[214:217], v[12:15]
	v_mfma_f32_16x16x32_bf16 v[52:55], v[158:161], v[186:189], v[52:55]
	v_mfma_f32_16x16x32_bf16 v[52:55], v[162:165], v[190:193], v[52:55]
	v_mfma_f32_16x16x32_bf16 v[36:39], v[158:161], v[194:197], v[36:39]
	v_mfma_f32_16x16x32_bf16 v[36:39], v[162:165], v[198:201], v[36:39]
	v_mfma_f32_16x16x32_bf16 v[20:23], v[158:161], v[202:205], v[20:23]
	v_mfma_f32_16x16x32_bf16 v[20:23], v[162:165], v[206:209], v[20:23]
	v_mfma_f32_16x16x32_bf16 v[4:7], v[158:161], v[210:213], v[4:7]
	v_mfma_f32_16x16x32_bf16 v[4:7], v[162:165], v[214:217], v[4:7]
	s_setprio 0
	s_setprio 1
	v_mfma_f32_16x16x32_bf16 v[56:59], v[166:169], v[186:189], v[56:59]
	v_mfma_f32_16x16x32_bf16 v[56:59], v[170:173], v[190:193], v[56:59]
	v_mfma_f32_16x16x32_bf16 v[40:43], v[166:169], v[194:197], v[40:43]
	v_mfma_f32_16x16x32_bf16 v[40:43], v[170:173], v[198:201], v[40:43]
	v_mfma_f32_16x16x32_bf16 v[24:27], v[166:169], v[202:205], v[24:27]
	v_mfma_f32_16x16x32_bf16 v[24:27], v[170:173], v[206:209], v[24:27]
	v_mfma_f32_16x16x32_bf16 v[8:11], v[166:169], v[210:213], v[8:11]
	v_mfma_f32_16x16x32_bf16 v[8:11], v[170:173], v[214:217], v[8:11]
	v_mfma_f32_16x16x32_bf16 v[48:51], v[174:177], v[186:189], v[48:51]
	v_mfma_f32_16x16x32_bf16 v[48:51], v[182:185], v[190:193], v[48:51]
	v_mfma_f32_16x16x32_bf16 v[32:35], v[174:177], v[194:197], v[32:35]
	v_mfma_f32_16x16x32_bf16 v[32:35], v[182:185], v[198:201], v[32:35]
	v_mfma_f32_16x16x32_bf16 v[16:19], v[174:177], v[202:205], v[16:19]
	v_mfma_f32_16x16x32_bf16 v[16:19], v[182:185], v[206:209], v[16:19]
	v_mfma_f32_16x16x32_bf16 v[0:3], v[174:177], v[210:213], v[0:3]
	v_mfma_f32_16x16x32_bf16 v[0:3], v[182:185], v[214:217], v[0:3]
	s_setprio 0
	s_barrier
	s_add_i32 s64, 0, 0x18000
	s_add_i32 s65, 0, 0x1c000
	v_add_u32_e32 v162, s64, v145
	v_add_u32_e32 v181, s65, v145
	ds_read_b128 v[150:153], v162
	ds_read_b128 v[154:157], v162 offset:1024
	ds_read_b128 v[158:161], v162 offset:2048
	ds_read_b128 v[162:165], v162 offset:3072
	ds_read_b128 v[166:169], v181
	ds_read_b128 v[170:173], v181 offset:1024
	ds_read_b128 v[174:177], v181 offset:2048
	ds_read_b128 v[182:185], v181 offset:3072
	s_add_u32 s30, s30, 0x100000
	s_addc_u32 s31, s31, 0
	s_mov_b32 m0, s43
	v_lshl_add_u64 v[224:225], s[30:31], 0, v[134:135]
	ds_read_b128 v[186:189], v149 offset:32768
	ds_read_b128 v[190:193], v149 offset:33792
	ds_read_b128 v[194:197], v149 offset:34816
	ds_read_b128 v[198:201], v149 offset:35840
	ds_read_b128 v[202:205], v149 offset:36864
	ds_read_b128 v[206:209], v149 offset:37888
	ds_read_b128 v[210:213], v149 offset:38912
	ds_read_b128 v[214:217], v149 offset:39936
	global_load_lds_dwordx4 v[224:225], off
	v_lshl_add_u64 v[224:225], s[30:31], 0, v[130:131]
	s_mov_b32 m0, s46
	s_nop 0
	global_load_lds_dwordx4 v[224:225], off
	s_waitcnt vmcnt(8)
	s_waitcnt lgkmcnt(0)
	s_setprio 1
	s_barrier
	v_mfma_f32_16x16x32_bf16 v[124:127], v[150:153], v[186:189], v[124:127]
	v_mfma_f32_16x16x32_bf16 v[124:127], v[154:157], v[190:193], v[124:127]
	v_mfma_f32_16x16x32_bf16 v[108:111], v[150:153], v[194:197], v[108:111]
	v_mfma_f32_16x16x32_bf16 v[108:111], v[154:157], v[198:201], v[108:111]
	v_mfma_f32_16x16x32_bf16 v[92:95], v[150:153], v[202:205], v[92:95]
	v_mfma_f32_16x16x32_bf16 v[92:95], v[154:157], v[206:209], v[92:95]
	v_mfma_f32_16x16x32_bf16 v[76:79], v[150:153], v[210:213], v[76:79]
	v_mfma_f32_16x16x32_bf16 v[76:79], v[154:157], v[214:217], v[76:79]
	v_mfma_f32_16x16x32_bf16 v[116:119], v[158:161], v[186:189], v[116:119]
	v_mfma_f32_16x16x32_bf16 v[116:119], v[162:165], v[190:193], v[116:119]
	v_mfma_f32_16x16x32_bf16 v[100:103], v[158:161], v[194:197], v[100:103]
	v_mfma_f32_16x16x32_bf16 v[100:103], v[162:165], v[198:201], v[100:103]
	v_mfma_f32_16x16x32_bf16 v[84:87], v[158:161], v[202:205], v[84:87]
	v_mfma_f32_16x16x32_bf16 v[84:87], v[162:165], v[206:209], v[84:87]
	v_mfma_f32_16x16x32_bf16 v[68:71], v[158:161], v[210:213], v[68:71]
	v_mfma_f32_16x16x32_bf16 v[68:71], v[162:165], v[214:217], v[68:71]
	s_setprio 0
	s_setprio 1
	v_mfma_f32_16x16x32_bf16 v[120:123], v[166:169], v[186:189], v[120:123]
	v_mfma_f32_16x16x32_bf16 v[120:123], v[170:173], v[190:193], v[120:123]
	v_mfma_f32_16x16x32_bf16 v[104:107], v[166:169], v[194:197], v[104:107]
	v_mfma_f32_16x16x32_bf16 v[104:107], v[170:173], v[198:201], v[104:107]
	v_mfma_f32_16x16x32_bf16 v[88:91], v[166:169], v[202:205], v[88:91]
	v_mfma_f32_16x16x32_bf16 v[88:91], v[170:173], v[206:209], v[88:91]
	v_mfma_f32_16x16x32_bf16 v[72:75], v[166:169], v[210:213], v[72:75]
	v_mfma_f32_16x16x32_bf16 v[72:75], v[170:173], v[214:217], v[72:75]
	v_mfma_f32_16x16x32_bf16 v[112:115], v[174:177], v[186:189], v[112:115]
	v_mfma_f32_16x16x32_bf16 v[112:115], v[182:185], v[190:193], v[112:115]
	v_mfma_f32_16x16x32_bf16 v[96:99], v[174:177], v[194:197], v[96:99]
	v_mfma_f32_16x16x32_bf16 v[96:99], v[182:185], v[198:201], v[96:99]
	v_mfma_f32_16x16x32_bf16 v[80:83], v[174:177], v[202:205], v[80:83]
	v_mfma_f32_16x16x32_bf16 v[80:83], v[182:185], v[206:209], v[80:83]
	v_mfma_f32_16x16x32_bf16 v[64:67], v[174:177], v[210:213], v[64:67]
	v_mfma_f32_16x16x32_bf16 v[64:67], v[182:185], v[214:217], v[64:67]
	s_setprio 0
	s_barrier
; #define PG8_STAGE(bufoff, gbase, voff) do { _Pragma("unroll") for (int _i = 0; _i < 2; ++_i) \
;         __builtin_amdgcn_global_load_lds((const unsigned*)((const char*)(gbase) + (voff)[_i]), (LAS unsigned*)(lds + (bufoff) + ldsw + _i * 8192), 16, 0, 0); } while (0)
; #define PG8_LDA(dst, b, h) do { _Pragma("unroll") for (int m = 0; m < 4; ++m) _Pragma("unroll") for (int k = 0; k < 2; ++k) dst[m][k] = *(const LAS bf16x8*)(lds + PG8_SA(b, h) + aoff + m * 2048 + k * 1024); } while (0)
; #define PG8_MMA(ai, bj, At, Bt) do { __builtin_amdgcn_s_setprio(1); _Pragma("unroll") for (int m = 0; m < 4; ++m) _Pragma("unroll") for (int n = 0; n < 2; ++n) _Pragma("unroll") for (int k = 0; k < 2; ++k) \
;         acc[ai][bj][m][n] = __builtin_amdgcn_mfma_f32_16x16x32_bf16(Bt[n][k], At[m][k], acc[ai][bj][m][n], 0, 0, 0); __builtin_amdgcn_s_setprio(0); } while (0)
; #define PG8_WAIT_V(n) asm volatile("s_waitcnt vmcnt(" #n ")" ::: "memory")
; #define PG8_WAIT_L(n) asm volatile("s_waitcnt lgkmcnt(" #n ")" ::: "memory")
; #define PG8_BAR __builtin_amdgcn_s_barrier()
; #define PG8_SCHED __builtin_amdgcn_sched_barrier(0)
; template <class Epi>
; DI void gemm_phase(LAS unsigned char* lds, const Gemm g, const StaticOrder& S, const Epi& E) {
;     ...
;             PG8_LDA(At, 1, 1); PG8_STAGE(PG8_SB(1, 0), b3, voffB); PG8_STAGE(PG8_SB(1, 1), b3 + hstepB, voffB); PG8_STAGE(PG8_SA(1, 0), a3, voffA);
;             PG8_WAIT_V(8); PG8_WAIT_L(0); PG8_BAR; PG8_MMA(1, 0, At, B0); PG8_MMA(1, 1, At, B1); PG8_BAR; PG8_SCHED;
;         }
	s_add_i32 s30, s64, s39
	v_lshl_add_u64 v[178:179], v[178:179], 0, s[12:13]
	s_mov_b32 m0, s30
	ds_read_b128 v[186:189], v149 offset:49152
	ds_read_b128 v[190:193], v149 offset:50176
	ds_read_b128 v[194:197], v149 offset:51200
	ds_read_b128 v[198:201], v149 offset:52224
	ds_read_b128 v[202:205], v149 offset:53248
	ds_read_b128 v[206:209], v149 offset:54272
	ds_read_b128 v[210:213], v149 offset:55296
	ds_read_b128 v[214:217], v149 offset:56320
	global_load_lds_dwordx4 v[178:179], off
	s_add_i32 m0, s30, 0x2000
	s_add_u32 s28, s28, 0x100080
	v_lshl_add_u64 v[178:179], v[218:219], 0, s[12:13]
	s_addc_u32 s29, s29, 0
	s_add_i32 s30, s65, s39
	global_load_lds_dwordx4 v[178:179], off
	v_lshl_add_u64 v[178:179], s[28:29], 0, v[132:133]
	s_mov_b32 m0, s30
	s_nop 0
	global_load_lds_dwordx4 v[178:179], off
	v_lshl_add_u64 v[178:179], s[28:29], 0, v[128:129]
	s_add_i32 m0, s30, 0x2000
	s_nop 0
	global_load_lds_dwordx4 v[178:179], off
	v_lshl_add_u64 v[178:179], v[220:221], 0, s[12:13]
	s_mov_b32 m0, s52
	s_nop 0
	global_load_lds_dwordx4 v[178:179], off
	v_lshl_add_u64 v[178:179], v[222:223], 0, s[12:13]
	s_mov_b32 m0, s53
	s_nop 0
	global_load_lds_dwordx4 v[178:179], off
	s_waitcnt vmcnt(8)
	s_waitcnt lgkmcnt(0)
	s_setprio 1
	s_barrier
	v_mfma_f32_16x16x32_bf16 v[60:63], v[150:153], v[186:189], v[60:63]
	v_mfma_f32_16x16x32_bf16 v[60:63], v[154:157], v[190:193], v[60:63]
	v_mfma_f32_16x16x32_bf16 v[44:47], v[150:153], v[194:197], v[44:47]
	v_mfma_f32_16x16x32_bf16 v[44:47], v[154:157], v[198:201], v[44:47]
	v_mfma_f32_16x16x32_bf16 v[28:31], v[150:153], v[202:205], v[28:31]
	v_mfma_f32_16x16x32_bf16 v[28:31], v[154:157], v[206:209], v[28:31]
	v_mfma_f32_16x16x32_bf16 v[12:15], v[150:153], v[210:213], v[12:15]
	v_mfma_f32_16x16x32_bf16 v[12:15], v[154:157], v[214:217], v[12:15]
	v_mfma_f32_16x16x32_bf16 v[52:55], v[158:161], v[186:189], v[52:55]
	v_mfma_f32_16x16x32_bf16 v[52:55], v[162:165], v[190:193], v[52:55]
	v_mfma_f32_16x16x32_bf16 v[36:39], v[158:161], v[194:197], v[36:39]
	v_mfma_f32_16x16x32_bf16 v[36:39], v[162:165], v[198:201], v[36:39]
	v_mfma_f32_16x16x32_bf16 v[20:23], v[158:161], v[202:205], v[20:23]
	v_mfma_f32_16x16x32_bf16 v[20:23], v[162:165], v[206:209], v[20:23]
	v_mfma_f32_16x16x32_bf16 v[4:7], v[158:161], v[210:213], v[4:7]
	v_mfma_f32_16x16x32_bf16 v[4:7], v[162:165], v[214:217], v[4:7]
	s_setprio 0
	s_setprio 1
	v_mfma_f32_16x16x32_bf16 v[56:59], v[166:169], v[186:189], v[56:59]
	v_mfma_f32_16x16x32_bf16 v[56:59], v[170:173], v[190:193], v[56:59]
	v_mfma_f32_16x16x32_bf16 v[40:43], v[166:169], v[194:197], v[40:43]
	v_mfma_f32_16x16x32_bf16 v[40:43], v[170:173], v[198:201], v[40:43]
	v_mfma_f32_16x16x32_bf16 v[24:27], v[166:169], v[202:205], v[24:27]
	v_mfma_f32_16x16x32_bf16 v[24:27], v[170:173], v[206:209], v[24:27]
	v_mfma_f32_16x16x32_bf16 v[8:11], v[166:169], v[210:213], v[8:11]
	v_mfma_f32_16x16x32_bf16 v[8:11], v[170:173], v[214:217], v[8:11]
	v_mfma_f32_16x16x32_bf16 v[48:51], v[174:177], v[186:189], v[48:51]
	v_mfma_f32_16x16x32_bf16 v[48:51], v[182:185], v[190:193], v[48:51]
	v_mfma_f32_16x16x32_bf16 v[32:35], v[174:177], v[194:197], v[32:35]
	v_mfma_f32_16x16x32_bf16 v[32:35], v[182:185], v[198:201], v[32:35]
	v_mfma_f32_16x16x32_bf16 v[16:19], v[174:177], v[202:205], v[16:19]
	v_mfma_f32_16x16x32_bf16 v[16:19], v[182:185], v[206:209], v[16:19]
	v_mfma_f32_16x16x32_bf16 v[0:3], v[174:177], v[210:213], v[0:3]
	v_mfma_f32_16x16x32_bf16 v[0:3], v[182:185], v[214:217], v[0:3]
	s_setprio 0
	s_barrier
	s_add_u32 s26, s26, 0x100
	s_addc_u32 s27, s27, 0
	s_add_u32 s61, s61, 0x100
	s_addc_u32 s62, s62, 0
	s_cmp_ge_i32 s63, s51
	s_mov_b32 s28, s63
	s_cbranch_scc0 .LBB0_705

; #define PG8_STAGE(bufoff, gbase, voff) do { _Pragma("unroll") for (int _i = 0; _i < 2; ++_i) \
;         __builtin_amdgcn_global_load_lds((const unsigned*)((const char*)(gbase) + (voff)[_i]), (LAS unsigned*)(lds + (bufoff) + ldsw + _i * 8192), 16, 0, 0); } while (0)
; #define PG8_LDA(dst, b, h) do { _Pragma("unroll") for (int m = 0; m < 4; ++m) _Pragma("unroll") for (int k = 0; k < 2; ++k) dst[m][k] = *(const LAS bf16x8*)(lds + PG8_SA(b, h) + aoff + m * 2048 + k * 1024); } while (0)
; #define PG8_LDB(dst, b, h) do { _Pragma("unroll") for (int n = 0; n < 2; ++n) _Pragma("unroll") for (int k = 0; k < 2; ++k) dst[n][k] = *(const LAS bf16x8*)(lds + PG8_SB(b, h) + boff + n * 2048 + k * 1024); } while (0)
; #define PG8_MMA(ai, bj, At, Bt) do { __builtin_amdgcn_s_setprio(1); _Pragma("unroll") for (int m = 0; m < 4; ++m) _Pragma("unroll") for (int n = 0; n < 2; ++n) _Pragma("unroll") for (int k = 0; k < 2; ++k) \
;         acc[ai][bj][m][n] = __builtin_amdgcn_mfma_f32_16x16x32_bf16(Bt[n][k], At[m][k], acc[ai][bj][m][n], 0, 0, 0); __builtin_amdgcn_s_setprio(0); } while (0)
; #define PG8_WAIT_V(n) asm volatile("s_waitcnt vmcnt(" #n ")" ::: "memory")
; #define PG8_WAIT_L(n) asm volatile("s_waitcnt lgkmcnt(" #n ")" ::: "memory")
; #define PG8_BAR __builtin_amdgcn_s_barrier()
; #define PG8_SCHED __builtin_amdgcn_sched_barrier(0)
; template <class Epi>
; DI void gemm_phase(LAS unsigned char* lds, const Gemm g, const StaticOrder& S, const Epi& E) {
;     ...
;             const bool last = (t == nt - 2);
;             const char* a1 = cA + (size_t)(t + 1) * kstep;
;             const char* a2 = last ? nA : cA + (size_t)(t + 2) * kstep; const char* b2 = last ? nB : cB + (size_t)(t + 2) * kstep;
;             const char* a3 = a2 + kstep; const char* b3 = b2 + kstep;
;             PG8_LDB(B0, 0, 0); PG8_LDB(B1, 0, 1); PG8_SCHED; PG8_LDA(At, 0, 0); PG8_STAGE(PG8_SA(1, 1), a1 + hstepA, voffA);
;             PG8_WAIT_V(8); PG8_WAIT_L(0); PG8_BAR; PG8_MMA(0, 0, At, B0); PG8_MMA(0, 1, At, B1); PG8_BAR; PG8_SCHED;
;             PG8_LDA(At, 0, 1); PG8_STAGE(PG8_SB(0, 0), b2, voffB); PG8_STAGE(PG8_SB(0, 1), b2 + hstepB, voffB); PG8_STAGE(PG8_SA(0, 0), a2, voffA);
;             PG8_WAIT_V(8); PG8_WAIT_L(0); PG8_BAR; PG8_MMA(1, 0, At, B0); PG8_MMA(1, 1, At, B1); PG8_BAR; PG8_SCHED;
.LBB0_727:
	ds_read_b128 v[150:153], v147
	ds_read_b128 v[154:157], v147 offset:1024
	ds_read_b128 v[158:161], v147 offset:2048
	ds_read_b128 v[162:165], v147 offset:3072
	ds_read_b128 v[166:169], v148
	ds_read_b128 v[170:173], v148 offset:1024
	ds_read_b128 v[174:177], v148 offset:2048
	ds_read_b128 v[182:185], v148 offset:3072
	s_add_i32 s74, s38, 2
	s_add_u32 s39, s34, 0xffff0080
	s_addc_u32 s40, s35, -1
	s_cmp_eq_u32 s60, s38
	s_cselect_b32 s38, s71, s72
	s_cselect_b32 s41, s25, s40
	s_cselect_b32 s40, s27, s39
	s_cselect_b32 s39, s70, s73
	v_lshl_add_u64 v[178:179], s[34:35], 0, v[136:137]
	s_add_i32 m0, s51, 0xc000
	ds_read_b128 v[186:189], v149
	ds_read_b128 v[190:193], v149 offset:1024
	ds_read_b128 v[194:197], v149 offset:2048
	ds_read_b128 v[198:201], v149 offset:3072
	ds_read_b128 v[202:205], v149 offset:4096
	ds_read_b128 v[206:209], v149 offset:5120
	ds_read_b128 v[210:213], v149 offset:6144
	ds_read_b128 v[214:217], v149 offset:7168
	global_load_lds_dwordx4 v[178:179], off
	v_lshl_add_u64 v[178:179], s[34:35], 0, v[138:139]
	s_add_i32 m0, s51, 0xe000
	s_nop 0
	global_load_lds_dwordx4 v[178:179], off
	s_waitcnt vmcnt(8)
	s_waitcnt lgkmcnt(0)
	s_setprio 1
	s_barrier
	v_mfma_f32_16x16x32_bf16 v[120:123], v[150:153], v[186:189], v[120:123]
	v_mfma_f32_16x16x32_bf16 v[120:123], v[154:157], v[190:193], v[120:123]
	v_mfma_f32_16x16x32_bf16 v[108:111], v[150:153], v[194:197], v[108:111]
	v_mfma_f32_16x16x32_bf16 v[108:111], v[154:157], v[198:201], v[108:111]
	v_mfma_f32_16x16x32_bf16 v[92:95], v[150:153], v[202:205], v[92:95]
	v_mfma_f32_16x16x32_bf16 v[92:95], v[154:157], v[206:209], v[92:95]
	v_mfma_f32_16x16x32_bf16 v[76:79], v[150:153], v[210:213], v[76:79]
	v_mfma_f32_16x16x32_bf16 v[76:79], v[154:157], v[214:217], v[76:79]
	v_mfma_f32_16x16x32_bf16 v[124:127], v[158:161], v[186:189], v[124:127]
	v_mfma_f32_16x16x32_bf16 v[124:127], v[162:165], v[190:193], v[124:127]
	v_mfma_f32_16x16x32_bf16 v[104:107], v[158:161], v[194:197], v[104:107]
	v_mfma_f32_16x16x32_bf16 v[104:107], v[162:165], v[198:201], v[104:107]
	v_mfma_f32_16x16x32_bf16 v[88:91], v[158:161], v[202:205], v[88:91]
	v_mfma_f32_16x16x32_bf16 v[88:91], v[162:165], v[206:209], v[88:91]
	v_mfma_f32_16x16x32_bf16 v[72:75], v[158:161], v[210:213], v[72:75]
	v_mfma_f32_16x16x32_bf16 v[72:75], v[162:165], v[214:217], v[72:75]
	s_setprio 0
	s_setprio 1
	v_mfma_f32_16x16x32_bf16 v[116:119], v[166:169], v[186:189], v[116:119]
	v_mfma_f32_16x16x32_bf16 v[116:119], v[170:173], v[190:193], v[116:119]
	v_mfma_f32_16x16x32_bf16 v[100:103], v[166:169], v[194:197], v[100:103]
	v_mfma_f32_16x16x32_bf16 v[100:103], v[170:173], v[198:201], v[100:103]
	v_mfma_f32_16x16x32_bf16 v[84:87], v[166:169], v[202:205], v[84:87]
	v_mfma_f32_16x16x32_bf16 v[84:87], v[170:173], v[206:209], v[84:87]
	v_mfma_f32_16x16x32_bf16 v[68:71], v[166:169], v[210:213], v[68:71]
	v_mfma_f32_16x16x32_bf16 v[68:71], v[170:173], v[214:217], v[68:71]
	v_mfma_f32_16x16x32_bf16 v[112:115], v[174:177], v[186:189], v[112:115]
	v_mfma_f32_16x16x32_bf16 v[112:115], v[182:185], v[190:193], v[112:115]
	v_mfma_f32_16x16x32_bf16 v[96:99], v[174:177], v[194:197], v[96:99]
	v_mfma_f32_16x16x32_bf16 v[96:99], v[182:185], v[198:201], v[96:99]
	v_mfma_f32_16x16x32_bf16 v[80:83], v[174:177], v[202:205], v[80:83]
	v_mfma_f32_16x16x32_bf16 v[80:83], v[182:185], v[206:209], v[80:83]
	v_mfma_f32_16x16x32_bf16 v[64:67], v[174:177], v[210:213], v[64:67]
	v_mfma_f32_16x16x32_bf16 v[64:67], v[182:185], v[214:217], v[64:67]
	s_setprio 0
	s_barrier
	s_add_i32 s75, s62, s50
	v_lshl_add_u64 v[178:179], s[38:39], 0, v[132:133]
	s_mov_b32 m0, s75
	ds_read_b128 v[186:189], v149 offset:16384
	ds_read_b128 v[190:193], v149 offset:17408
	ds_read_b128 v[194:197], v149 offset:18432
	ds_read_b128 v[198:201], v149 offset:19456
	ds_read_b128 v[202:205], v149 offset:20480
	ds_read_b128 v[206:209], v149 offset:21504
	ds_read_b128 v[210:213], v149 offset:22528
	ds_read_b128 v[214:217], v149 offset:23552
	global_load_lds_dwordx4 v[178:179], off
	s_add_i32 m0, s75, 0x2000
	s_add_u32 s76, s38, 0x10000
	v_lshl_add_u64 v[218:219], s[38:39], 0, v[128:129]
	s_addc_u32 s77, s39, 0
	s_add_i32 s75, s63, s50
	global_load_lds_dwordx4 v[218:219], off
	v_lshl_add_u64 v[220:221], s[76:77], 0, v[132:133]
	s_mov_b32 m0, s75
	v_lshl_add_u64 v[222:223], s[40:41], 0, v[130:131]
	global_load_lds_dwordx4 v[220:221], off
	v_lshl_add_u64 v[220:221], s[76:77], 0, v[128:129]
	s_add_i32 m0, s75, 0x2000
	s_nop 0
	global_load_lds_dwordx4 v[220:221], off
	v_lshl_add_u64 v[220:221], s[40:41], 0, v[134:135]
	s_mov_b32 m0, s51
	s_nop 0
	global_load_lds_dwordx4 v[220:221], off
	s_mov_b32 m0, s52
	s_nop 0
	global_load_lds_dwordx4 v[222:223], off
	s_waitcnt vmcnt(8)
	s_waitcnt lgkmcnt(0)
	s_setprio 1
	s_barrier
; #define PG8_STAGE(bufoff, gbase, voff) do { _Pragma("unroll") for (int _i = 0; _i < 2; ++_i) \
;         __builtin_amdgcn_global_load_lds((const unsigned*)((const char*)(gbase) + (voff)[_i]), (LAS unsigned*)(lds + (bufoff) + ldsw + _i * 8192), 16, 0, 0); } while (0)
; #define PG8_LDA(dst, b, h) do { _Pragma("unroll") for (int m = 0; m < 4; ++m) _Pragma("unroll") for (int k = 0; k < 2; ++k) dst[m][k] = *(const LAS bf16x8*)(lds + PG8_SA(b, h) + aoff + m * 2048 + k * 1024); } while (0)
; #define PG8_LDB(dst, b, h) do { _Pragma("unroll") for (int n = 0; n < 2; ++n) _Pragma("unroll") for (int k = 0; k < 2; ++k) dst[n][k] = *(const LAS bf16x8*)(lds + PG8_SB(b, h) + boff + n * 2048 + k * 1024); } while (0)
; #define PG8_MMA(ai, bj, At, Bt) do { __builtin_amdgcn_s_setprio(1); _Pragma("unroll") for (int m = 0; m < 4; ++m) _Pragma("unroll") for (int n = 0; n < 2; ++n) _Pragma("unroll") for (int k = 0; k < 2; ++k) \
;         acc[ai][bj][m][n] = __builtin_amdgcn_mfma_f32_16x16x32_bf16(Bt[n][k], At[m][k], acc[ai][bj][m][n], 0, 0, 0); __builtin_amdgcn_s_setprio(0); } while (0)
; #define PG8_WAIT_V(n) asm volatile("s_waitcnt vmcnt(" #n ")" ::: "memory")
; #define PG8_WAIT_L(n) asm volatile("s_waitcnt lgkmcnt(" #n ")" ::: "memory")
; #define PG8_BAR __builtin_amdgcn_s_barrier()
; #define PG8_SCHED __builtin_amdgcn_sched_barrier(0)
; template <class Epi>
; DI void gemm_phase(LAS unsigned char* lds, const Gemm g, const StaticOrder& S, const Epi& E) {
;     ...
;             PG8_WAIT_V(8); PG8_WAIT_L(0); PG8_BAR; PG8_MMA(1, 0, At, B0); PG8_MMA(1, 1, At, B1); PG8_BAR; PG8_SCHED;
;             PG8_LDB(B0, 1, 0); PG8_LDB(B1, 1, 1); PG8_SCHED; PG8_LDA(At, 1, 0); PG8_STAGE(PG8_SA(0, 1), a2 + hstepA, voffA);
;             PG8_WAIT_V(8); PG8_WAIT_L(0); PG8_BAR; PG8_MMA(0, 0, At, B0); PG8_MMA(0, 1, At, B1); PG8_BAR; PG8_SCHED;
	v_mfma_f32_16x16x32_bf16 v[60:63], v[150:153], v[186:189], v[60:63]
	v_mfma_f32_16x16x32_bf16 v[60:63], v[154:157], v[190:193], v[60:63]
	v_mfma_f32_16x16x32_bf16 v[44:47], v[150:153], v[194:197], v[44:47]
	v_mfma_f32_16x16x32_bf16 v[44:47], v[154:157], v[198:201], v[44:47]
	v_mfma_f32_16x16x32_bf16 v[28:31], v[150:153], v[202:205], v[28:31]
	v_mfma_f32_16x16x32_bf16 v[28:31], v[154:157], v[206:209], v[28:31]
	v_mfma_f32_16x16x32_bf16 v[12:15], v[150:153], v[210:213], v[12:15]
	v_mfma_f32_16x16x32_bf16 v[12:15], v[154:157], v[214:217], v[12:15]
	v_mfma_f32_16x16x32_bf16 v[56:59], v[158:161], v[186:189], v[56:59]
	v_mfma_f32_16x16x32_bf16 v[56:59], v[162:165], v[190:193], v[56:59]
	v_mfma_f32_16x16x32_bf16 v[40:43], v[158:161], v[194:197], v[40:43]
	v_mfma_f32_16x16x32_bf16 v[40:43], v[162:165], v[198:201], v[40:43]
	v_mfma_f32_16x16x32_bf16 v[24:27], v[158:161], v[202:205], v[24:27]
	v_mfma_f32_16x16x32_bf16 v[24:27], v[162:165], v[206:209], v[24:27]
	v_mfma_f32_16x16x32_bf16 v[8:11], v[158:161], v[210:213], v[8:11]
	v_mfma_f32_16x16x32_bf16 v[8:11], v[162:165], v[214:217], v[8:11]
	s_setprio 0
	s_setprio 1
	v_mfma_f32_16x16x32_bf16 v[52:55], v[166:169], v[186:189], v[52:55]
	v_mfma_f32_16x16x32_bf16 v[52:55], v[170:173], v[190:193], v[52:55]
	v_mfma_f32_16x16x32_bf16 v[36:39], v[166:169], v[194:197], v[36:39]
	v_mfma_f32_16x16x32_bf16 v[36:39], v[170:173], v[198:201], v[36:39]
	v_mfma_f32_16x16x32_bf16 v[20:23], v[166:169], v[202:205], v[20:23]
	v_mfma_f32_16x16x32_bf16 v[20:23], v[170:173], v[206:209], v[20:23]
	v_mfma_f32_16x16x32_bf16 v[4:7], v[166:169], v[210:213], v[4:7]
	v_mfma_f32_16x16x32_bf16 v[4:7], v[170:173], v[214:217], v[4:7]
	v_mfma_f32_16x16x32_bf16 v[48:51], v[174:177], v[186:189], v[48:51]
	v_mfma_f32_16x16x32_bf16 v[48:51], v[182:185], v[190:193], v[48:51]
	v_mfma_f32_16x16x32_bf16 v[32:35], v[174:177], v[194:197], v[32:35]
	v_mfma_f32_16x16x32_bf16 v[32:35], v[182:185], v[198:201], v[32:35]
	v_mfma_f32_16x16x32_bf16 v[16:19], v[174:177], v[202:205], v[16:19]
	v_mfma_f32_16x16x32_bf16 v[16:19], v[182:185], v[206:209], v[16:19]
	v_mfma_f32_16x16x32_bf16 v[0:3], v[174:177], v[210:213], v[0:3]
	v_mfma_f32_16x16x32_bf16 v[0:3], v[182:185], v[214:217], v[0:3]
	s_setprio 0
	s_barrier
	s_add_i32 s75, 0, 0x18000
	s_add_i32 s76, 0, 0x1c000
	v_add_u32_e32 v162, s75, v145
	v_add_u32_e32 v181, s76, v145
	ds_read_b128 v[150:153], v162
	ds_read_b128 v[154:157], v162 offset:1024
	ds_read_b128 v[158:161], v162 offset:2048
	ds_read_b128 v[162:165], v162 offset:3072
	ds_read_b128 v[166:169], v181
	ds_read_b128 v[170:173], v181 offset:1024
	ds_read_b128 v[174:177], v181 offset:2048
	ds_read_b128 v[182:185], v181 offset:3072
	s_add_u32 s40, s40, 0x10000
	s_addc_u32 s41, s41, 0
	s_mov_b32 m0, s53
	v_lshl_add_u64 v[224:225], s[40:41], 0, v[134:135]
	ds_read_b128 v[186:189], v149 offset:32768
	ds_read_b128 v[190:193], v149 offset:33792
	ds_read_b128 v[194:197], v149 offset:34816
	ds_read_b128 v[198:201], v149 offset:35840
	ds_read_b128 v[202:205], v149 offset:36864
	ds_read_b128 v[206:209], v149 offset:37888
	ds_read_b128 v[210:213], v149 offset:38912
	ds_read_b128 v[214:217], v149 offset:39936
	global_load_lds_dwordx4 v[224:225], off
	v_lshl_add_u64 v[224:225], s[40:41], 0, v[130:131]
	s_mov_b32 m0, s54
	s_nop 0
	global_load_lds_dwordx4 v[224:225], off
	s_waitcnt vmcnt(8)
	s_waitcnt lgkmcnt(0)
	s_setprio 1
	s_barrier
	v_mfma_f32_16x16x32_bf16 v[120:123], v[150:153], v[186:189], v[120:123]
	v_mfma_f32_16x16x32_bf16 v[120:123], v[154:157], v[190:193], v[120:123]
	v_mfma_f32_16x16x32_bf16 v[108:111], v[150:153], v[194:197], v[108:111]
	v_mfma_f32_16x16x32_bf16 v[108:111], v[154:157], v[198:201], v[108:111]
	v_mfma_f32_16x16x32_bf16 v[92:95], v[150:153], v[202:205], v[92:95]
	v_mfma_f32_16x16x32_bf16 v[92:95], v[154:157], v[206:209], v[92:95]
	v_mfma_f32_16x16x32_bf16 v[76:79], v[150:153], v[210:213], v[76:79]
	v_mfma_f32_16x16x32_bf16 v[76:79], v[154:157], v[214:217], v[76:79]
	v_mfma_f32_16x16x32_bf16 v[124:127], v[158:161], v[186:189], v[124:127]
	v_mfma_f32_16x16x32_bf16 v[124:127], v[162:165], v[190:193], v[124:127]
	v_mfma_f32_16x16x32_bf16 v[104:107], v[158:161], v[194:197], v[104:107]
	v_mfma_f32_16x16x32_bf16 v[104:107], v[162:165], v[198:201], v[104:107]
	v_mfma_f32_16x16x32_bf16 v[88:91], v[158:161], v[202:205], v[88:91]
	v_mfma_f32_16x16x32_bf16 v[88:91], v[162:165], v[206:209], v[88:91]
	v_mfma_f32_16x16x32_bf16 v[72:75], v[158:161], v[210:213], v[72:75]
	v_mfma_f32_16x16x32_bf16 v[72:75], v[162:165], v[214:217], v[72:75]
	s_setprio 0
	s_setprio 1
	v_mfma_f32_16x16x32_bf16 v[116:119], v[166:169], v[186:189], v[116:119]
	v_mfma_f32_16x16x32_bf16 v[116:119], v[170:173], v[190:193], v[116:119]
	v_mfma_f32_16x16x32_bf16 v[100:103], v[166:169], v[194:197], v[100:103]
	v_mfma_f32_16x16x32_bf16 v[100:103], v[170:173], v[198:201], v[100:103]
	v_mfma_f32_16x16x32_bf16 v[84:87], v[166:169], v[202:205], v[84:87]
	v_mfma_f32_16x16x32_bf16 v[84:87], v[170:173], v[206:209], v[84:87]
	v_mfma_f32_16x16x32_bf16 v[68:71], v[166:169], v[210:213], v[68:71]
	v_mfma_f32_16x16x32_bf16 v[68:71], v[170:173], v[214:217], v[68:71]
	v_mfma_f32_16x16x32_bf16 v[112:115], v[174:177], v[186:189], v[112:115]
	v_mfma_f32_16x16x32_bf16 v[112:115], v[182:185], v[190:193], v[112:115]
	v_mfma_f32_16x16x32_bf16 v[96:99], v[174:177], v[194:197], v[96:99]
	v_mfma_f32_16x16x32_bf16 v[96:99], v[182:185], v[198:201], v[96:99]
	v_mfma_f32_16x16x32_bf16 v[80:83], v[174:177], v[202:205], v[80:83]
	v_mfma_f32_16x16x32_bf16 v[80:83], v[182:185], v[206:209], v[80:83]
	v_mfma_f32_16x16x32_bf16 v[64:67], v[174:177], v[210:213], v[64:67]
	v_mfma_f32_16x16x32_bf16 v[64:67], v[182:185], v[214:217], v[64:67]
	s_setprio 0
	s_barrier
; #define PG8_STAGE(bufoff, gbase, voff) do { _Pragma("unroll") for (int _i = 0; _i < 2; ++_i) \
;         __builtin_amdgcn_global_load_lds((const unsigned*)((const char*)(gbase) + (voff)[_i]), (LAS unsigned*)(lds + (bufoff) + ldsw + _i * 8192), 16, 0, 0); } while (0)
; #define PG8_LDA(dst, b, h) do { _Pragma("unroll") for (int m = 0; m < 4; ++m) _Pragma("unroll") for (int k = 0; k < 2; ++k) dst[m][k] = *(const LAS bf16x8*)(lds + PG8_SA(b, h) + aoff + m * 2048 + k * 1024); } while (0)
; #define PG8_MMA(ai, bj, At, Bt) do { __builtin_amdgcn_s_setprio(1); _Pragma("unroll") for (int m = 0; m < 4; ++m) _Pragma("unroll") for (int n = 0; n < 2; ++n) _Pragma("unroll") for (int k = 0; k < 2; ++k) \
;         acc[ai][bj][m][n] = __builtin_amdgcn_mfma_f32_16x16x32_bf16(Bt[n][k], At[m][k], acc[ai][bj][m][n], 0, 0, 0); __builtin_amdgcn_s_setprio(0); } while (0)
; #define PG8_WAIT_V(n) asm volatile("s_waitcnt vmcnt(" #n ")" ::: "memory")
; #define PG8_WAIT_L(n) asm volatile("s_waitcnt lgkmcnt(" #n ")" ::: "memory")
; #define PG8_BAR __builtin_amdgcn_s_barrier()
; #define PG8_SCHED __builtin_amdgcn_sched_barrier(0)
; template <class Epi>
; DI void gemm_phase(LAS unsigned char* lds, const Gemm g, const StaticOrder& S, const Epi& E) {
;     ...
;             PG8_LDA(At, 1, 1); PG8_STAGE(PG8_SB(1, 0), b3, voffB); PG8_STAGE(PG8_SB(1, 1), b3 + hstepB, voffB); PG8_STAGE(PG8_SA(1, 0), a3, voffA);
;             PG8_WAIT_V(8); PG8_WAIT_L(0); PG8_BAR; PG8_MMA(1, 0, At, B0); PG8_MMA(1, 1, At, B1); PG8_BAR; PG8_SCHED;
;         }
	s_add_i32 s40, s75, s50
	v_lshl_add_u64 v[178:179], v[178:179], 0, s[10:11]
	s_mov_b32 m0, s40
	ds_read_b128 v[186:189], v149 offset:49152
	ds_read_b128 v[190:193], v149 offset:50176
	ds_read_b128 v[194:197], v149 offset:51200
	ds_read_b128 v[198:201], v149 offset:52224
	ds_read_b128 v[202:205], v149 offset:53248
	ds_read_b128 v[206:209], v149 offset:54272
	ds_read_b128 v[210:213], v149 offset:55296
	ds_read_b128 v[214:217], v149 offset:56320
	global_load_lds_dwordx4 v[178:179], off
	s_add_i32 m0, s40, 0x2000
	s_add_u32 s38, s38, 0x10080
	v_lshl_add_u64 v[178:179], v[218:219], 0, s[10:11]
	s_addc_u32 s39, s39, 0
	s_add_i32 s40, s76, s50
	global_load_lds_dwordx4 v[178:179], off
	v_lshl_add_u64 v[178:179], s[38:39], 0, v[132:133]
	s_mov_b32 m0, s40
	s_nop 0
	global_load_lds_dwordx4 v[178:179], off
	v_lshl_add_u64 v[178:179], s[38:39], 0, v[128:129]
	s_add_i32 m0, s40, 0x2000
	s_nop 0
	global_load_lds_dwordx4 v[178:179], off
	v_lshl_add_u64 v[178:179], v[220:221], 0, s[10:11]
	s_mov_b32 m0, s58
	s_nop 0
	global_load_lds_dwordx4 v[178:179], off
	v_lshl_add_u64 v[178:179], v[222:223], 0, s[10:11]
	s_mov_b32 m0, s59
	s_nop 0
	global_load_lds_dwordx4 v[178:179], off
	s_waitcnt vmcnt(8)
	s_waitcnt lgkmcnt(0)
	s_setprio 1
	s_barrier
	v_mfma_f32_16x16x32_bf16 v[60:63], v[150:153], v[186:189], v[60:63]
	v_mfma_f32_16x16x32_bf16 v[60:63], v[154:157], v[190:193], v[60:63]
	v_mfma_f32_16x16x32_bf16 v[44:47], v[150:153], v[194:197], v[44:47]
	v_mfma_f32_16x16x32_bf16 v[44:47], v[154:157], v[198:201], v[44:47]
	v_mfma_f32_16x16x32_bf16 v[28:31], v[150:153], v[202:205], v[28:31]
	v_mfma_f32_16x16x32_bf16 v[28:31], v[154:157], v[206:209], v[28:31]
	v_mfma_f32_16x16x32_bf16 v[12:15], v[150:153], v[210:213], v[12:15]
	v_mfma_f32_16x16x32_bf16 v[12:15], v[154:157], v[214:217], v[12:15]
	v_mfma_f32_16x16x32_bf16 v[56:59], v[158:161], v[186:189], v[56:59]
	v_mfma_f32_16x16x32_bf16 v[56:59], v[162:165], v[190:193], v[56:59]
	v_mfma_f32_16x16x32_bf16 v[40:43], v[158:161], v[194:197], v[40:43]
	v_mfma_f32_16x16x32_bf16 v[40:43], v[162:165], v[198:201], v[40:43]
	v_mfma_f32_16x16x32_bf16 v[24:27], v[158:161], v[202:205], v[24:27]
	v_mfma_f32_16x16x32_bf16 v[24:27], v[162:165], v[206:209], v[24:27]
	v_mfma_f32_16x16x32_bf16 v[8:11], v[158:161], v[210:213], v[8:11]
	v_mfma_f32_16x16x32_bf16 v[8:11], v[162:165], v[214:217], v[8:11]
	s_setprio 0
	s_setprio 1
	v_mfma_f32_16x16x32_bf16 v[52:55], v[166:169], v[186:189], v[52:55]
	v_mfma_f32_16x16x32_bf16 v[52:55], v[170:173], v[190:193], v[52:55]
	v_mfma_f32_16x16x32_bf16 v[36:39], v[166:169], v[194:197], v[36:39]
	v_mfma_f32_16x16x32_bf16 v[36:39], v[170:173], v[198:201], v[36:39]
	v_mfma_f32_16x16x32_bf16 v[20:23], v[166:169], v[202:205], v[20:23]
	v_mfma_f32_16x16x32_bf16 v[20:23], v[170:173], v[206:209], v[20:23]
	v_mfma_f32_16x16x32_bf16 v[4:7], v[166:169], v[210:213], v[4:7]
	v_mfma_f32_16x16x32_bf16 v[4:7], v[170:173], v[214:217], v[4:7]
	v_mfma_f32_16x16x32_bf16 v[48:51], v[174:177], v[186:189], v[48:51]
	v_mfma_f32_16x16x32_bf16 v[48:51], v[182:185], v[190:193], v[48:51]
	v_mfma_f32_16x16x32_bf16 v[32:35], v[174:177], v[194:197], v[32:35]
	v_mfma_f32_16x16x32_bf16 v[32:35], v[182:185], v[198:201], v[32:35]
	v_mfma_f32_16x16x32_bf16 v[16:19], v[174:177], v[202:205], v[16:19]
	v_mfma_f32_16x16x32_bf16 v[16:19], v[182:185], v[206:209], v[16:19]
	v_mfma_f32_16x16x32_bf16 v[0:3], v[174:177], v[210:213], v[0:3]
	v_mfma_f32_16x16x32_bf16 v[0:3], v[182:185], v[214:217], v[0:3]
	s_setprio 0
	s_barrier
	s_add_u32 s34, s34, 0x100
	s_addc_u32 s35, s35, 0
	s_add_u32 s72, s72, 0x100
	s_addc_u32 s73, s73, 0
	s_cmp_ge_i32 s74, s57
	s_mov_b32 s38, s74
	s_cbranch_scc0 .LBB0_727

; #define PG8_STAGE(bufoff, gbase, voff) do { _Pragma("unroll") for (int _i = 0; _i < 2; ++_i) \
;         __builtin_amdgcn_global_load_lds((const unsigned*)((const char*)(gbase) + (voff)[_i]), (LAS unsigned*)(lds + (bufoff) + ldsw + _i * 8192), 16, 0, 0); } while (0)
; #define PG8_LDA(dst, b, h) do { _Pragma("unroll") for (int m = 0; m < 4; ++m) _Pragma("unroll") for (int k = 0; k < 2; ++k) dst[m][k] = *(const LAS bf16x8*)(lds + PG8_SA(b, h) + aoff + m * 2048 + k * 1024); } while (0)
; #define PG8_LDB(dst, b, h) do { _Pragma("unroll") for (int n = 0; n < 2; ++n) _Pragma("unroll") for (int k = 0; k < 2; ++k) dst[n][k] = *(const LAS bf16x8*)(lds + PG8_SB(b, h) + boff + n * 2048 + k * 1024); } while (0)
; #define PG8_MMA(ai, bj, At, Bt) do { __builtin_amdgcn_s_setprio(1); _Pragma("unroll") for (int m = 0; m < 4; ++m) _Pragma("unroll") for (int n = 0; n < 2; ++n) _Pragma("unroll") for (int k = 0; k < 2; ++k) \
;         acc[ai][bj][m][n] = __builtin_amdgcn_mfma_f32_16x16x32_bf16(Bt[n][k], At[m][k], acc[ai][bj][m][n], 0, 0, 0); __builtin_amdgcn_s_setprio(0); } while (0)
; #define PG8_WAIT_V(n) asm volatile("s_waitcnt vmcnt(" #n ")" ::: "memory")
; #define PG8_WAIT_L(n) asm volatile("s_waitcnt lgkmcnt(" #n ")" ::: "memory")
; #define PG8_BAR __builtin_amdgcn_s_barrier()
; #define PG8_SCHED __builtin_amdgcn_sched_barrier(0)
; template <class Epi>
; DI void gemm_phase(LAS unsigned char* lds, const Gemm g, const StaticOrder& S, const Epi& E) {
;     ...
;             const bool last = (t == nt - 2);
;             const char* a1 = cA + (size_t)(t + 1) * kstep;
;             const char* a2 = last ? nA : cA + (size_t)(t + 2) * kstep; const char* b2 = last ? nB : cB + (size_t)(t + 2) * kstep;
;             const char* a3 = a2 + kstep; const char* b3 = b2 + kstep;
;             PG8_LDB(B0, 0, 0); PG8_LDB(B1, 0, 1); PG8_SCHED; PG8_LDA(At, 0, 0); PG8_STAGE(PG8_SA(1, 1), a1 + hstepA, voffA);
;             PG8_WAIT_V(8); PG8_WAIT_L(0); PG8_BAR; PG8_MMA(0, 0, At, B0); PG8_MMA(0, 1, At, B1); PG8_BAR; PG8_SCHED;
;             PG8_LDA(At, 0, 1); PG8_STAGE(PG8_SB(0, 0), b2, voffB); PG8_STAGE(PG8_SB(0, 1), b2 + hstepB, voffB); PG8_STAGE(PG8_SA(0, 0), a2, voffA);
;             PG8_WAIT_V(8); PG8_WAIT_L(0); PG8_BAR; PG8_MMA(1, 0, At, B0); PG8_MMA(1, 1, At, B1); PG8_BAR; PG8_SCHED;
.LBB0_813:
	ds_read_b128 v[144:147], v151
	ds_read_b128 v[156:159], v151 offset:1024
	ds_read_b128 v[160:163], v151 offset:2048
	ds_read_b128 v[164:167], v151 offset:3072
	ds_read_b128 v[168:171], v152
	ds_read_b128 v[172:175], v152 offset:1024
	ds_read_b128 v[176:179], v152 offset:2048
	ds_read_b128 v[182:185], v152 offset:3072
	s_add_i32 s63, s28, 2
	s_add_u32 s26, s24, 0x100
	s_addc_u32 s27, s25, 0
	s_cmp_eq_u32 s54, s28
	s_cselect_b32 s28, s22, s61
	s_cselect_b32 s31, s9, s27
	s_cselect_b32 s30, s8, s26
	s_cselect_b32 s29, s23, s62
	v_lshl_add_u64 v[218:219], s[24:25], 0, v[136:137]
	s_add_i32 m0, s40, 0xc000
	ds_read_b128 v[186:189], v153
	ds_read_b128 v[190:193], v153 offset:1024
	ds_read_b128 v[194:197], v153 offset:2048
	ds_read_b128 v[198:201], v153 offset:3072
	ds_read_b128 v[202:205], v153 offset:4096
	ds_read_b128 v[206:209], v153 offset:5120
	ds_read_b128 v[210:213], v153 offset:6144
	ds_read_b128 v[214:217], v153 offset:7168
	global_load_lds_dwordx4 v[218:219], off
	v_lshl_add_u64 v[218:219], s[24:25], 0, v[138:139]
	s_add_i32 m0, s40, 0xe000
	s_nop 0
	global_load_lds_dwordx4 v[218:219], off
	s_waitcnt vmcnt(8)
	s_waitcnt lgkmcnt(0)
	s_setprio 1
	s_barrier
	v_mfma_f32_16x16x32_bf16 v[124:127], v[144:147], v[186:189], v[124:127]
	v_mfma_f32_16x16x32_bf16 v[124:127], v[156:159], v[190:193], v[124:127]
	v_mfma_f32_16x16x32_bf16 v[108:111], v[144:147], v[194:197], v[108:111]
	v_mfma_f32_16x16x32_bf16 v[108:111], v[156:159], v[198:201], v[108:111]
	v_mfma_f32_16x16x32_bf16 v[92:95], v[144:147], v[202:205], v[92:95]
	v_mfma_f32_16x16x32_bf16 v[92:95], v[156:159], v[206:209], v[92:95]
	v_mfma_f32_16x16x32_bf16 v[76:79], v[144:147], v[210:213], v[76:79]
	v_mfma_f32_16x16x32_bf16 v[76:79], v[156:159], v[214:217], v[76:79]
	v_mfma_f32_16x16x32_bf16 v[120:123], v[160:163], v[186:189], v[120:123]
	v_mfma_f32_16x16x32_bf16 v[120:123], v[164:167], v[190:193], v[120:123]
	v_mfma_f32_16x16x32_bf16 v[104:107], v[160:163], v[194:197], v[104:107]
	v_mfma_f32_16x16x32_bf16 v[104:107], v[164:167], v[198:201], v[104:107]
	v_mfma_f32_16x16x32_bf16 v[88:91], v[160:163], v[202:205], v[88:91]
	v_mfma_f32_16x16x32_bf16 v[88:91], v[164:167], v[206:209], v[88:91]
	v_mfma_f32_16x16x32_bf16 v[72:75], v[160:163], v[210:213], v[72:75]
	v_mfma_f32_16x16x32_bf16 v[72:75], v[164:167], v[214:217], v[72:75]
	s_setprio 0
	s_setprio 1
	v_mfma_f32_16x16x32_bf16 v[116:119], v[168:171], v[186:189], v[116:119]
	v_mfma_f32_16x16x32_bf16 v[116:119], v[172:175], v[190:193], v[116:119]
	v_mfma_f32_16x16x32_bf16 v[100:103], v[168:171], v[194:197], v[100:103]
	v_mfma_f32_16x16x32_bf16 v[100:103], v[172:175], v[198:201], v[100:103]
	v_mfma_f32_16x16x32_bf16 v[84:87], v[168:171], v[202:205], v[84:87]
	v_mfma_f32_16x16x32_bf16 v[84:87], v[172:175], v[206:209], v[84:87]
	v_mfma_f32_16x16x32_bf16 v[68:71], v[168:171], v[210:213], v[68:71]
	v_mfma_f32_16x16x32_bf16 v[68:71], v[172:175], v[214:217], v[68:71]
	v_mfma_f32_16x16x32_bf16 v[112:115], v[176:179], v[186:189], v[112:115]
	v_mfma_f32_16x16x32_bf16 v[112:115], v[182:185], v[190:193], v[112:115]
	v_mfma_f32_16x16x32_bf16 v[96:99], v[176:179], v[194:197], v[96:99]
	v_mfma_f32_16x16x32_bf16 v[96:99], v[182:185], v[198:201], v[96:99]
	v_mfma_f32_16x16x32_bf16 v[80:83], v[176:179], v[202:205], v[80:83]
	v_mfma_f32_16x16x32_bf16 v[80:83], v[182:185], v[206:209], v[80:83]
	v_mfma_f32_16x16x32_bf16 v[64:67], v[176:179], v[210:213], v[64:67]
	v_mfma_f32_16x16x32_bf16 v[64:67], v[182:185], v[214:217], v[64:67]
	s_setprio 0
	s_barrier
	s_add_i32 s24, s55, s39
	v_lshl_add_u64 v[218:219], s[28:29], 0, v[130:131]
	s_mov_b32 m0, s24
	ds_read_b128 v[186:189], v153 offset:16384
	ds_read_b128 v[190:193], v153 offset:17408
	ds_read_b128 v[194:197], v153 offset:18432
	ds_read_b128 v[198:201], v153 offset:19456
	ds_read_b128 v[202:205], v153 offset:20480
	ds_read_b128 v[206:209], v153 offset:21504
	ds_read_b128 v[210:213], v153 offset:22528
	ds_read_b128 v[214:217], v153 offset:23552
	global_load_lds_dwordx4 v[218:219], off
	s_add_i32 m0, s24, 0x2000
	s_add_u32 s24, s28, 0x2b0000
	v_lshl_add_u64 v[220:221], s[28:29], 0, v[134:135]
	s_addc_u32 s25, s29, 0
	s_add_i32 s64, s56, s39
	global_load_lds_dwordx4 v[220:221], off
	v_lshl_add_u64 v[222:223], s[24:25], 0, v[130:131]
	s_mov_b32 m0, s64
	v_lshl_add_u64 v[224:225], s[30:31], 0, v[132:133]
	global_load_lds_dwordx4 v[222:223], off
	v_lshl_add_u64 v[222:223], s[24:25], 0, v[134:135]
	s_add_i32 m0, s64, 0x2000
	s_nop 0
	global_load_lds_dwordx4 v[222:223], off
	v_lshl_add_u64 v[222:223], s[30:31], 0, v[128:129]
	s_mov_b32 m0, s40
	s_nop 0
	global_load_lds_dwordx4 v[222:223], off
	s_mov_b32 m0, s41
	s_nop 0
	global_load_lds_dwordx4 v[224:225], off
	s_waitcnt vmcnt(8)
	s_waitcnt lgkmcnt(0)
	s_setprio 1
	s_barrier
; #define PG8_STAGE(bufoff, gbase, voff) do { _Pragma("unroll") for (int _i = 0; _i < 2; ++_i) \
;         __builtin_amdgcn_global_load_lds((const unsigned*)((const char*)(gbase) + (voff)[_i]), (LAS unsigned*)(lds + (bufoff) + ldsw + _i * 8192), 16, 0, 0); } while (0)
; #define PG8_LDA(dst, b, h) do { _Pragma("unroll") for (int m = 0; m < 4; ++m) _Pragma("unroll") for (int k = 0; k < 2; ++k) dst[m][k] = *(const LAS bf16x8*)(lds + PG8_SA(b, h) + aoff + m * 2048 + k * 1024); } while (0)
; #define PG8_LDB(dst, b, h) do { _Pragma("unroll") for (int n = 0; n < 2; ++n) _Pragma("unroll") for (int k = 0; k < 2; ++k) dst[n][k] = *(const LAS bf16x8*)(lds + PG8_SB(b, h) + boff + n * 2048 + k * 1024); } while (0)
; #define PG8_MMA(ai, bj, At, Bt) do { __builtin_amdgcn_s_setprio(1); _Pragma("unroll") for (int m = 0; m < 4; ++m) _Pragma("unroll") for (int n = 0; n < 2; ++n) _Pragma("unroll") for (int k = 0; k < 2; ++k) \
;         acc[ai][bj][m][n] = __builtin_amdgcn_mfma_f32_16x16x32_bf16(Bt[n][k], At[m][k], acc[ai][bj][m][n], 0, 0, 0); __builtin_amdgcn_s_setprio(0); } while (0)
; #define PG8_WAIT_V(n) asm volatile("s_waitcnt vmcnt(" #n ")" ::: "memory")
; #define PG8_WAIT_L(n) asm volatile("s_waitcnt lgkmcnt(" #n ")" ::: "memory")
; #define PG8_BAR __builtin_amdgcn_s_barrier()
; #define PG8_SCHED __builtin_amdgcn_sched_barrier(0)
; template <class Epi>
; DI void gemm_phase(LAS unsigned char* lds, const Gemm g, const StaticOrder& S, const Epi& E) {
;     ...
;             PG8_WAIT_V(8); PG8_WAIT_L(0); PG8_BAR; PG8_MMA(1, 0, At, B0); PG8_MMA(1, 1, At, B1); PG8_BAR; PG8_SCHED;
;             PG8_LDB(B0, 1, 0); PG8_LDB(B1, 1, 1); PG8_SCHED; PG8_LDA(At, 1, 0); PG8_STAGE(PG8_SA(0, 1), a2 + hstepA, voffA);
;             PG8_WAIT_V(8); PG8_WAIT_L(0); PG8_BAR; PG8_MMA(0, 0, At, B0); PG8_MMA(0, 1, At, B1); PG8_BAR; PG8_SCHED;
	v_mfma_f32_16x16x32_bf16 v[60:63], v[144:147], v[186:189], v[60:63]
	v_mfma_f32_16x16x32_bf16 v[60:63], v[156:159], v[190:193], v[60:63]
	v_mfma_f32_16x16x32_bf16 v[44:47], v[144:147], v[194:197], v[44:47]
	v_mfma_f32_16x16x32_bf16 v[44:47], v[156:159], v[198:201], v[44:47]
	v_mfma_f32_16x16x32_bf16 v[28:31], v[144:147], v[202:205], v[28:31]
	v_mfma_f32_16x16x32_bf16 v[28:31], v[156:159], v[206:209], v[28:31]
	v_mfma_f32_16x16x32_bf16 v[12:15], v[144:147], v[210:213], v[12:15]
	v_mfma_f32_16x16x32_bf16 v[12:15], v[156:159], v[214:217], v[12:15]
	v_mfma_f32_16x16x32_bf16 v[56:59], v[160:163], v[186:189], v[56:59]
	v_mfma_f32_16x16x32_bf16 v[56:59], v[164:167], v[190:193], v[56:59]
	v_mfma_f32_16x16x32_bf16 v[40:43], v[160:163], v[194:197], v[40:43]
	v_mfma_f32_16x16x32_bf16 v[40:43], v[164:167], v[198:201], v[40:43]
	v_mfma_f32_16x16x32_bf16 v[24:27], v[160:163], v[202:205], v[24:27]
	v_mfma_f32_16x16x32_bf16 v[24:27], v[164:167], v[206:209], v[24:27]
	v_mfma_f32_16x16x32_bf16 v[8:11], v[160:163], v[210:213], v[8:11]
	v_mfma_f32_16x16x32_bf16 v[8:11], v[164:167], v[214:217], v[8:11]
	s_setprio 0
	s_setprio 1
	v_mfma_f32_16x16x32_bf16 v[52:55], v[168:171], v[186:189], v[52:55]
	v_mfma_f32_16x16x32_bf16 v[52:55], v[172:175], v[190:193], v[52:55]
	v_mfma_f32_16x16x32_bf16 v[36:39], v[168:171], v[194:197], v[36:39]
	v_mfma_f32_16x16x32_bf16 v[36:39], v[172:175], v[198:201], v[36:39]
	v_mfma_f32_16x16x32_bf16 v[20:23], v[168:171], v[202:205], v[20:23]
	v_mfma_f32_16x16x32_bf16 v[20:23], v[172:175], v[206:209], v[20:23]
	v_mfma_f32_16x16x32_bf16 v[4:7], v[168:171], v[210:213], v[4:7]
	v_mfma_f32_16x16x32_bf16 v[4:7], v[172:175], v[214:217], v[4:7]
	v_mfma_f32_16x16x32_bf16 v[48:51], v[176:179], v[186:189], v[48:51]
	v_mfma_f32_16x16x32_bf16 v[48:51], v[182:185], v[190:193], v[48:51]
	v_mfma_f32_16x16x32_bf16 v[32:35], v[176:179], v[194:197], v[32:35]
	v_mfma_f32_16x16x32_bf16 v[32:35], v[182:185], v[198:201], v[32:35]
	v_mfma_f32_16x16x32_bf16 v[16:19], v[176:179], v[202:205], v[16:19]
	v_mfma_f32_16x16x32_bf16 v[16:19], v[182:185], v[206:209], v[16:19]
	v_mfma_f32_16x16x32_bf16 v[0:3], v[176:179], v[210:213], v[0:3]
	v_mfma_f32_16x16x32_bf16 v[0:3], v[182:185], v[214:217], v[0:3]
	s_setprio 0
	s_barrier
	s_add_i32 s64, 0, 0x18000
	v_add_u32_e32 v155, s64, v149
	s_add_i32 s65, 0, 0x1c000
	ds_read_b128 v[144:147], v155
	ds_read_b128 v[156:159], v155 offset:1024
	ds_read_b128 v[160:163], v155 offset:2048
	ds_read_b128 v[164:167], v155 offset:3072
	v_add_u32_e32 v155, s65, v149
	ds_read_b128 v[168:171], v155
	ds_read_b128 v[172:175], v155 offset:1024
	ds_read_b128 v[176:179], v155 offset:2048
	ds_read_b128 v[182:185], v155 offset:3072
	s_add_u32 s24, s30, 0x2b0000
	s_addc_u32 s25, s31, 0
	s_mov_b32 m0, s42
	v_lshl_add_u64 v[226:227], s[24:25], 0, v[128:129]
	ds_read_b128 v[186:189], v153 offset:32768
	ds_read_b128 v[190:193], v153 offset:33792
	ds_read_b128 v[194:197], v153 offset:34816
	ds_read_b128 v[198:201], v153 offset:35840
	ds_read_b128 v[202:205], v153 offset:36864
	ds_read_b128 v[206:209], v153 offset:37888
	ds_read_b128 v[210:213], v153 offset:38912
	ds_read_b128 v[214:217], v153 offset:39936
	global_load_lds_dwordx4 v[226:227], off
	v_lshl_add_u64 v[226:227], s[24:25], 0, v[132:133]
	s_mov_b32 m0, s43
	s_nop 0
	global_load_lds_dwordx4 v[226:227], off
	s_waitcnt vmcnt(8)
	s_waitcnt lgkmcnt(0)
	s_setprio 1
	s_barrier
	v_mfma_f32_16x16x32_bf16 v[124:127], v[144:147], v[186:189], v[124:127]
	v_mfma_f32_16x16x32_bf16 v[124:127], v[156:159], v[190:193], v[124:127]
	v_mfma_f32_16x16x32_bf16 v[108:111], v[144:147], v[194:197], v[108:111]
	v_mfma_f32_16x16x32_bf16 v[108:111], v[156:159], v[198:201], v[108:111]
	v_mfma_f32_16x16x32_bf16 v[92:95], v[144:147], v[202:205], v[92:95]
	v_mfma_f32_16x16x32_bf16 v[92:95], v[156:159], v[206:209], v[92:95]
	v_mfma_f32_16x16x32_bf16 v[76:79], v[144:147], v[210:213], v[76:79]
	v_mfma_f32_16x16x32_bf16 v[76:79], v[156:159], v[214:217], v[76:79]
	v_mfma_f32_16x16x32_bf16 v[120:123], v[160:163], v[186:189], v[120:123]
	v_mfma_f32_16x16x32_bf16 v[120:123], v[164:167], v[190:193], v[120:123]
	v_mfma_f32_16x16x32_bf16 v[104:107], v[160:163], v[194:197], v[104:107]
	v_mfma_f32_16x16x32_bf16 v[104:107], v[164:167], v[198:201], v[104:107]
	v_mfma_f32_16x16x32_bf16 v[88:91], v[160:163], v[202:205], v[88:91]
	v_mfma_f32_16x16x32_bf16 v[88:91], v[164:167], v[206:209], v[88:91]
	v_mfma_f32_16x16x32_bf16 v[72:75], v[160:163], v[210:213], v[72:75]
	v_mfma_f32_16x16x32_bf16 v[72:75], v[164:167], v[214:217], v[72:75]
	s_setprio 0
	s_setprio 1
	v_mfma_f32_16x16x32_bf16 v[116:119], v[168:171], v[186:189], v[116:119]
	v_mfma_f32_16x16x32_bf16 v[116:119], v[172:175], v[190:193], v[116:119]
	v_mfma_f32_16x16x32_bf16 v[100:103], v[168:171], v[194:197], v[100:103]
	v_mfma_f32_16x16x32_bf16 v[100:103], v[172:175], v[198:201], v[100:103]
	v_mfma_f32_16x16x32_bf16 v[84:87], v[168:171], v[202:205], v[84:87]
	v_mfma_f32_16x16x32_bf16 v[84:87], v[172:175], v[206:209], v[84:87]
	v_mfma_f32_16x16x32_bf16 v[68:71], v[168:171], v[210:213], v[68:71]
	v_mfma_f32_16x16x32_bf16 v[68:71], v[172:175], v[214:217], v[68:71]
	v_mfma_f32_16x16x32_bf16 v[112:115], v[176:179], v[186:189], v[112:115]
	v_mfma_f32_16x16x32_bf16 v[112:115], v[182:185], v[190:193], v[112:115]
	v_mfma_f32_16x16x32_bf16 v[96:99], v[176:179], v[194:197], v[96:99]
	v_mfma_f32_16x16x32_bf16 v[96:99], v[182:185], v[198:201], v[96:99]
	v_mfma_f32_16x16x32_bf16 v[80:83], v[176:179], v[202:205], v[80:83]
	v_mfma_f32_16x16x32_bf16 v[80:83], v[182:185], v[206:209], v[80:83]
	v_mfma_f32_16x16x32_bf16 v[64:67], v[176:179], v[210:213], v[64:67]
	v_mfma_f32_16x16x32_bf16 v[64:67], v[182:185], v[214:217], v[64:67]
	s_setprio 0
	s_barrier
; #define PG8_STAGE(bufoff, gbase, voff) do { _Pragma("unroll") for (int _i = 0; _i < 2; ++_i) \
;         __builtin_amdgcn_global_load_lds((const unsigned*)((const char*)(gbase) + (voff)[_i]), (LAS unsigned*)(lds + (bufoff) + ldsw + _i * 8192), 16, 0, 0); } while (0)
; #define PG8_LDA(dst, b, h) do { _Pragma("unroll") for (int m = 0; m < 4; ++m) _Pragma("unroll") for (int k = 0; k < 2; ++k) dst[m][k] = *(const LAS bf16x8*)(lds + PG8_SA(b, h) + aoff + m * 2048 + k * 1024); } while (0)
; #define PG8_MMA(ai, bj, At, Bt) do { __builtin_amdgcn_s_setprio(1); _Pragma("unroll") for (int m = 0; m < 4; ++m) _Pragma("unroll") for (int n = 0; n < 2; ++n) _Pragma("unroll") for (int k = 0; k < 2; ++k) \
;         acc[ai][bj][m][n] = __builtin_amdgcn_mfma_f32_16x16x32_bf16(Bt[n][k], At[m][k], acc[ai][bj][m][n], 0, 0, 0); __builtin_amdgcn_s_setprio(0); } while (0)
; #define PG8_WAIT_V(n) asm volatile("s_waitcnt vmcnt(" #n ")" ::: "memory")
; #define PG8_WAIT_L(n) asm volatile("s_waitcnt lgkmcnt(" #n ")" ::: "memory")
; #define PG8_BAR __builtin_amdgcn_s_barrier()
; #define PG8_SCHED __builtin_amdgcn_sched_barrier(0)
; template <class Epi>
; DI void gemm_phase(LAS unsigned char* lds, const Gemm g, const StaticOrder& S, const Epi& E) {
;     ...
;             PG8_LDA(At, 1, 1); PG8_STAGE(PG8_SB(1, 0), b3, voffB); PG8_STAGE(PG8_SB(1, 1), b3 + hstepB, voffB); PG8_STAGE(PG8_SA(1, 0), a3, voffA);
;             PG8_WAIT_V(8); PG8_WAIT_L(0); PG8_BAR; PG8_MMA(1, 0, At, B0); PG8_MMA(1, 1, At, B1); PG8_BAR; PG8_SCHED;
;         }
	s_add_i32 s24, s64, s39
	v_lshl_add_u64 v[218:219], v[218:219], 0, s[16:17]
	s_mov_b32 m0, s24
	ds_read_b128 v[186:189], v153 offset:49152
	ds_read_b128 v[190:193], v153 offset:50176
	ds_read_b128 v[194:197], v153 offset:51200
	ds_read_b128 v[198:201], v153 offset:52224
	ds_read_b128 v[202:205], v153 offset:53248
	ds_read_b128 v[206:209], v153 offset:54272
	ds_read_b128 v[210:213], v153 offset:55296
	ds_read_b128 v[214:217], v153 offset:56320
	global_load_lds_dwordx4 v[218:219], off
	s_add_i32 m0, s24, 0x2000
	s_add_u32 s24, s28, 0x2b0080
	v_lshl_add_u64 v[218:219], v[220:221], 0, s[16:17]
	s_addc_u32 s25, s29, 0
	s_add_i32 s28, s65, s39
	global_load_lds_dwordx4 v[218:219], off
	v_lshl_add_u64 v[218:219], s[24:25], 0, v[130:131]
	s_mov_b32 m0, s28
	s_nop 0
	global_load_lds_dwordx4 v[218:219], off
	v_lshl_add_u64 v[218:219], s[24:25], 0, v[134:135]
	s_add_i32 m0, s28, 0x2000
	s_nop 0
	global_load_lds_dwordx4 v[218:219], off
	v_lshl_add_u64 v[218:219], v[222:223], 0, s[16:17]
	s_mov_b32 m0, s52
	s_nop 0
	global_load_lds_dwordx4 v[218:219], off
	v_lshl_add_u64 v[218:219], v[224:225], 0, s[16:17]
	s_mov_b32 m0, s53
	s_nop 0
	global_load_lds_dwordx4 v[218:219], off
	s_waitcnt vmcnt(8)
	s_waitcnt lgkmcnt(0)
	s_setprio 1
	s_barrier
	v_mfma_f32_16x16x32_bf16 v[60:63], v[144:147], v[186:189], v[60:63]
	v_mfma_f32_16x16x32_bf16 v[60:63], v[156:159], v[190:193], v[60:63]
	v_mfma_f32_16x16x32_bf16 v[44:47], v[144:147], v[194:197], v[44:47]
	v_mfma_f32_16x16x32_bf16 v[44:47], v[156:159], v[198:201], v[44:47]
	v_mfma_f32_16x16x32_bf16 v[28:31], v[144:147], v[202:205], v[28:31]
	v_mfma_f32_16x16x32_bf16 v[28:31], v[156:159], v[206:209], v[28:31]
	v_mfma_f32_16x16x32_bf16 v[12:15], v[144:147], v[210:213], v[12:15]
	v_mfma_f32_16x16x32_bf16 v[12:15], v[156:159], v[214:217], v[12:15]
	v_mfma_f32_16x16x32_bf16 v[56:59], v[160:163], v[186:189], v[56:59]
	v_mfma_f32_16x16x32_bf16 v[56:59], v[164:167], v[190:193], v[56:59]
	v_mfma_f32_16x16x32_bf16 v[40:43], v[160:163], v[194:197], v[40:43]
	v_mfma_f32_16x16x32_bf16 v[40:43], v[164:167], v[198:201], v[40:43]
	v_mfma_f32_16x16x32_bf16 v[24:27], v[160:163], v[202:205], v[24:27]
	v_mfma_f32_16x16x32_bf16 v[24:27], v[164:167], v[206:209], v[24:27]
	v_mfma_f32_16x16x32_bf16 v[8:11], v[160:163], v[210:213], v[8:11]
	v_mfma_f32_16x16x32_bf16 v[8:11], v[164:167], v[214:217], v[8:11]
	s_setprio 0
	s_setprio 1
	v_mfma_f32_16x16x32_bf16 v[52:55], v[168:171], v[186:189], v[52:55]
	v_mfma_f32_16x16x32_bf16 v[52:55], v[172:175], v[190:193], v[52:55]
	v_mfma_f32_16x16x32_bf16 v[36:39], v[168:171], v[194:197], v[36:39]
	v_mfma_f32_16x16x32_bf16 v[36:39], v[172:175], v[198:201], v[36:39]
	v_mfma_f32_16x16x32_bf16 v[20:23], v[168:171], v[202:205], v[20:23]
	v_mfma_f32_16x16x32_bf16 v[20:23], v[172:175], v[206:209], v[20:23]
	v_mfma_f32_16x16x32_bf16 v[4:7], v[168:171], v[210:213], v[4:7]
	v_mfma_f32_16x16x32_bf16 v[4:7], v[172:175], v[214:217], v[4:7]
	v_mfma_f32_16x16x32_bf16 v[48:51], v[176:179], v[186:189], v[48:51]
	v_mfma_f32_16x16x32_bf16 v[48:51], v[182:185], v[190:193], v[48:51]
	v_mfma_f32_16x16x32_bf16 v[32:35], v[176:179], v[194:197], v[32:35]
	v_mfma_f32_16x16x32_bf16 v[32:35], v[182:185], v[198:201], v[32:35]
	v_mfma_f32_16x16x32_bf16 v[16:19], v[176:179], v[202:205], v[16:19]
	v_mfma_f32_16x16x32_bf16 v[16:19], v[182:185], v[206:209], v[16:19]
	v_mfma_f32_16x16x32_bf16 v[0:3], v[176:179], v[210:213], v[0:3]
	v_mfma_f32_16x16x32_bf16 v[0:3], v[182:185], v[214:217], v[0:3]
	s_setprio 0
	s_barrier
	s_add_u32 s61, s61, 0x100
	s_addc_u32 s62, s62, 0
	s_cmp_ge_i32 s63, s51
	s_mov_b64 s[24:25], s[26:27]
	s_mov_b32 s28, s63
	s_cbranch_scc0 .LBB0_813

; #define PG8_STAGE(bufoff, gbase, voff) do { _Pragma("unroll") for (int _i = 0; _i < 2; ++_i) \
;         __builtin_amdgcn_global_load_lds((const unsigned*)((const char*)(gbase) + (voff)[_i]), (LAS unsigned*)(lds + (bufoff) + ldsw + _i * 8192), 16, 0, 0); } while (0)
; #define PG8_LDA(dst, b, h) do { _Pragma("unroll") for (int m = 0; m < 4; ++m) _Pragma("unroll") for (int k = 0; k < 2; ++k) dst[m][k] = *(const LAS bf16x8*)(lds + PG8_SA(b, h) + aoff + m * 2048 + k * 1024); } while (0)
; #define PG8_LDB(dst, b, h) do { _Pragma("unroll") for (int n = 0; n < 2; ++n) _Pragma("unroll") for (int k = 0; k < 2; ++k) dst[n][k] = *(const LAS bf16x8*)(lds + PG8_SB(b, h) + boff + n * 2048 + k * 1024); } while (0)
; #define PG8_MMA(ai, bj, At, Bt) do { __builtin_amdgcn_s_setprio(1); _Pragma("unroll") for (int m = 0; m < 4; ++m) _Pragma("unroll") for (int n = 0; n < 2; ++n) _Pragma("unroll") for (int k = 0; k < 2; ++k) \
;         acc[ai][bj][m][n] = __builtin_amdgcn_mfma_f32_16x16x32_bf16(Bt[n][k], At[m][k], acc[ai][bj][m][n], 0, 0, 0); __builtin_amdgcn_s_setprio(0); } while (0)
; #define PG8_WAIT_V(n) asm volatile("s_waitcnt vmcnt(" #n ")" ::: "memory")
; #define PG8_WAIT_L(n) asm volatile("s_waitcnt lgkmcnt(" #n ")" ::: "memory")
; #define PG8_BAR __builtin_amdgcn_s_barrier()
; #define PG8_SCHED __builtin_amdgcn_sched_barrier(0)
; template <class Epi>
; DI void gemm_phase(LAS unsigned char* lds, const Gemm g, const StaticOrder& S, const Epi& E) {
;     ...
;             const bool last = (t == nt - 2);
;             const char* a1 = cA + (size_t)(t + 1) * kstep;
;             const char* a2 = last ? nA : cA + (size_t)(t + 2) * kstep; const char* b2 = last ? nB : cB + (size_t)(t + 2) * kstep;
;             const char* a3 = a2 + kstep; const char* b3 = b2 + kstep;
;             PG8_LDB(B0, 0, 0); PG8_LDB(B1, 0, 1); PG8_SCHED; PG8_LDA(At, 0, 0); PG8_STAGE(PG8_SA(1, 1), a1 + hstepA, voffA);
;             PG8_WAIT_V(8); PG8_WAIT_L(0); PG8_BAR; PG8_MMA(0, 0, At, B0); PG8_MMA(0, 1, At, B1); PG8_BAR; PG8_SCHED;
;             PG8_LDA(At, 0, 1); PG8_STAGE(PG8_SB(0, 0), b2, voffB); PG8_STAGE(PG8_SB(0, 1), b2 + hstepB, voffB); PG8_STAGE(PG8_SA(0, 0), a2, voffA);
;             PG8_WAIT_V(8); PG8_WAIT_L(0); PG8_BAR; PG8_MMA(1, 0, At, B0); PG8_MMA(1, 1, At, B1); PG8_BAR; PG8_SCHED;
.LBB0_972:
	ds_read_b128 v[128:131], v201
	ds_read_b128 v[132:135], v201 offset:1024
	ds_read_b128 v[136:139], v201 offset:2048
	ds_read_b128 v[140:143], v201 offset:3072
	ds_read_b128 v[144:147], v202
	ds_read_b128 v[148:151], v202 offset:1024
	ds_read_b128 v[152:155], v202 offset:2048
	ds_read_b128 v[156:159], v202 offset:3072
	s_add_i32 s55, s30, 2
	s_add_u32 s31, s28, 0xfff00080
	s_addc_u32 s34, s29, -1
	s_cmp_eq_u32 s46, s30
	s_cselect_b32 s30, s52, s53
	s_cselect_b32 s35, s19, s34
	s_cselect_b32 s34, s21, s31
	s_cselect_b32 s31, s51, s54
	v_lshl_add_u64 v[196:197], s[28:29], 0, v[180:181]
	s_add_i32 m0, s27, 0xc000
	ds_read_b128 v[160:163], v203
	ds_read_b128 v[164:167], v203 offset:1024
	ds_read_b128 v[168:171], v203 offset:2048
	ds_read_b128 v[188:191], v203 offset:3072
	ds_read_b128 v[192:195], v203 offset:4096
	ds_read_b128 v[204:207], v203 offset:5120
	ds_read_b128 v[208:211], v203 offset:6144
	ds_read_b128 v[212:215], v203 offset:7168
	global_load_lds_dwordx4 v[196:197], off
	v_lshl_add_u64 v[196:197], s[28:29], 0, v[182:183]
	s_add_i32 m0, s27, 0xe000
	s_nop 0
	global_load_lds_dwordx4 v[196:197], off
	s_waitcnt vmcnt(8)
	s_waitcnt lgkmcnt(0)
	s_setprio 1
	s_barrier
	v_mfma_f32_16x16x32_bf16 v[124:127], v[128:131], v[160:163], v[124:127]
	v_mfma_f32_16x16x32_bf16 v[124:127], v[132:135], v[164:167], v[124:127]
	v_mfma_f32_16x16x32_bf16 v[108:111], v[128:131], v[168:171], v[108:111]
	v_mfma_f32_16x16x32_bf16 v[108:111], v[132:135], v[188:191], v[108:111]
	v_mfma_f32_16x16x32_bf16 v[92:95], v[128:131], v[192:195], v[92:95]
	v_mfma_f32_16x16x32_bf16 v[92:95], v[132:135], v[204:207], v[92:95]
	v_mfma_f32_16x16x32_bf16 v[76:79], v[128:131], v[208:211], v[76:79]
	v_mfma_f32_16x16x32_bf16 v[76:79], v[132:135], v[212:215], v[76:79]
	v_mfma_f32_16x16x32_bf16 v[120:123], v[136:139], v[160:163], v[120:123]
	v_mfma_f32_16x16x32_bf16 v[120:123], v[140:143], v[164:167], v[120:123]
	v_mfma_f32_16x16x32_bf16 v[104:107], v[136:139], v[168:171], v[104:107]
	v_mfma_f32_16x16x32_bf16 v[104:107], v[140:143], v[188:191], v[104:107]
	v_mfma_f32_16x16x32_bf16 v[88:91], v[136:139], v[192:195], v[88:91]
	v_mfma_f32_16x16x32_bf16 v[88:91], v[140:143], v[204:207], v[88:91]
	v_mfma_f32_16x16x32_bf16 v[72:75], v[136:139], v[208:211], v[72:75]
	v_mfma_f32_16x16x32_bf16 v[72:75], v[140:143], v[212:215], v[72:75]
	s_setprio 0
	s_setprio 1
	v_mfma_f32_16x16x32_bf16 v[116:119], v[144:147], v[160:163], v[116:119]
	v_mfma_f32_16x16x32_bf16 v[116:119], v[148:151], v[164:167], v[116:119]
	v_mfma_f32_16x16x32_bf16 v[100:103], v[144:147], v[168:171], v[100:103]
	v_mfma_f32_16x16x32_bf16 v[100:103], v[148:151], v[188:191], v[100:103]
	v_mfma_f32_16x16x32_bf16 v[84:87], v[144:147], v[192:195], v[84:87]
	v_mfma_f32_16x16x32_bf16 v[84:87], v[148:151], v[204:207], v[84:87]
	v_mfma_f32_16x16x32_bf16 v[68:71], v[144:147], v[208:211], v[68:71]
	v_mfma_f32_16x16x32_bf16 v[68:71], v[148:151], v[212:215], v[68:71]
	v_mfma_f32_16x16x32_bf16 v[112:115], v[152:155], v[160:163], v[112:115]
	v_mfma_f32_16x16x32_bf16 v[112:115], v[156:159], v[164:167], v[112:115]
	v_mfma_f32_16x16x32_bf16 v[96:99], v[152:155], v[168:171], v[96:99]
	v_mfma_f32_16x16x32_bf16 v[96:99], v[156:159], v[188:191], v[96:99]
	v_mfma_f32_16x16x32_bf16 v[80:83], v[152:155], v[192:195], v[80:83]
	v_mfma_f32_16x16x32_bf16 v[80:83], v[156:159], v[204:207], v[80:83]
	v_mfma_f32_16x16x32_bf16 v[64:67], v[152:155], v[208:211], v[64:67]
	v_mfma_f32_16x16x32_bf16 v[64:67], v[156:159], v[212:215], v[64:67]
	s_setprio 0
	s_barrier
	s_add_i32 s56, s48, s38
	v_lshl_add_u64 v[196:197], s[30:31], 0, v[174:175]
	s_mov_b32 m0, s56
	ds_read_b128 v[160:163], v203 offset:16384
	ds_read_b128 v[164:167], v203 offset:17408
	ds_read_b128 v[168:171], v203 offset:18432
	ds_read_b128 v[188:191], v203 offset:19456
	ds_read_b128 v[192:195], v203 offset:20480
	ds_read_b128 v[204:207], v203 offset:21504
	ds_read_b128 v[208:211], v203 offset:22528
	ds_read_b128 v[212:215], v203 offset:23552
	global_load_lds_dwordx4 v[196:197], off
	s_add_i32 m0, s56, 0x2000
	s_add_u32 s56, s30, 0x100000
	v_lshl_add_u64 v[216:217], s[30:31], 0, v[178:179]
	s_addc_u32 s57, s31, 0
	s_add_i32 s58, s49, s38
	global_load_lds_dwordx4 v[216:217], off
	v_lshl_add_u64 v[218:219], s[56:57], 0, v[174:175]
	s_mov_b32 m0, s58
	v_lshl_add_u64 v[220:221], s[34:35], 0, v[176:177]
	global_load_lds_dwordx4 v[218:219], off
	v_lshl_add_u64 v[218:219], s[56:57], 0, v[178:179]
	s_add_i32 m0, s58, 0x2000
	s_nop 0
	global_load_lds_dwordx4 v[218:219], off
	v_lshl_add_u64 v[218:219], s[34:35], 0, v[172:173]
	s_mov_b32 m0, s27
	s_nop 0
	global_load_lds_dwordx4 v[218:219], off
	s_mov_b32 m0, s39
	s_nop 0
	global_load_lds_dwordx4 v[220:221], off
	s_waitcnt vmcnt(8)
	s_waitcnt lgkmcnt(0)
	s_setprio 1
	s_barrier
; #define PG8_STAGE(bufoff, gbase, voff) do { _Pragma("unroll") for (int _i = 0; _i < 2; ++_i) \
;         __builtin_amdgcn_global_load_lds((const unsigned*)((const char*)(gbase) + (voff)[_i]), (LAS unsigned*)(lds + (bufoff) + ldsw + _i * 8192), 16, 0, 0); } while (0)
; #define PG8_LDA(dst, b, h) do { _Pragma("unroll") for (int m = 0; m < 4; ++m) _Pragma("unroll") for (int k = 0; k < 2; ++k) dst[m][k] = *(const LAS bf16x8*)(lds + PG8_SA(b, h) + aoff + m * 2048 + k * 1024); } while (0)
; #define PG8_LDB(dst, b, h) do { _Pragma("unroll") for (int n = 0; n < 2; ++n) _Pragma("unroll") for (int k = 0; k < 2; ++k) dst[n][k] = *(const LAS bf16x8*)(lds + PG8_SB(b, h) + boff + n * 2048 + k * 1024); } while (0)
; #define PG8_MMA(ai, bj, At, Bt) do { __builtin_amdgcn_s_setprio(1); _Pragma("unroll") for (int m = 0; m < 4; ++m) _Pragma("unroll") for (int n = 0; n < 2; ++n) _Pragma("unroll") for (int k = 0; k < 2; ++k) \
;         acc[ai][bj][m][n] = __builtin_amdgcn_mfma_f32_16x16x32_bf16(Bt[n][k], At[m][k], acc[ai][bj][m][n], 0, 0, 0); __builtin_amdgcn_s_setprio(0); } while (0)
; #define PG8_WAIT_V(n) asm volatile("s_waitcnt vmcnt(" #n ")" ::: "memory")
; #define PG8_WAIT_L(n) asm volatile("s_waitcnt lgkmcnt(" #n ")" ::: "memory")
; #define PG8_BAR __builtin_amdgcn_s_barrier()
; #define PG8_SCHED __builtin_amdgcn_sched_barrier(0)
; template <class Epi>
; DI void gemm_phase(LAS unsigned char* lds, const Gemm g, const StaticOrder& S, const Epi& E) {
;     ...
;             PG8_WAIT_V(8); PG8_WAIT_L(0); PG8_BAR; PG8_MMA(1, 0, At, B0); PG8_MMA(1, 1, At, B1); PG8_BAR; PG8_SCHED;
;             PG8_LDB(B0, 1, 0); PG8_LDB(B1, 1, 1); PG8_SCHED; PG8_LDA(At, 1, 0); PG8_STAGE(PG8_SA(0, 1), a2 + hstepA, voffA);
;             PG8_WAIT_V(8); PG8_WAIT_L(0); PG8_BAR; PG8_MMA(0, 0, At, B0); PG8_MMA(0, 1, At, B1); PG8_BAR; PG8_SCHED;
	v_mfma_f32_16x16x32_bf16 v[60:63], v[128:131], v[160:163], v[60:63]
	v_mfma_f32_16x16x32_bf16 v[60:63], v[132:135], v[164:167], v[60:63]
	v_mfma_f32_16x16x32_bf16 v[44:47], v[128:131], v[168:171], v[44:47]
	v_mfma_f32_16x16x32_bf16 v[44:47], v[132:135], v[188:191], v[44:47]
	v_mfma_f32_16x16x32_bf16 v[28:31], v[128:131], v[192:195], v[28:31]
	v_mfma_f32_16x16x32_bf16 v[28:31], v[132:135], v[204:207], v[28:31]
	v_mfma_f32_16x16x32_bf16 v[12:15], v[128:131], v[208:211], v[12:15]
	v_mfma_f32_16x16x32_bf16 v[12:15], v[132:135], v[212:215], v[12:15]
	v_mfma_f32_16x16x32_bf16 v[56:59], v[136:139], v[160:163], v[56:59]
	v_mfma_f32_16x16x32_bf16 v[56:59], v[140:143], v[164:167], v[56:59]
	v_mfma_f32_16x16x32_bf16 v[40:43], v[136:139], v[168:171], v[40:43]
	v_mfma_f32_16x16x32_bf16 v[40:43], v[140:143], v[188:191], v[40:43]
	v_mfma_f32_16x16x32_bf16 v[24:27], v[136:139], v[192:195], v[24:27]
	v_mfma_f32_16x16x32_bf16 v[24:27], v[140:143], v[204:207], v[24:27]
	v_mfma_f32_16x16x32_bf16 v[8:11], v[136:139], v[208:211], v[8:11]
	v_mfma_f32_16x16x32_bf16 v[8:11], v[140:143], v[212:215], v[8:11]
	s_setprio 0
	s_setprio 1
	v_mfma_f32_16x16x32_bf16 v[52:55], v[144:147], v[160:163], v[52:55]
	v_mfma_f32_16x16x32_bf16 v[52:55], v[148:151], v[164:167], v[52:55]
	v_mfma_f32_16x16x32_bf16 v[36:39], v[144:147], v[168:171], v[36:39]
	v_mfma_f32_16x16x32_bf16 v[36:39], v[148:151], v[188:191], v[36:39]
	v_mfma_f32_16x16x32_bf16 v[20:23], v[144:147], v[192:195], v[20:23]
	v_mfma_f32_16x16x32_bf16 v[20:23], v[148:151], v[204:207], v[20:23]
	v_mfma_f32_16x16x32_bf16 v[4:7], v[144:147], v[208:211], v[4:7]
	v_mfma_f32_16x16x32_bf16 v[4:7], v[148:151], v[212:215], v[4:7]
	v_mfma_f32_16x16x32_bf16 v[48:51], v[152:155], v[160:163], v[48:51]
	v_mfma_f32_16x16x32_bf16 v[48:51], v[156:159], v[164:167], v[48:51]
	v_mfma_f32_16x16x32_bf16 v[32:35], v[152:155], v[168:171], v[32:35]
	v_mfma_f32_16x16x32_bf16 v[32:35], v[156:159], v[188:191], v[32:35]
	v_mfma_f32_16x16x32_bf16 v[16:19], v[152:155], v[192:195], v[16:19]
	v_mfma_f32_16x16x32_bf16 v[16:19], v[156:159], v[204:207], v[16:19]
	v_mfma_f32_16x16x32_bf16 v[0:3], v[152:155], v[208:211], v[0:3]
	v_mfma_f32_16x16x32_bf16 v[0:3], v[156:159], v[212:215], v[0:3]
	s_setprio 0
	s_barrier
	s_add_i32 s56, 0, 0x18000
	s_add_i32 s57, 0, 0x1c000
	v_add_u32_e32 v140, s56, v199
	v_add_u32_e32 v156, s57, v199
	ds_read_b128 v[128:131], v140
	ds_read_b128 v[132:135], v140 offset:1024
	ds_read_b128 v[136:139], v140 offset:2048
	ds_read_b128 v[140:143], v140 offset:3072
	ds_read_b128 v[144:147], v156
	ds_read_b128 v[148:151], v156 offset:1024
	ds_read_b128 v[152:155], v156 offset:2048
	ds_read_b128 v[156:159], v156 offset:3072
	s_add_u32 s34, s34, 0x100000
	s_addc_u32 s35, s35, 0
	s_mov_b32 m0, s40
	v_lshl_add_u64 v[222:223], s[34:35], 0, v[172:173]
	ds_read_b128 v[160:163], v203 offset:32768
	ds_read_b128 v[164:167], v203 offset:33792
	ds_read_b128 v[168:171], v203 offset:34816
	ds_read_b128 v[188:191], v203 offset:35840
	ds_read_b128 v[192:195], v203 offset:36864
	ds_read_b128 v[204:207], v203 offset:37888
	ds_read_b128 v[208:211], v203 offset:38912
	ds_read_b128 v[212:215], v203 offset:39936
	global_load_lds_dwordx4 v[222:223], off
	v_lshl_add_u64 v[222:223], s[34:35], 0, v[176:177]
	s_mov_b32 m0, s41
	s_nop 0
	global_load_lds_dwordx4 v[222:223], off
	s_waitcnt vmcnt(8)
	s_waitcnt lgkmcnt(0)
	s_setprio 1
	s_barrier
	v_mfma_f32_16x16x32_bf16 v[124:127], v[128:131], v[160:163], v[124:127]
	v_mfma_f32_16x16x32_bf16 v[124:127], v[132:135], v[164:167], v[124:127]
	v_mfma_f32_16x16x32_bf16 v[108:111], v[128:131], v[168:171], v[108:111]
	v_mfma_f32_16x16x32_bf16 v[108:111], v[132:135], v[188:191], v[108:111]
	v_mfma_f32_16x16x32_bf16 v[92:95], v[128:131], v[192:195], v[92:95]
	v_mfma_f32_16x16x32_bf16 v[92:95], v[132:135], v[204:207], v[92:95]
	v_mfma_f32_16x16x32_bf16 v[76:79], v[128:131], v[208:211], v[76:79]
	v_mfma_f32_16x16x32_bf16 v[76:79], v[132:135], v[212:215], v[76:79]
	v_mfma_f32_16x16x32_bf16 v[120:123], v[136:139], v[160:163], v[120:123]
	v_mfma_f32_16x16x32_bf16 v[120:123], v[140:143], v[164:167], v[120:123]
	v_mfma_f32_16x16x32_bf16 v[104:107], v[136:139], v[168:171], v[104:107]
	v_mfma_f32_16x16x32_bf16 v[104:107], v[140:143], v[188:191], v[104:107]
	v_mfma_f32_16x16x32_bf16 v[88:91], v[136:139], v[192:195], v[88:91]
	v_mfma_f32_16x16x32_bf16 v[88:91], v[140:143], v[204:207], v[88:91]
	v_mfma_f32_16x16x32_bf16 v[72:75], v[136:139], v[208:211], v[72:75]
	v_mfma_f32_16x16x32_bf16 v[72:75], v[140:143], v[212:215], v[72:75]
	s_setprio 0
	s_setprio 1
	v_mfma_f32_16x16x32_bf16 v[116:119], v[144:147], v[160:163], v[116:119]
	v_mfma_f32_16x16x32_bf16 v[116:119], v[148:151], v[164:167], v[116:119]
	v_mfma_f32_16x16x32_bf16 v[100:103], v[144:147], v[168:171], v[100:103]
	v_mfma_f32_16x16x32_bf16 v[100:103], v[148:151], v[188:191], v[100:103]
	v_mfma_f32_16x16x32_bf16 v[84:87], v[144:147], v[192:195], v[84:87]
	v_mfma_f32_16x16x32_bf16 v[84:87], v[148:151], v[204:207], v[84:87]
	v_mfma_f32_16x16x32_bf16 v[68:71], v[144:147], v[208:211], v[68:71]
	v_mfma_f32_16x16x32_bf16 v[68:71], v[148:151], v[212:215], v[68:71]
	v_mfma_f32_16x16x32_bf16 v[112:115], v[152:155], v[160:163], v[112:115]
	v_mfma_f32_16x16x32_bf16 v[112:115], v[156:159], v[164:167], v[112:115]
	v_mfma_f32_16x16x32_bf16 v[96:99], v[152:155], v[168:171], v[96:99]
	v_mfma_f32_16x16x32_bf16 v[96:99], v[156:159], v[188:191], v[96:99]
	v_mfma_f32_16x16x32_bf16 v[80:83], v[152:155], v[192:195], v[80:83]
	v_mfma_f32_16x16x32_bf16 v[80:83], v[156:159], v[204:207], v[80:83]
	v_mfma_f32_16x16x32_bf16 v[64:67], v[152:155], v[208:211], v[64:67]
	v_mfma_f32_16x16x32_bf16 v[64:67], v[156:159], v[212:215], v[64:67]
	s_setprio 0
	s_barrier
; #define PG8_STAGE(bufoff, gbase, voff) do { _Pragma("unroll") for (int _i = 0; _i < 2; ++_i) \
;         __builtin_amdgcn_global_load_lds((const unsigned*)((const char*)(gbase) + (voff)[_i]), (LAS unsigned*)(lds + (bufoff) + ldsw + _i * 8192), 16, 0, 0); } while (0)
; #define PG8_LDA(dst, b, h) do { _Pragma("unroll") for (int m = 0; m < 4; ++m) _Pragma("unroll") for (int k = 0; k < 2; ++k) dst[m][k] = *(const LAS bf16x8*)(lds + PG8_SA(b, h) + aoff + m * 2048 + k * 1024); } while (0)
; #define PG8_MMA(ai, bj, At, Bt) do { __builtin_amdgcn_s_setprio(1); _Pragma("unroll") for (int m = 0; m < 4; ++m) _Pragma("unroll") for (int n = 0; n < 2; ++n) _Pragma("unroll") for (int k = 0; k < 2; ++k) \
;         acc[ai][bj][m][n] = __builtin_amdgcn_mfma_f32_16x16x32_bf16(Bt[n][k], At[m][k], acc[ai][bj][m][n], 0, 0, 0); __builtin_amdgcn_s_setprio(0); } while (0)
; #define PG8_WAIT_V(n) asm volatile("s_waitcnt vmcnt(" #n ")" ::: "memory")
; #define PG8_WAIT_L(n) asm volatile("s_waitcnt lgkmcnt(" #n ")" ::: "memory")
; #define PG8_BAR __builtin_amdgcn_s_barrier()
; #define PG8_SCHED __builtin_amdgcn_sched_barrier(0)
; template <class Epi>
; DI void gemm_phase(LAS unsigned char* lds, const Gemm g, const StaticOrder& S, const Epi& E) {
;     ...
;             PG8_LDA(At, 1, 1); PG8_STAGE(PG8_SB(1, 0), b3, voffB); PG8_STAGE(PG8_SB(1, 1), b3 + hstepB, voffB); PG8_STAGE(PG8_SA(1, 0), a3, voffA);
;             PG8_WAIT_V(8); PG8_WAIT_L(0); PG8_BAR; PG8_MMA(1, 0, At, B0); PG8_MMA(1, 1, At, B1); PG8_BAR; PG8_SCHED;
;         }
	s_add_i32 s34, s56, s38
	v_lshl_add_u64 v[196:197], v[196:197], 0, s[12:13]
	s_mov_b32 m0, s34
	ds_read_b128 v[160:163], v203 offset:49152
	ds_read_b128 v[164:167], v203 offset:50176
	ds_read_b128 v[168:171], v203 offset:51200
	ds_read_b128 v[188:191], v203 offset:52224
	ds_read_b128 v[192:195], v203 offset:53248
	ds_read_b128 v[204:207], v203 offset:54272
	ds_read_b128 v[208:211], v203 offset:55296
	ds_read_b128 v[212:215], v203 offset:56320
	global_load_lds_dwordx4 v[196:197], off
	s_add_i32 m0, s34, 0x2000
	s_add_u32 s30, s30, 0x100080
	v_lshl_add_u64 v[196:197], v[216:217], 0, s[12:13]
	s_addc_u32 s31, s31, 0
	s_add_i32 s34, s57, s38
	global_load_lds_dwordx4 v[196:197], off
	v_lshl_add_u64 v[196:197], s[30:31], 0, v[174:175]
	s_mov_b32 m0, s34
	s_nop 0
	global_load_lds_dwordx4 v[196:197], off
	v_lshl_add_u64 v[196:197], s[30:31], 0, v[178:179]
	s_add_i32 m0, s34, 0x2000
	s_nop 0
	global_load_lds_dwordx4 v[196:197], off
	v_lshl_add_u64 v[196:197], v[218:219], 0, s[12:13]
	s_mov_b32 m0, s44
	s_nop 0
	global_load_lds_dwordx4 v[196:197], off
	v_lshl_add_u64 v[196:197], v[220:221], 0, s[12:13]
	s_mov_b32 m0, s45
	s_nop 0
	global_load_lds_dwordx4 v[196:197], off
	s_waitcnt vmcnt(8)
	s_waitcnt lgkmcnt(0)
	s_setprio 1
	s_barrier
	v_mfma_f32_16x16x32_bf16 v[60:63], v[128:131], v[160:163], v[60:63]
	v_mfma_f32_16x16x32_bf16 v[60:63], v[132:135], v[164:167], v[60:63]
	v_mfma_f32_16x16x32_bf16 v[44:47], v[128:131], v[168:171], v[44:47]
	v_mfma_f32_16x16x32_bf16 v[44:47], v[132:135], v[188:191], v[44:47]
	v_mfma_f32_16x16x32_bf16 v[28:31], v[128:131], v[192:195], v[28:31]
	v_mfma_f32_16x16x32_bf16 v[28:31], v[132:135], v[204:207], v[28:31]
	v_mfma_f32_16x16x32_bf16 v[12:15], v[128:131], v[208:211], v[12:15]
	v_mfma_f32_16x16x32_bf16 v[12:15], v[132:135], v[212:215], v[12:15]
	v_mfma_f32_16x16x32_bf16 v[56:59], v[136:139], v[160:163], v[56:59]
	v_mfma_f32_16x16x32_bf16 v[56:59], v[140:143], v[164:167], v[56:59]
	v_mfma_f32_16x16x32_bf16 v[40:43], v[136:139], v[168:171], v[40:43]
	v_mfma_f32_16x16x32_bf16 v[40:43], v[140:143], v[188:191], v[40:43]
	v_mfma_f32_16x16x32_bf16 v[24:27], v[136:139], v[192:195], v[24:27]
	v_mfma_f32_16x16x32_bf16 v[24:27], v[140:143], v[204:207], v[24:27]
	v_mfma_f32_16x16x32_bf16 v[8:11], v[136:139], v[208:211], v[8:11]
	v_mfma_f32_16x16x32_bf16 v[8:11], v[140:143], v[212:215], v[8:11]
	s_setprio 0
	s_setprio 1
	v_mfma_f32_16x16x32_bf16 v[52:55], v[144:147], v[160:163], v[52:55]
	v_mfma_f32_16x16x32_bf16 v[52:55], v[148:151], v[164:167], v[52:55]
	v_mfma_f32_16x16x32_bf16 v[36:39], v[144:147], v[168:171], v[36:39]
	v_mfma_f32_16x16x32_bf16 v[36:39], v[148:151], v[188:191], v[36:39]
	v_mfma_f32_16x16x32_bf16 v[20:23], v[144:147], v[192:195], v[20:23]
	v_mfma_f32_16x16x32_bf16 v[20:23], v[148:151], v[204:207], v[20:23]
	v_mfma_f32_16x16x32_bf16 v[4:7], v[144:147], v[208:211], v[4:7]
	v_mfma_f32_16x16x32_bf16 v[4:7], v[148:151], v[212:215], v[4:7]
	v_mfma_f32_16x16x32_bf16 v[48:51], v[152:155], v[160:163], v[48:51]
	v_mfma_f32_16x16x32_bf16 v[48:51], v[156:159], v[164:167], v[48:51]
	v_mfma_f32_16x16x32_bf16 v[32:35], v[152:155], v[168:171], v[32:35]
	v_mfma_f32_16x16x32_bf16 v[32:35], v[156:159], v[188:191], v[32:35]
	v_mfma_f32_16x16x32_bf16 v[16:19], v[152:155], v[192:195], v[16:19]
	v_mfma_f32_16x16x32_bf16 v[16:19], v[156:159], v[204:207], v[16:19]
	v_mfma_f32_16x16x32_bf16 v[0:3], v[152:155], v[208:211], v[0:3]
	v_mfma_f32_16x16x32_bf16 v[0:3], v[156:159], v[212:215], v[0:3]
	s_setprio 0
	s_barrier
	s_add_u32 s28, s28, 0x100
	s_addc_u32 s29, s29, 0
	s_add_u32 s53, s53, 0x100
	s_addc_u32 s54, s54, 0
	s_cmp_ge_i32 s55, s43
	s_mov_b32 s30, s55
	s_cbranch_scc0 .LBB0_972
